# GEMM main loops: VALU/m0 instructions between the MFMA burst end and the barrier hoisted into the burst's free issue slots (18 sites)
# speedup vs baseline: 1.0179x; 1.0011x over previous
.LBB0_139:
	v_or_b32_e32 v140, 0x10000, v146
	v_add_u32_e32 v150, 0x10400, v146
	v_add_u32_e32 v154, 0x10800, v146
	v_add_u32_e32 v158, 0x10c00, v146
	ds_read_b128 v[140:143], v140
	ds_read_b128 v[150:153], v150
	ds_read_b128 v[154:157], v154
	ds_read_b128 v[158:161], v158
	s_add_u32 s10, s6, 0xfff80080
	s_addc_u32 s11, s7, -1
	s_cmp_eq_u32 s41, 28
	s_cselect_b32 s11, s63, s11
	s_cselect_b32 s10, s62, s10
	s_cselect_b32 s53, s61, s29
	s_cselect_b32 s52, s60, s28
	s_mov_b32 m0, s12
	v_lshl_add_u64 v[206:207], s[6:7], 0, v[136:137]
	ds_read_b128 v[162:165], v145
	ds_read_b128 v[166:169], v145 offset:1024
	ds_read_b128 v[170:173], v145 offset:2048
	ds_read_b128 v[174:177], v145 offset:3072
	ds_read_b128 v[178:181], v145 offset:4096
	ds_read_b128 v[182:185], v145 offset:5120
	ds_read_b128 v[186:189], v145 offset:6144
	ds_read_b128 v[190:193], v145 offset:7168
	global_load_lds_dwordx4 v[206:207], off
	v_lshl_add_u64 v[206:207], s[6:7], 0, v[138:139]
	s_mov_b32 m0, s78
	s_nop 0
	global_load_lds_dwordx4 v[206:207], off
	s_waitcnt lgkmcnt(8)
	s_barrier
	s_waitcnt lgkmcnt(0)
	s_setprio 1
	v_mfma_f32_16x16x32_bf16 v[126:129], v[140:143], v[162:165], v[126:129]
	v_mfma_f32_16x16x32_bf16 v[122:125], v[154:157], v[162:165], v[122:125]
	v_mfma_f32_16x16x32_bf16 v[118:121], v[140:143], v[170:173], v[118:121]
	v_mfma_f32_16x16x32_bf16 v[110:113], v[154:157], v[170:173], v[110:113]
	v_mfma_f32_16x16x32_bf16 v[102:105], v[140:143], v[178:181], v[102:105]
	v_mfma_f32_16x16x32_bf16 v[94:97], v[154:157], v[178:181], v[94:97]
	v_mfma_f32_16x16x32_bf16 v[86:89], v[140:143], v[186:189], v[86:89]
	v_mfma_f32_16x16x32_bf16 v[78:81], v[154:157], v[186:189], v[78:81]
	v_mfma_f32_16x16x32_bf16 v[126:129], v[150:153], v[166:169], v[126:129]
	v_mfma_f32_16x16x32_bf16 v[122:125], v[158:161], v[166:169], v[122:125]
	v_mfma_f32_16x16x32_bf16 v[118:121], v[150:153], v[174:177], v[118:121]
	v_mfma_f32_16x16x32_bf16 v[110:113], v[158:161], v[174:177], v[110:113]
	v_mfma_f32_16x16x32_bf16 v[102:105], v[150:153], v[182:185], v[102:105]
	v_mfma_f32_16x16x32_bf16 v[94:97], v[158:161], v[182:185], v[94:97]
	v_mfma_f32_16x16x32_bf16 v[86:89], v[150:153], v[190:193], v[86:89]
	v_mfma_f32_16x16x32_bf16 v[78:81], v[158:161], v[190:193], v[78:81]
	s_setprio 0
	s_barrier
	v_or_b32_e32 v197, 0x14000, v146
	s_mov_b32 m0, s83
	v_add_u32_e32 v199, 0x14400, v146
	ds_read_b128 v[206:209], v197
	ds_read_b128 v[210:213], v199
	v_add_u32_e32 v197, 0x14800, v146
	v_lshl_add_u64 v[222:223], s[52:53], 0, v[194:195]
	v_add_u32_e32 v199, 0x14c00, v146
	ds_read_b128 v[214:217], v197
	ds_read_b128 v[218:221], v199
	global_load_lds_dwordx4 v[222:223], off
	v_lshl_add_u64 v[224:225], s[52:53], 0, v[134:135]
	s_mov_b32 m0, s54
	s_nop 0
	global_load_lds_dwordx4 v[224:225], off
	s_barrier
	s_waitcnt lgkmcnt(0)
	s_setprio 1
	v_mfma_f32_16x16x32_bf16 v[114:117], v[206:209], v[162:165], v[114:117]
	v_mfma_f32_16x16x32_bf16 v[106:109], v[214:217], v[162:165], v[106:109]
	v_mfma_f32_16x16x32_bf16 v[98:101], v[206:209], v[170:173], v[98:101]
	v_mfma_f32_16x16x32_bf16 v[90:93], v[214:217], v[170:173], v[90:93]
	v_mfma_f32_16x16x32_bf16 v[82:85], v[206:209], v[178:181], v[82:85]
	v_mfma_f32_16x16x32_bf16 v[74:77], v[214:217], v[178:181], v[74:77]
	v_mfma_f32_16x16x32_bf16 v[70:73], v[206:209], v[186:189], v[70:73]
	v_mfma_f32_16x16x32_bf16 v[66:69], v[214:217], v[186:189], v[66:69]
	v_mfma_f32_16x16x32_bf16 v[114:117], v[210:213], v[166:169], v[114:117]
	v_mfma_f32_16x16x32_bf16 v[106:109], v[218:221], v[166:169], v[106:109]
	v_mfma_f32_16x16x32_bf16 v[98:101], v[210:213], v[174:177], v[98:101]
	v_mfma_f32_16x16x32_bf16 v[90:93], v[218:221], v[174:177], v[90:93]
	v_mfma_f32_16x16x32_bf16 v[82:85], v[210:213], v[182:185], v[82:85]
	v_mfma_f32_16x16x32_bf16 v[74:77], v[218:221], v[182:185], v[74:77]
	s_mov_b32 m0, s55
	v_mfma_f32_16x16x32_bf16 v[70:73], v[210:213], v[190:193], v[70:73]
	v_lshl_add_u64 v[226:227], s[10:11], 0, v[130:131]
	v_mfma_f32_16x16x32_bf16 v[66:69], v[218:221], v[190:193], v[66:69]
	s_setprio 0
	s_barrier
	ds_read_b128 v[162:165], v145 offset:16384
	ds_read_b128 v[166:169], v145 offset:17408
	ds_read_b128 v[170:173], v145 offset:18432
	ds_read_b128 v[174:177], v145 offset:19456
	ds_read_b128 v[178:181], v145 offset:20480
	ds_read_b128 v[182:185], v145 offset:21504
	ds_read_b128 v[186:189], v145 offset:22528
	ds_read_b128 v[190:193], v145 offset:23552
	global_load_lds_dwordx4 v[226:227], off
	v_lshl_add_u64 v[228:229], s[10:11], 0, v[132:133]
	s_mov_b32 m0, s34
	s_nop 0
	global_load_lds_dwordx4 v[228:229], off
	s_barrier
	s_waitcnt lgkmcnt(0)
	s_setprio 1
	v_mfma_f32_16x16x32_bf16 v[62:65], v[140:143], v[162:165], v[62:65]
	v_mfma_f32_16x16x32_bf16 v[58:61], v[154:157], v[162:165], v[58:61]
	v_mfma_f32_16x16x32_bf16 v[54:57], v[140:143], v[170:173], v[54:57]
	v_mfma_f32_16x16x32_bf16 v[46:49], v[154:157], v[170:173], v[46:49]
	v_mfma_f32_16x16x32_bf16 v[38:41], v[140:143], v[178:181], v[38:41]
	v_mfma_f32_16x16x32_bf16 v[30:33], v[154:157], v[178:181], v[30:33]
	v_mfma_f32_16x16x32_bf16 v[22:25], v[140:143], v[186:189], v[22:25]
	v_mfma_f32_16x16x32_bf16 v[14:17], v[154:157], v[186:189], v[14:17]
	v_mfma_f32_16x16x32_bf16 v[62:65], v[150:153], v[166:169], v[62:65]
	v_mfma_f32_16x16x32_bf16 v[58:61], v[158:161], v[166:169], v[58:61]
	v_mfma_f32_16x16x32_bf16 v[54:57], v[150:153], v[174:177], v[54:57]
	v_mfma_f32_16x16x32_bf16 v[46:49], v[158:161], v[174:177], v[46:49]
	v_mfma_f32_16x16x32_bf16 v[38:41], v[150:153], v[182:185], v[38:41]
	v_mfma_f32_16x16x32_bf16 v[30:33], v[158:161], v[182:185], v[30:33]
	v_mfma_f32_16x16x32_bf16 v[22:25], v[150:153], v[190:193], v[22:25]
	v_mfma_f32_16x16x32_bf16 v[14:17], v[158:161], v[190:193], v[14:17]
	s_setprio 0
	s_barrier
	s_add_u32 s58, s52, 0x80000
	s_addc_u32 s59, s53, 0
	s_mov_b32 m0, s4
	v_lshl_add_u64 v[140:141], s[58:59], 0, v[194:195]
	global_load_lds_dwordx4 v[140:141], off
	v_lshl_add_u64 v[140:141], s[58:59], 0, v[134:135]
	s_mov_b32 m0, s5
	s_nop 0
	global_load_lds_dwordx4 v[140:141], off
	s_waitcnt vmcnt(6)
	s_barrier
	s_setprio 1
	v_mfma_f32_16x16x32_bf16 v[50:53], v[206:209], v[162:165], v[50:53]
	v_mfma_f32_16x16x32_bf16 v[42:45], v[214:217], v[162:165], v[42:45]
	v_mfma_f32_16x16x32_bf16 v[34:37], v[206:209], v[170:173], v[34:37]
	v_mfma_f32_16x16x32_bf16 v[26:29], v[214:217], v[170:173], v[26:29]
	v_mfma_f32_16x16x32_bf16 v[18:21], v[206:209], v[178:181], v[18:21]
	v_mfma_f32_16x16x32_bf16 v[10:13], v[214:217], v[178:181], v[10:13]
	v_mfma_f32_16x16x32_bf16 v[6:9], v[206:209], v[186:189], v[6:9]
	v_mfma_f32_16x16x32_bf16 v[2:5], v[214:217], v[186:189], v[2:5]
	v_mfma_f32_16x16x32_bf16 v[50:53], v[210:213], v[166:169], v[50:53]
	v_mfma_f32_16x16x32_bf16 v[42:45], v[218:221], v[166:169], v[42:45]
	v_mfma_f32_16x16x32_bf16 v[34:37], v[210:213], v[174:177], v[34:37]
	v_mfma_f32_16x16x32_bf16 v[26:29], v[218:221], v[174:177], v[26:29]
	v_or_b32_e32 v140, 0x18000, v146
	v_mfma_f32_16x16x32_bf16 v[18:21], v[210:213], v[182:185], v[18:21]
	v_add_u32_e32 v150, 0x18400, v146
	v_mfma_f32_16x16x32_bf16 v[10:13], v[218:221], v[182:185], v[10:13]
	v_add_u32_e32 v154, 0x18800, v146
	v_mfma_f32_16x16x32_bf16 v[6:9], v[210:213], v[190:193], v[6:9]
	v_add_u32_e32 v158, 0x18c00, v146
	v_mfma_f32_16x16x32_bf16 v[2:5], v[218:221], v[190:193], v[2:5]
	s_setprio 0
	s_barrier
	ds_read_b128 v[140:143], v140
	ds_read_b128 v[150:153], v150
	ds_read_b128 v[154:157], v154
	ds_read_b128 v[158:161], v158
	s_add_u32 s10, s10, 0x80000
	s_addc_u32 s11, s11, 0
	s_mov_b32 m0, s56
	v_lshl_add_u64 v[206:207], s[10:11], 0, v[130:131]
	ds_read_b128 v[162:165], v145 offset:32768
	ds_read_b128 v[166:169], v145 offset:33792
	ds_read_b128 v[170:173], v145 offset:34816
	ds_read_b128 v[174:177], v145 offset:35840
	ds_read_b128 v[178:181], v145 offset:36864
	ds_read_b128 v[182:185], v145 offset:37888
	ds_read_b128 v[186:189], v145 offset:38912
	ds_read_b128 v[190:193], v145 offset:39936
	global_load_lds_dwordx4 v[206:207], off
	v_lshl_add_u64 v[206:207], s[10:11], 0, v[132:133]
	s_mov_b32 m0, s57
	s_nop 0
	global_load_lds_dwordx4 v[206:207], off
	s_waitcnt lgkmcnt(8)
	s_barrier
	s_waitcnt lgkmcnt(0)
	s_setprio 1
	v_mfma_f32_16x16x32_bf16 v[126:129], v[140:143], v[162:165], v[126:129]
	v_mfma_f32_16x16x32_bf16 v[122:125], v[154:157], v[162:165], v[122:125]
	v_mfma_f32_16x16x32_bf16 v[118:121], v[140:143], v[170:173], v[118:121]
	v_mfma_f32_16x16x32_bf16 v[110:113], v[154:157], v[170:173], v[110:113]
	v_mfma_f32_16x16x32_bf16 v[102:105], v[140:143], v[178:181], v[102:105]
	v_mfma_f32_16x16x32_bf16 v[94:97], v[154:157], v[178:181], v[94:97]
	v_mfma_f32_16x16x32_bf16 v[86:89], v[140:143], v[186:189], v[86:89]
	v_mfma_f32_16x16x32_bf16 v[78:81], v[154:157], v[186:189], v[78:81]
	v_mfma_f32_16x16x32_bf16 v[126:129], v[150:153], v[166:169], v[126:129]
	v_mfma_f32_16x16x32_bf16 v[122:125], v[158:161], v[166:169], v[122:125]
	v_mfma_f32_16x16x32_bf16 v[118:121], v[150:153], v[174:177], v[118:121]
	v_mfma_f32_16x16x32_bf16 v[110:113], v[158:161], v[174:177], v[110:113]
	v_mfma_f32_16x16x32_bf16 v[102:105], v[150:153], v[182:185], v[102:105]
	v_mfma_f32_16x16x32_bf16 v[94:97], v[158:161], v[182:185], v[94:97]
	v_mfma_f32_16x16x32_bf16 v[86:89], v[150:153], v[190:193], v[86:89]
	v_mfma_f32_16x16x32_bf16 v[78:81], v[158:161], v[190:193], v[78:81]
	s_setprio 0
	s_barrier
	v_or_b32_e32 v197, 0x1c000, v146
	s_mov_b32 m0, s70
	v_add_u32_e32 v199, 0x1c400, v146
	ds_read_b128 v[206:209], v197
	ds_read_b128 v[210:213], v199
	v_add_u32_e32 v197, 0x1c800, v146
	v_lshl_add_u64 v[222:223], v[222:223], 0, s[76:77]
	v_add_u32_e32 v199, 0x1cc00, v146
	ds_read_b128 v[214:217], v197
	ds_read_b128 v[218:221], v199
	global_load_lds_dwordx4 v[222:223], off
	v_lshl_add_u64 v[222:223], v[224:225], 0, s[76:77]
	s_mov_b32 m0, s71
	s_nop 0
	global_load_lds_dwordx4 v[222:223], off
	s_barrier
	s_waitcnt lgkmcnt(0)
	s_setprio 1
	v_mfma_f32_16x16x32_bf16 v[114:117], v[206:209], v[162:165], v[114:117]
	v_mfma_f32_16x16x32_bf16 v[106:109], v[214:217], v[162:165], v[106:109]
	v_mfma_f32_16x16x32_bf16 v[98:101], v[206:209], v[170:173], v[98:101]
	v_mfma_f32_16x16x32_bf16 v[90:93], v[214:217], v[170:173], v[90:93]
	v_mfma_f32_16x16x32_bf16 v[82:85], v[206:209], v[178:181], v[82:85]
	v_mfma_f32_16x16x32_bf16 v[74:77], v[214:217], v[178:181], v[74:77]
	v_mfma_f32_16x16x32_bf16 v[70:73], v[206:209], v[186:189], v[70:73]
	v_mfma_f32_16x16x32_bf16 v[66:69], v[214:217], v[186:189], v[66:69]
	v_mfma_f32_16x16x32_bf16 v[114:117], v[210:213], v[166:169], v[114:117]
	v_mfma_f32_16x16x32_bf16 v[106:109], v[218:221], v[166:169], v[106:109]
	v_mfma_f32_16x16x32_bf16 v[98:101], v[210:213], v[174:177], v[98:101]
	v_mfma_f32_16x16x32_bf16 v[90:93], v[218:221], v[174:177], v[90:93]
	v_mfma_f32_16x16x32_bf16 v[82:85], v[210:213], v[182:185], v[82:85]
	v_mfma_f32_16x16x32_bf16 v[74:77], v[218:221], v[182:185], v[74:77]
	s_mov_b32 m0, s33
	v_mfma_f32_16x16x32_bf16 v[70:73], v[210:213], v[190:193], v[70:73]
	v_lshl_add_u64 v[222:223], v[226:227], 0, s[76:77]
	v_mfma_f32_16x16x32_bf16 v[66:69], v[218:221], v[190:193], v[66:69]
	s_setprio 0
	s_barrier
	ds_read_b128 v[162:165], v145 offset:49152
	ds_read_b128 v[166:169], v145 offset:50176
	ds_read_b128 v[170:173], v145 offset:51200
	ds_read_b128 v[174:177], v145 offset:52224
	ds_read_b128 v[178:181], v145 offset:53248
	ds_read_b128 v[182:185], v145 offset:54272
	ds_read_b128 v[186:189], v145 offset:55296
	ds_read_b128 v[190:193], v145 offset:56320
	global_load_lds_dwordx4 v[222:223], off
	v_lshl_add_u64 v[222:223], v[228:229], 0, s[76:77]
	s_mov_b32 m0, s35
	s_nop 0
	global_load_lds_dwordx4 v[222:223], off
	s_barrier
	s_waitcnt lgkmcnt(0)
	s_setprio 1
	v_mfma_f32_16x16x32_bf16 v[62:65], v[140:143], v[162:165], v[62:65]
	v_mfma_f32_16x16x32_bf16 v[58:61], v[154:157], v[162:165], v[58:61]
	v_mfma_f32_16x16x32_bf16 v[54:57], v[140:143], v[170:173], v[54:57]
	v_mfma_f32_16x16x32_bf16 v[46:49], v[154:157], v[170:173], v[46:49]
	v_mfma_f32_16x16x32_bf16 v[38:41], v[140:143], v[178:181], v[38:41]
	v_mfma_f32_16x16x32_bf16 v[30:33], v[154:157], v[178:181], v[30:33]
	v_mfma_f32_16x16x32_bf16 v[22:25], v[140:143], v[186:189], v[22:25]
	v_mfma_f32_16x16x32_bf16 v[14:17], v[154:157], v[186:189], v[14:17]
	v_mfma_f32_16x16x32_bf16 v[62:65], v[150:153], v[166:169], v[62:65]
	v_mfma_f32_16x16x32_bf16 v[58:61], v[158:161], v[166:169], v[58:61]
	v_mfma_f32_16x16x32_bf16 v[54:57], v[150:153], v[174:177], v[54:57]
	v_mfma_f32_16x16x32_bf16 v[46:49], v[158:161], v[174:177], v[46:49]
	v_mfma_f32_16x16x32_bf16 v[38:41], v[150:153], v[182:185], v[38:41]
	v_mfma_f32_16x16x32_bf16 v[30:33], v[158:161], v[182:185], v[30:33]
	v_mfma_f32_16x16x32_bf16 v[22:25], v[150:153], v[190:193], v[22:25]
	v_mfma_f32_16x16x32_bf16 v[14:17], v[158:161], v[190:193], v[14:17]
	s_setprio 0
	s_barrier
	s_add_u32 s10, s52, 0x80080
	s_addc_u32 s11, s53, 0
	s_mov_b32 m0, s67
	v_lshl_add_u64 v[140:141], s[10:11], 0, v[194:195]
	global_load_lds_dwordx4 v[140:141], off
	v_lshl_add_u64 v[140:141], s[10:11], 0, v[134:135]
	s_mov_b32 m0, s17
	s_nop 0
	global_load_lds_dwordx4 v[140:141], off
	s_waitcnt vmcnt(6)
	s_barrier
	s_setprio 1
	v_mfma_f32_16x16x32_bf16 v[50:53], v[206:209], v[162:165], v[50:53]
	v_mfma_f32_16x16x32_bf16 v[42:45], v[214:217], v[162:165], v[42:45]
	v_mfma_f32_16x16x32_bf16 v[34:37], v[206:209], v[170:173], v[34:37]
	v_mfma_f32_16x16x32_bf16 v[26:29], v[214:217], v[170:173], v[26:29]
	v_mfma_f32_16x16x32_bf16 v[18:21], v[206:209], v[178:181], v[18:21]
	v_mfma_f32_16x16x32_bf16 v[10:13], v[214:217], v[178:181], v[10:13]
	v_mfma_f32_16x16x32_bf16 v[6:9], v[206:209], v[186:189], v[6:9]
	v_mfma_f32_16x16x32_bf16 v[2:5], v[214:217], v[186:189], v[2:5]
	v_mfma_f32_16x16x32_bf16 v[50:53], v[210:213], v[166:169], v[50:53]
	v_mfma_f32_16x16x32_bf16 v[42:45], v[218:221], v[166:169], v[42:45]
	v_mfma_f32_16x16x32_bf16 v[34:37], v[210:213], v[174:177], v[34:37]
	v_mfma_f32_16x16x32_bf16 v[26:29], v[218:221], v[174:177], v[26:29]
	v_mfma_f32_16x16x32_bf16 v[18:21], v[210:213], v[182:185], v[18:21]
	v_mfma_f32_16x16x32_bf16 v[10:13], v[218:221], v[182:185], v[10:13]
	v_mfma_f32_16x16x32_bf16 v[6:9], v[210:213], v[190:193], v[6:9]
	v_mfma_f32_16x16x32_bf16 v[2:5], v[218:221], v[190:193], v[2:5]
	s_setprio 0
	s_add_i32 s41, s41, 2
	s_add_u32 s6, s6, 0x100
	s_addc_u32 s7, s7, 0
	s_add_u32 s28, s28, 0x100
	s_addc_u32 s29, s29, 0
	s_cmp_gt_u32 s41, 29
	s_barrier
	s_cbranch_scc0 .LBB0_139
	s_cmp_gt_i32 s79, 3
	s_mov_b64 s[6:7], -1
	s_cbranch_scc0 .LBB0_146
	s_lshl_b32 s10, s82, 8
	v_lshl_or_b32 v140, s80, 8, v149
	s_cmp_lg_u32 s79, 4
	v_ashrrev_i32_e32 v141, 31, v140
	s_cbranch_scc0 .LBB0_143
	v_readlane_b32 s6, v252, 55
	v_readlane_b32 s7, v252, 56
	v_add_u32_e32 v150, s10, v147
	s_nop 0
	v_mov_b64_e32 v[142:143], s[6:7]
	s_mov_b32 s6, 0x9000
	v_mad_i64_i32 v[142:143], s[6:7], v150, s6, v[142:143]
	v_lshl_add_u64 v[142:143], v[140:141], 1, v[142:143]
	v_cvt_pk_bf16_f32 v150, v126, v127
	v_cvt_pk_bf16_f32 v151, v128, v129
	v_cvt_pk_bf16_f32 v152, v122, v123
	v_cvt_pk_bf16_f32 v153, v124, v125
	global_store_dwordx4 v[142:143], v[150:153], off
	v_add_co_u32_e32 v154, vcc, s44, v142
	s_nop 0
	v_cvt_pk_bf16_f32 v150, v114, v115
	v_cvt_pk_bf16_f32 v151, v116, v117
	v_cvt_pk_bf16_f32 v152, v106, v107
	v_cvt_pk_bf16_f32 v153, v108, v109
	global_store_dwordx4 v[142:143], v[150:153], off offset:256
	v_addc_co_u32_e32 v155, vcc, 0, v143, vcc
	s_nop 0
	v_cvt_pk_bf16_f32 v150, v118, v119
	v_cvt_pk_bf16_f32 v151, v120, v121
	v_cvt_pk_bf16_f32 v152, v110, v111
	v_cvt_pk_bf16_f32 v153, v112, v113
	global_store_dwordx4 v[154:155], v[150:153], off
	s_mov_b64 s[6:7], 0
	s_nop 0
	v_cvt_pk_bf16_f32 v150, v98, v99
	v_cvt_pk_bf16_f32 v151, v100, v101
	v_cvt_pk_bf16_f32 v152, v90, v91
	v_cvt_pk_bf16_f32 v153, v92, v93
	global_store_dwordx4 v[154:155], v[150:153], off offset:256
	v_add_co_u32_e32 v154, vcc, s45, v142
	s_nop 0
	v_cvt_pk_bf16_f32 v150, v102, v103
	v_cvt_pk_bf16_f32 v151, v104, v105
	v_cvt_pk_bf16_f32 v152, v94, v95
	v_cvt_pk_bf16_f32 v153, v96, v97
	s_nop 0
	v_addc_co_u32_e32 v155, vcc, 0, v143, vcc
	global_store_dwordx4 v[154:155], v[150:153], off
	s_nop 1
	v_cvt_pk_bf16_f32 v150, v82, v83
	v_cvt_pk_bf16_f32 v151, v84, v85
	v_cvt_pk_bf16_f32 v152, v74, v75
	v_cvt_pk_bf16_f32 v153, v76, v77
	global_store_dwordx4 v[154:155], v[150:153], off offset:256
	v_add_co_u32_e32 v154, vcc, s90, v142
	s_nop 0
	v_cvt_pk_bf16_f32 v150, v86, v87
	v_cvt_pk_bf16_f32 v151, v88, v89
	v_cvt_pk_bf16_f32 v152, v78, v79
	v_cvt_pk_bf16_f32 v153, v80, v81
	s_nop 0
	v_addc_co_u32_e32 v155, vcc, 0, v143, vcc
	global_store_dwordx4 v[154:155], v[150:153], off
	s_nop 1
	v_cvt_pk_bf16_f32 v150, v70, v71
	v_cvt_pk_bf16_f32 v151, v72, v73
	v_cvt_pk_bf16_f32 v152, v66, v67
	v_cvt_pk_bf16_f32 v153, v68, v69
	global_store_dwordx4 v[154:155], v[150:153], off offset:256
	v_add_co_u32_e32 v154, vcc, s20, v142
	s_nop 0
	v_cvt_pk_bf16_f32 v150, v62, v63
	v_cvt_pk_bf16_f32 v151, v64, v65
	v_cvt_pk_bf16_f32 v152, v58, v59
	v_cvt_pk_bf16_f32 v153, v60, v61
	s_nop 0
	v_addc_co_u32_e32 v155, vcc, 0, v143, vcc
	global_store_dwordx4 v[154:155], v[150:153], off
	s_nop 1
	v_cvt_pk_bf16_f32 v150, v50, v51
	v_cvt_pk_bf16_f32 v151, v52, v53
	v_cvt_pk_bf16_f32 v152, v42, v43
	v_cvt_pk_bf16_f32 v153, v44, v45
	global_store_dwordx4 v[154:155], v[150:153], off offset:256
	v_add_co_u32_e32 v154, vcc, s21, v142
	s_nop 0
	v_cvt_pk_bf16_f32 v150, v54, v55
	v_cvt_pk_bf16_f32 v151, v56, v57
	v_cvt_pk_bf16_f32 v152, v46, v47
	v_cvt_pk_bf16_f32 v153, v48, v49
	s_nop 0
	v_addc_co_u32_e32 v155, vcc, 0, v143, vcc
	global_store_dwordx4 v[154:155], v[150:153], off
	s_nop 1
	v_cvt_pk_bf16_f32 v150, v34, v35
	v_cvt_pk_bf16_f32 v151, v36, v37
	v_cvt_pk_bf16_f32 v152, v26, v27
	v_cvt_pk_bf16_f32 v153, v28, v29
	global_store_dwordx4 v[154:155], v[150:153], off offset:256
	v_add_co_u32_e32 v154, vcc, s22, v142
	s_nop 0
	v_cvt_pk_bf16_f32 v150, v38, v39
	v_cvt_pk_bf16_f32 v151, v40, v41
	v_cvt_pk_bf16_f32 v152, v30, v31
	v_cvt_pk_bf16_f32 v153, v32, v33
	s_nop 0
	v_addc_co_u32_e32 v155, vcc, 0, v143, vcc
	global_store_dwordx4 v[154:155], v[150:153], off
	v_add_co_u32_e32 v142, vcc, s23, v142
	s_nop 0
	v_cvt_pk_bf16_f32 v150, v18, v19
	v_cvt_pk_bf16_f32 v151, v20, v21
	v_cvt_pk_bf16_f32 v152, v10, v11
	v_cvt_pk_bf16_f32 v153, v12, v13
	global_store_dwordx4 v[154:155], v[150:153], off offset:256
	v_addc_co_u32_e32 v143, vcc, 0, v143, vcc
	s_nop 0
	v_cvt_pk_bf16_f32 v150, v22, v23
	v_cvt_pk_bf16_f32 v151, v24, v25
	v_cvt_pk_bf16_f32 v152, v14, v15
	v_cvt_pk_bf16_f32 v153, v16, v17
	global_store_dwordx4 v[142:143], v[150:153], off
	s_nop 1
	v_cvt_pk_bf16_f32 v150, v6, v7
	v_cvt_pk_bf16_f32 v151, v8, v9
	v_cvt_pk_bf16_f32 v152, v2, v3
	v_cvt_pk_bf16_f32 v153, v4, v5
	global_store_dwordx4 v[142:143], v[150:153], off offset:256

.LBB0_204:
	s_add_u32 s80, s54, s62
	s_addc_u32 s81, s55, s63
	s_add_u32 s82, s80, 0x100
	s_addc_u32 s83, s81, 0
	s_and_b64 s[10:11], s[8:9], exec
	s_cselect_b32 s83, s1, s83
	s_cselect_b32 s82, s0, s82
	s_add_u32 s10, s52, s62
	s_addc_u32 s11, s53, s63
	s_add_u32 s10, s10, 0x100
	s_addc_u32 s11, s11, 0
	s_and_b64 s[8:9], s[8:9], exec
	s_cselect_b32 vcc_hi, s7, s11
	s_cselect_b32 vcc_lo, s6, s10
	s_add_u32 s10, s80, 0x10080
	v_or_b32_e32 v138, 0x10000, v142
	s_addc_u32 s11, s81, 0
	s_add_i32 m0, s5, 0xc000
	s_add_i32 s87, s5, 0xe000
	ds_read_b128 v[144:147], v138
	v_add_u32_e32 v138, 0x10400, v142
	s_add_u32 s80, vcc_lo, 0x340000
	ds_read_b128 v[148:151], v138
	v_add_u32_e32 v138, 0x10800, v142
	s_addc_u32 s81, vcc_hi, 0
	ds_read_b128 v[152:155], v138
	v_add_u32_e32 v138, 0x10c00, v142
	s_add_u32 s62, s82, 0x10000
	ds_read_b128 v[156:159], v138
	s_addc_u32 s63, s83, 0
	s_add_u32 s8, vcc_lo, 0x340080
	s_addc_u32 s9, vcc_hi, 0
	v_lshl_add_u64 v[138:139], s[10:11], 0, v[136:137]
	ds_read_b128 v[160:163], v141
	ds_read_b128 v[164:167], v141 offset:1024
	ds_read_b128 v[168:171], v141 offset:2048
	ds_read_b128 v[172:175], v141 offset:3072
	ds_read_b128 v[176:179], v141 offset:4096
	ds_read_b128 v[180:183], v141 offset:5120
	ds_read_b128 v[184:187], v141 offset:6144
	ds_read_b128 v[188:191], v141 offset:7168
	global_load_lds_dwordx4 v[138:139], off
	v_lshl_add_u64 v[138:139], s[10:11], 0, v[132:133]
	s_mov_b32 m0, s87
	s_nop 0
	global_load_lds_dwordx4 v[138:139], off
	s_waitcnt lgkmcnt(8)
	s_barrier
	s_waitcnt lgkmcnt(0)
	s_setprio 1
	v_mfma_f32_16x16x32_bf16 v[126:129], v[144:147], v[160:163], v[126:129]
	v_mfma_f32_16x16x32_bf16 v[122:125], v[152:155], v[160:163], v[122:125]
	v_mfma_f32_16x16x32_bf16 v[118:121], v[144:147], v[168:171], v[118:121]
	v_mfma_f32_16x16x32_bf16 v[110:113], v[152:155], v[168:171], v[110:113]
	v_mfma_f32_16x16x32_bf16 v[102:105], v[144:147], v[176:179], v[102:105]
	v_mfma_f32_16x16x32_bf16 v[94:97], v[152:155], v[176:179], v[94:97]
	v_mfma_f32_16x16x32_bf16 v[86:89], v[144:147], v[184:187], v[86:89]
	v_mfma_f32_16x16x32_bf16 v[78:81], v[152:155], v[184:187], v[78:81]
	v_mfma_f32_16x16x32_bf16 v[126:129], v[148:151], v[164:167], v[126:129]
	v_mfma_f32_16x16x32_bf16 v[122:125], v[156:159], v[164:167], v[122:125]
	v_mfma_f32_16x16x32_bf16 v[118:121], v[148:151], v[172:175], v[118:121]
	v_mfma_f32_16x16x32_bf16 v[110:113], v[156:159], v[172:175], v[110:113]
	v_mfma_f32_16x16x32_bf16 v[102:105], v[148:151], v[180:183], v[102:105]
	v_mfma_f32_16x16x32_bf16 v[94:97], v[156:159], v[180:183], v[94:97]
	v_mfma_f32_16x16x32_bf16 v[86:89], v[148:151], v[188:191], v[86:89]
	v_mfma_f32_16x16x32_bf16 v[78:81], v[156:159], v[188:191], v[78:81]
	s_setprio 0
	s_barrier
	v_or_b32_e32 v138, 0x14000, v142
	v_add_u32_e32 v139, 0x14400, v142
	ds_read_b128 v[206:209], v138
	ds_read_b128 v[210:213], v139
	v_add_u32_e32 v138, 0x14800, v142
	v_add_u32_e32 v139, 0x14c00, v142
	s_mov_b32 m0, s12
	ds_read_b128 v[214:217], v138
	ds_read_b128 v[218:221], v139
	v_lshl_add_u64 v[138:139], vcc, 0, v[134:135]
	global_load_lds_dwordx4 v[138:139], off
	v_lshl_add_u64 v[192:193], vcc, 0, v[130:131]
	s_mov_b32 m0, s17
	s_nop 0
	global_load_lds_dwordx4 v[192:193], off
	s_barrier
	s_waitcnt lgkmcnt(0)
	s_setprio 1
	v_mfma_f32_16x16x32_bf16 v[114:117], v[206:209], v[160:163], v[114:117]
	v_mfma_f32_16x16x32_bf16 v[106:109], v[214:217], v[160:163], v[106:109]
	v_mfma_f32_16x16x32_bf16 v[98:101], v[206:209], v[168:171], v[98:101]
	v_mfma_f32_16x16x32_bf16 v[90:93], v[214:217], v[168:171], v[90:93]
	v_mfma_f32_16x16x32_bf16 v[82:85], v[206:209], v[176:179], v[82:85]
	v_mfma_f32_16x16x32_bf16 v[74:77], v[214:217], v[176:179], v[74:77]
	v_mfma_f32_16x16x32_bf16 v[70:73], v[206:209], v[184:187], v[70:73]
	v_mfma_f32_16x16x32_bf16 v[66:69], v[214:217], v[184:187], v[66:69]
	v_mfma_f32_16x16x32_bf16 v[114:117], v[210:213], v[164:167], v[114:117]
	v_mfma_f32_16x16x32_bf16 v[106:109], v[218:221], v[164:167], v[106:109]
	v_mfma_f32_16x16x32_bf16 v[98:101], v[210:213], v[172:175], v[98:101]
	v_mfma_f32_16x16x32_bf16 v[90:93], v[218:221], v[172:175], v[90:93]
	v_mfma_f32_16x16x32_bf16 v[82:85], v[210:213], v[180:183], v[82:85]
	v_mfma_f32_16x16x32_bf16 v[74:77], v[218:221], v[180:183], v[74:77]
	s_mov_b32 m0, s5
	v_mfma_f32_16x16x32_bf16 v[70:73], v[210:213], v[188:191], v[70:73]
	v_lshl_add_u64 v[222:223], s[82:83], 0, v[136:137]
	v_mfma_f32_16x16x32_bf16 v[66:69], v[218:221], v[188:191], v[66:69]
	s_setprio 0
	s_barrier
	ds_read_b128 v[160:163], v141 offset:16384
	ds_read_b128 v[164:167], v141 offset:17408
	ds_read_b128 v[168:171], v141 offset:18432
	ds_read_b128 v[172:175], v141 offset:19456
	ds_read_b128 v[176:179], v141 offset:20480
	ds_read_b128 v[180:183], v141 offset:21504
	ds_read_b128 v[184:187], v141 offset:22528
	ds_read_b128 v[188:191], v141 offset:23552
	global_load_lds_dwordx4 v[222:223], off
	v_lshl_add_u64 v[224:225], s[82:83], 0, v[132:133]
	s_mov_b32 m0, s26
	s_nop 0
	global_load_lds_dwordx4 v[224:225], off
	s_barrier
	s_waitcnt lgkmcnt(0)
	s_setprio 1
	v_mfma_f32_16x16x32_bf16 v[62:65], v[144:147], v[160:163], v[62:65]
	v_mfma_f32_16x16x32_bf16 v[58:61], v[152:155], v[160:163], v[58:61]
	v_mfma_f32_16x16x32_bf16 v[54:57], v[144:147], v[168:171], v[54:57]
	v_mfma_f32_16x16x32_bf16 v[46:49], v[152:155], v[168:171], v[46:49]
	v_mfma_f32_16x16x32_bf16 v[38:41], v[144:147], v[176:179], v[38:41]
	v_mfma_f32_16x16x32_bf16 v[30:33], v[152:155], v[176:179], v[30:33]
	v_mfma_f32_16x16x32_bf16 v[22:25], v[144:147], v[184:187], v[22:25]
	v_mfma_f32_16x16x32_bf16 v[14:17], v[152:155], v[184:187], v[14:17]
	v_mfma_f32_16x16x32_bf16 v[62:65], v[148:151], v[164:167], v[62:65]
	v_mfma_f32_16x16x32_bf16 v[58:61], v[156:159], v[164:167], v[58:61]
	v_mfma_f32_16x16x32_bf16 v[54:57], v[148:151], v[172:175], v[54:57]
	v_mfma_f32_16x16x32_bf16 v[46:49], v[156:159], v[172:175], v[46:49]
	v_mfma_f32_16x16x32_bf16 v[38:41], v[148:151], v[180:183], v[38:41]
	v_mfma_f32_16x16x32_bf16 v[30:33], v[156:159], v[180:183], v[30:33]
	v_mfma_f32_16x16x32_bf16 v[22:25], v[148:151], v[188:191], v[22:25]
	v_mfma_f32_16x16x32_bf16 v[14:17], v[156:159], v[188:191], v[14:17]
	s_setprio 0
	s_barrier
	s_mov_b32 m0, s34
	v_lshl_add_u64 v[144:145], s[80:81], 0, v[134:135]
	global_load_lds_dwordx4 v[144:145], off
	v_lshl_add_u64 v[144:145], s[80:81], 0, v[130:131]
	s_mov_b32 m0, s35
	s_nop 0
	global_load_lds_dwordx4 v[144:145], off
	s_waitcnt vmcnt(6)
	s_barrier
	s_setprio 1
	v_mfma_f32_16x16x32_bf16 v[50:53], v[206:209], v[160:163], v[50:53]
	v_mfma_f32_16x16x32_bf16 v[42:45], v[214:217], v[160:163], v[42:45]
	v_mfma_f32_16x16x32_bf16 v[34:37], v[206:209], v[168:171], v[34:37]
	v_mfma_f32_16x16x32_bf16 v[26:29], v[214:217], v[168:171], v[26:29]
	v_mfma_f32_16x16x32_bf16 v[18:21], v[206:209], v[176:179], v[18:21]
	v_mfma_f32_16x16x32_bf16 v[10:13], v[214:217], v[176:179], v[10:13]
	v_mfma_f32_16x16x32_bf16 v[6:9], v[206:209], v[184:187], v[6:9]
	v_mfma_f32_16x16x32_bf16 v[2:5], v[214:217], v[184:187], v[2:5]
	v_mfma_f32_16x16x32_bf16 v[50:53], v[210:213], v[164:167], v[50:53]
	v_mfma_f32_16x16x32_bf16 v[42:45], v[218:221], v[164:167], v[42:45]
	v_mfma_f32_16x16x32_bf16 v[34:37], v[210:213], v[172:175], v[34:37]
	v_mfma_f32_16x16x32_bf16 v[26:29], v[218:221], v[172:175], v[26:29]
	v_or_b32_e32 v144, 0x18000, v142
	v_mfma_f32_16x16x32_bf16 v[18:21], v[210:213], v[180:183], v[18:21]
	v_add_u32_e32 v148, 0x18400, v142
	v_mfma_f32_16x16x32_bf16 v[10:13], v[218:221], v[180:183], v[10:13]
	v_add_u32_e32 v152, 0x18800, v142
	v_mfma_f32_16x16x32_bf16 v[6:9], v[210:213], v[188:191], v[6:9]
	v_add_u32_e32 v156, 0x18c00, v142
	v_mfma_f32_16x16x32_bf16 v[2:5], v[218:221], v[188:191], v[2:5]
	s_setprio 0
	s_barrier
	ds_read_b128 v[144:147], v144
	ds_read_b128 v[148:151], v148
	ds_read_b128 v[152:155], v152
	ds_read_b128 v[156:159], v156
	s_mov_b32 m0, s56
	v_lshl_add_u64 v[206:207], s[62:63], 0, v[136:137]
	ds_read_b128 v[160:163], v141 offset:32768
	ds_read_b128 v[164:167], v141 offset:33792
	ds_read_b128 v[168:171], v141 offset:34816
	ds_read_b128 v[172:175], v141 offset:35840
	ds_read_b128 v[176:179], v141 offset:36864
	ds_read_b128 v[180:183], v141 offset:37888
	ds_read_b128 v[184:187], v141 offset:38912
	ds_read_b128 v[188:191], v141 offset:39936
	global_load_lds_dwordx4 v[206:207], off
	v_lshl_add_u64 v[206:207], s[62:63], 0, v[132:133]
	s_mov_b32 m0, s57
	s_nop 0
	global_load_lds_dwordx4 v[206:207], off
	s_waitcnt lgkmcnt(8)
	s_barrier
	s_waitcnt lgkmcnt(0)
	s_setprio 1
	v_mfma_f32_16x16x32_bf16 v[126:129], v[144:147], v[160:163], v[126:129]
	v_mfma_f32_16x16x32_bf16 v[122:125], v[152:155], v[160:163], v[122:125]
	v_mfma_f32_16x16x32_bf16 v[118:121], v[144:147], v[168:171], v[118:121]
	v_mfma_f32_16x16x32_bf16 v[110:113], v[152:155], v[168:171], v[110:113]
	v_mfma_f32_16x16x32_bf16 v[102:105], v[144:147], v[176:179], v[102:105]
	v_mfma_f32_16x16x32_bf16 v[94:97], v[152:155], v[176:179], v[94:97]
	v_mfma_f32_16x16x32_bf16 v[86:89], v[144:147], v[184:187], v[86:89]
	v_mfma_f32_16x16x32_bf16 v[78:81], v[152:155], v[184:187], v[78:81]
	v_mfma_f32_16x16x32_bf16 v[126:129], v[148:151], v[164:167], v[126:129]
	v_mfma_f32_16x16x32_bf16 v[122:125], v[156:159], v[164:167], v[122:125]
	v_mfma_f32_16x16x32_bf16 v[118:121], v[148:151], v[172:175], v[118:121]
	v_mfma_f32_16x16x32_bf16 v[110:113], v[156:159], v[172:175], v[110:113]
	v_mfma_f32_16x16x32_bf16 v[102:105], v[148:151], v[180:183], v[102:105]
	v_mfma_f32_16x16x32_bf16 v[94:97], v[156:159], v[180:183], v[94:97]
	v_mfma_f32_16x16x32_bf16 v[86:89], v[148:151], v[188:191], v[86:89]
	v_mfma_f32_16x16x32_bf16 v[78:81], v[156:159], v[188:191], v[78:81]
	s_setprio 0
	s_barrier
	v_or_b32_e32 v197, 0x1c000, v142
	s_mov_b32 m0, s58
	v_add_u32_e32 v199, 0x1c400, v142
	ds_read_b128 v[206:209], v197
	ds_read_b128 v[210:213], v199
	v_add_u32_e32 v197, 0x1c800, v142
	v_lshl_add_u64 v[138:139], v[138:139], 0, s[76:77]
	v_add_u32_e32 v199, 0x1cc00, v142
	ds_read_b128 v[214:217], v197
	ds_read_b128 v[218:221], v199
	global_load_lds_dwordx4 v[138:139], off
	v_lshl_add_u64 v[138:139], v[192:193], 0, s[76:77]
	s_mov_b32 m0, s59
	s_nop 0
	global_load_lds_dwordx4 v[138:139], off
	s_barrier
	s_waitcnt lgkmcnt(0)
	s_setprio 1
	v_mfma_f32_16x16x32_bf16 v[114:117], v[206:209], v[160:163], v[114:117]
	v_mfma_f32_16x16x32_bf16 v[106:109], v[214:217], v[160:163], v[106:109]
	v_mfma_f32_16x16x32_bf16 v[98:101], v[206:209], v[168:171], v[98:101]
	v_mfma_f32_16x16x32_bf16 v[90:93], v[214:217], v[168:171], v[90:93]
	v_mfma_f32_16x16x32_bf16 v[82:85], v[206:209], v[176:179], v[82:85]
	v_mfma_f32_16x16x32_bf16 v[74:77], v[214:217], v[176:179], v[74:77]
	v_mfma_f32_16x16x32_bf16 v[70:73], v[206:209], v[184:187], v[70:73]
	v_mfma_f32_16x16x32_bf16 v[66:69], v[214:217], v[184:187], v[66:69]
	v_mfma_f32_16x16x32_bf16 v[114:117], v[210:213], v[164:167], v[114:117]
	v_mfma_f32_16x16x32_bf16 v[106:109], v[218:221], v[164:167], v[106:109]
	v_mfma_f32_16x16x32_bf16 v[98:101], v[210:213], v[172:175], v[98:101]
	v_mfma_f32_16x16x32_bf16 v[90:93], v[218:221], v[172:175], v[90:93]
	v_mfma_f32_16x16x32_bf16 v[82:85], v[210:213], v[180:183], v[82:85]
	v_mfma_f32_16x16x32_bf16 v[74:77], v[218:221], v[180:183], v[74:77]
	s_mov_b32 m0, s67
	v_mfma_f32_16x16x32_bf16 v[70:73], v[210:213], v[188:191], v[70:73]
	v_lshl_add_u64 v[138:139], v[222:223], 0, s[76:77]
	v_mfma_f32_16x16x32_bf16 v[66:69], v[218:221], v[188:191], v[66:69]
	s_setprio 0
	s_barrier
	ds_read_b128 v[160:163], v141 offset:49152
	ds_read_b128 v[164:167], v141 offset:50176
	ds_read_b128 v[168:171], v141 offset:51200
	ds_read_b128 v[172:175], v141 offset:52224
	ds_read_b128 v[176:179], v141 offset:53248
	ds_read_b128 v[180:183], v141 offset:54272
	ds_read_b128 v[184:187], v141 offset:55296
	ds_read_b128 v[188:191], v141 offset:56320
	global_load_lds_dwordx4 v[138:139], off
	v_lshl_add_u64 v[138:139], v[224:225], 0, s[76:77]
	s_mov_b32 m0, s70
	s_nop 0
	global_load_lds_dwordx4 v[138:139], off
	s_barrier
	s_waitcnt lgkmcnt(0)
	s_setprio 1
	v_mfma_f32_16x16x32_bf16 v[62:65], v[144:147], v[160:163], v[62:65]
	v_mfma_f32_16x16x32_bf16 v[58:61], v[152:155], v[160:163], v[58:61]
	v_mfma_f32_16x16x32_bf16 v[54:57], v[144:147], v[168:171], v[54:57]
	v_mfma_f32_16x16x32_bf16 v[46:49], v[152:155], v[168:171], v[46:49]
	v_mfma_f32_16x16x32_bf16 v[38:41], v[144:147], v[176:179], v[38:41]
	v_mfma_f32_16x16x32_bf16 v[30:33], v[152:155], v[176:179], v[30:33]
	v_mfma_f32_16x16x32_bf16 v[22:25], v[144:147], v[184:187], v[22:25]
	v_mfma_f32_16x16x32_bf16 v[14:17], v[152:155], v[184:187], v[14:17]
	v_mfma_f32_16x16x32_bf16 v[62:65], v[148:151], v[164:167], v[62:65]
	v_mfma_f32_16x16x32_bf16 v[58:61], v[156:159], v[164:167], v[58:61]
	v_mfma_f32_16x16x32_bf16 v[54:57], v[148:151], v[172:175], v[54:57]
	v_mfma_f32_16x16x32_bf16 v[46:49], v[156:159], v[172:175], v[46:49]
	v_mfma_f32_16x16x32_bf16 v[38:41], v[148:151], v[180:183], v[38:41]
	v_mfma_f32_16x16x32_bf16 v[30:33], v[156:159], v[180:183], v[30:33]
	v_mfma_f32_16x16x32_bf16 v[22:25], v[148:151], v[188:191], v[22:25]
	v_mfma_f32_16x16x32_bf16 v[14:17], v[156:159], v[188:191], v[14:17]
	s_setprio 0
	s_barrier
	s_mov_b32 m0, s71
	v_lshl_add_u64 v[138:139], s[8:9], 0, v[134:135]
	global_load_lds_dwordx4 v[138:139], off
	v_lshl_add_u64 v[138:139], s[8:9], 0, v[130:131]
	s_mov_b32 m0, s78
	s_nop 0
	global_load_lds_dwordx4 v[138:139], off
	s_waitcnt vmcnt(6)
	s_barrier
	s_setprio 1
	v_mfma_f32_16x16x32_bf16 v[50:53], v[206:209], v[160:163], v[50:53]
	v_mfma_f32_16x16x32_bf16 v[42:45], v[214:217], v[160:163], v[42:45]
	v_mfma_f32_16x16x32_bf16 v[34:37], v[206:209], v[168:171], v[34:37]
	v_mfma_f32_16x16x32_bf16 v[26:29], v[214:217], v[168:171], v[26:29]
	v_mfma_f32_16x16x32_bf16 v[18:21], v[206:209], v[176:179], v[18:21]
	v_mfma_f32_16x16x32_bf16 v[10:13], v[214:217], v[176:179], v[10:13]
	v_mfma_f32_16x16x32_bf16 v[6:9], v[206:209], v[184:187], v[6:9]
	v_mfma_f32_16x16x32_bf16 v[2:5], v[214:217], v[184:187], v[2:5]
	v_mfma_f32_16x16x32_bf16 v[50:53], v[210:213], v[164:167], v[50:53]
	v_mfma_f32_16x16x32_bf16 v[42:45], v[218:221], v[164:167], v[42:45]
	v_mfma_f32_16x16x32_bf16 v[34:37], v[210:213], v[172:175], v[34:37]
	v_mfma_f32_16x16x32_bf16 v[26:29], v[218:221], v[172:175], v[26:29]
	v_mfma_f32_16x16x32_bf16 v[18:21], v[210:213], v[180:183], v[18:21]
	v_mfma_f32_16x16x32_bf16 v[10:13], v[218:221], v[180:183], v[10:13]
	v_mfma_f32_16x16x32_bf16 v[6:9], v[210:213], v[188:191], v[6:9]
	v_mfma_f32_16x16x32_bf16 v[2:5], v[218:221], v[188:191], v[2:5]
	s_setprio 0
	s_andn2_b64 vcc, exec, s[60:61]
	s_mov_b64 s[8:9], -1
	s_mov_b64 s[60:61], 0
	s_mov_b64 s[62:63], 0x100
	s_barrier
	s_cbranch_vccz .LBB0_204
	s_cmp_gt_i32 s29, 63
	s_cbranch_scc0 .LBB0_207
	s_lshl_b32 s8, s29, 10
	s_lshl_b32 s9, s94, 8
	s_add_i32 s9, s9, s8
	v_add_u32_e32 v138, s9, v143
	v_ashrrev_i32_e32 v139, 31, v138
	v_lshlrev_b64 v[138:139], 10, v[138:139]
	s_lshl_b32 s8, s42, 8
	v_lshl_add_u64 v[138:139], s[64:65], 0, v[138:139]
	s_ashr_i32 s9, s8, 31
	v_lshl_add_u64 v[138:139], s[8:9], 1, v[138:139]
	s_mov_b64 s[8:9], 0

.LBB0_255:
	v_or_b32_e32 v130, 0x10000, v182
	v_add_u32_e32 v134, 0x10400, v182
	v_add_u32_e32 v138, 0x10800, v182
	v_add_u32_e32 v142, 0x10c00, v182
	ds_read_b128 v[130:133], v130
	ds_read_b128 v[134:137], v134
	ds_read_b128 v[138:141], v138
	ds_read_b128 v[142:145], v142
	s_add_u32 s8, s6, 0xfff00080
	s_addc_u32 s9, s7, -1
	s_cmp_eq_u32 s79, 60
	s_cselect_b32 s11, s53, s9
	s_cselect_b32 s10, s52, s8
	s_cselect_b32 s9, s61, s78
	s_cselect_b32 s8, s60, s1
	v_lshl_add_u64 v[178:179], s[6:7], 0, v[166:167]
	s_add_i32 m0, s5, 0xc000
	ds_read_b128 v[146:149], v181
	ds_read_b128 v[150:153], v181 offset:1024
	ds_read_b128 v[154:157], v181 offset:2048
	ds_read_b128 v[170:173], v181 offset:3072
	ds_read_b128 v[174:177], v181 offset:4096
	ds_read_b128 v[184:187], v181 offset:5120
	ds_read_b128 v[188:191], v181 offset:6144
	ds_read_b128 v[206:209], v181 offset:7168
	global_load_lds_dwordx4 v[178:179], off
	v_lshl_add_u64 v[178:179], s[6:7], 0, v[168:169]
	s_add_i32 m0, s5, 0xe000
	s_nop 0
	global_load_lds_dwordx4 v[178:179], off
	s_waitcnt lgkmcnt(8)
	s_barrier
	s_waitcnt lgkmcnt(0)
	s_setprio 1
	v_mfma_f32_16x16x32_bf16 v[126:129], v[130:133], v[146:149], v[126:129]
	v_mfma_f32_16x16x32_bf16 v[122:125], v[138:141], v[146:149], v[122:125]
	v_mfma_f32_16x16x32_bf16 v[110:113], v[130:133], v[154:157], v[110:113]
	v_mfma_f32_16x16x32_bf16 v[106:109], v[138:141], v[154:157], v[106:109]
	v_mfma_f32_16x16x32_bf16 v[94:97], v[130:133], v[174:177], v[94:97]
	v_mfma_f32_16x16x32_bf16 v[90:93], v[138:141], v[174:177], v[90:93]
	v_mfma_f32_16x16x32_bf16 v[78:81], v[130:133], v[188:191], v[78:81]
	v_mfma_f32_16x16x32_bf16 v[74:77], v[138:141], v[188:191], v[74:77]
	v_mfma_f32_16x16x32_bf16 v[126:129], v[134:137], v[150:153], v[126:129]
	v_mfma_f32_16x16x32_bf16 v[122:125], v[142:145], v[150:153], v[122:125]
	v_mfma_f32_16x16x32_bf16 v[110:113], v[134:137], v[170:173], v[110:113]
	v_mfma_f32_16x16x32_bf16 v[106:109], v[142:145], v[170:173], v[106:109]
	v_mfma_f32_16x16x32_bf16 v[94:97], v[134:137], v[184:187], v[94:97]
	v_mfma_f32_16x16x32_bf16 v[90:93], v[142:145], v[184:187], v[90:93]
	v_mfma_f32_16x16x32_bf16 v[78:81], v[134:137], v[206:209], v[78:81]
	v_mfma_f32_16x16x32_bf16 v[74:77], v[142:145], v[206:209], v[74:77]
	s_setprio 0
	s_barrier
	v_or_b32_e32 v178, 0x14000, v182
	v_add_u32_e32 v179, 0x14400, v182
	ds_read_b128 v[210:213], v178
	ds_read_b128 v[214:217], v179
	v_add_u32_e32 v178, 0x14800, v182
	v_add_u32_e32 v179, 0x14c00, v182
	s_mov_b32 m0, s12
	ds_read_b128 v[218:221], v178
	ds_read_b128 v[222:225], v179
	v_lshl_add_u64 v[178:179], s[8:9], 0, v[162:163]
	global_load_lds_dwordx4 v[178:179], off
	v_lshl_add_u64 v[192:193], s[8:9], 0, v[158:159]
	s_mov_b32 m0, s17
	s_nop 0
	global_load_lds_dwordx4 v[192:193], off
	s_barrier
	s_waitcnt lgkmcnt(0)
	s_setprio 1
	v_mfma_f32_16x16x32_bf16 v[118:121], v[210:213], v[146:149], v[118:121]
	v_mfma_f32_16x16x32_bf16 v[114:117], v[218:221], v[146:149], v[114:117]
	v_mfma_f32_16x16x32_bf16 v[102:105], v[210:213], v[154:157], v[102:105]
	v_mfma_f32_16x16x32_bf16 v[98:101], v[218:221], v[154:157], v[98:101]
	v_mfma_f32_16x16x32_bf16 v[86:89], v[210:213], v[174:177], v[86:89]
	v_mfma_f32_16x16x32_bf16 v[82:85], v[218:221], v[174:177], v[82:85]
	v_mfma_f32_16x16x32_bf16 v[70:73], v[210:213], v[188:191], v[70:73]
	v_mfma_f32_16x16x32_bf16 v[66:69], v[218:221], v[188:191], v[66:69]
	v_mfma_f32_16x16x32_bf16 v[118:121], v[214:217], v[150:153], v[118:121]
	v_mfma_f32_16x16x32_bf16 v[114:117], v[222:225], v[150:153], v[114:117]
	v_mfma_f32_16x16x32_bf16 v[102:105], v[214:217], v[170:173], v[102:105]
	v_mfma_f32_16x16x32_bf16 v[98:101], v[222:225], v[170:173], v[98:101]
	v_mfma_f32_16x16x32_bf16 v[86:89], v[214:217], v[184:187], v[86:89]
	v_mfma_f32_16x16x32_bf16 v[82:85], v[222:225], v[184:187], v[82:85]
	s_mov_b32 m0, s5
	v_mfma_f32_16x16x32_bf16 v[70:73], v[214:217], v[206:209], v[70:73]
	v_lshl_add_u64 v[226:227], s[10:11], 0, v[164:165]
	v_mfma_f32_16x16x32_bf16 v[66:69], v[222:225], v[206:209], v[66:69]
	s_setprio 0
	s_barrier
	ds_read_b128 v[146:149], v181 offset:16384
	ds_read_b128 v[150:153], v181 offset:17408
	ds_read_b128 v[154:157], v181 offset:18432
	ds_read_b128 v[170:173], v181 offset:19456
	ds_read_b128 v[174:177], v181 offset:20480
	ds_read_b128 v[184:187], v181 offset:21504
	ds_read_b128 v[188:191], v181 offset:22528
	ds_read_b128 v[206:209], v181 offset:23552
	global_load_lds_dwordx4 v[226:227], off
	v_lshl_add_u64 v[228:229], s[10:11], 0, v[160:161]
	s_mov_b32 m0, s26
	s_nop 0
	global_load_lds_dwordx4 v[228:229], off
	s_barrier
	s_waitcnt lgkmcnt(0)
	s_setprio 1
	v_mfma_f32_16x16x32_bf16 v[62:65], v[130:133], v[146:149], v[62:65]
	v_mfma_f32_16x16x32_bf16 v[58:61], v[138:141], v[146:149], v[58:61]
	v_mfma_f32_16x16x32_bf16 v[46:49], v[130:133], v[154:157], v[46:49]
	v_mfma_f32_16x16x32_bf16 v[42:45], v[138:141], v[154:157], v[42:45]
	v_mfma_f32_16x16x32_bf16 v[30:33], v[130:133], v[174:177], v[30:33]
	v_mfma_f32_16x16x32_bf16 v[26:29], v[138:141], v[174:177], v[26:29]
	v_mfma_f32_16x16x32_bf16 v[14:17], v[130:133], v[188:191], v[14:17]
	v_mfma_f32_16x16x32_bf16 v[10:13], v[138:141], v[188:191], v[10:13]
	v_mfma_f32_16x16x32_bf16 v[62:65], v[134:137], v[150:153], v[62:65]
	v_mfma_f32_16x16x32_bf16 v[58:61], v[142:145], v[150:153], v[58:61]
	v_mfma_f32_16x16x32_bf16 v[46:49], v[134:137], v[170:173], v[46:49]
	v_mfma_f32_16x16x32_bf16 v[42:45], v[142:145], v[170:173], v[42:45]
	v_mfma_f32_16x16x32_bf16 v[30:33], v[134:137], v[184:187], v[30:33]
	v_mfma_f32_16x16x32_bf16 v[26:29], v[142:145], v[184:187], v[26:29]
	v_mfma_f32_16x16x32_bf16 v[14:17], v[134:137], v[206:209], v[14:17]
	v_mfma_f32_16x16x32_bf16 v[10:13], v[142:145], v[206:209], v[10:13]
	s_setprio 0
	s_barrier
	s_add_u32 s80, s8, 0x100000
	s_addc_u32 s81, s9, 0
	s_mov_b32 m0, s34
	v_lshl_add_u64 v[130:131], s[80:81], 0, v[162:163]
	global_load_lds_dwordx4 v[130:131], off
	v_lshl_add_u64 v[130:131], s[80:81], 0, v[158:159]
	s_mov_b32 m0, s35
	s_nop 0
	global_load_lds_dwordx4 v[130:131], off
	s_waitcnt vmcnt(6)
	s_barrier
	s_setprio 1
	v_mfma_f32_16x16x32_bf16 v[54:57], v[210:213], v[146:149], v[54:57]
	v_mfma_f32_16x16x32_bf16 v[50:53], v[218:221], v[146:149], v[50:53]
	v_mfma_f32_16x16x32_bf16 v[38:41], v[210:213], v[154:157], v[38:41]
	v_mfma_f32_16x16x32_bf16 v[34:37], v[218:221], v[154:157], v[34:37]
	v_mfma_f32_16x16x32_bf16 v[22:25], v[210:213], v[174:177], v[22:25]
	v_mfma_f32_16x16x32_bf16 v[18:21], v[218:221], v[174:177], v[18:21]
	v_mfma_f32_16x16x32_bf16 v[6:9], v[210:213], v[188:191], v[6:9]
	v_mfma_f32_16x16x32_bf16 v[2:5], v[218:221], v[188:191], v[2:5]
	v_mfma_f32_16x16x32_bf16 v[54:57], v[214:217], v[150:153], v[54:57]
	v_mfma_f32_16x16x32_bf16 v[50:53], v[222:225], v[150:153], v[50:53]
	v_mfma_f32_16x16x32_bf16 v[38:41], v[214:217], v[170:173], v[38:41]
	v_mfma_f32_16x16x32_bf16 v[34:37], v[222:225], v[170:173], v[34:37]
	v_or_b32_e32 v130, 0x18000, v182
	v_mfma_f32_16x16x32_bf16 v[22:25], v[214:217], v[184:187], v[22:25]
	v_add_u32_e32 v134, 0x18400, v182
	v_mfma_f32_16x16x32_bf16 v[18:21], v[222:225], v[184:187], v[18:21]
	v_add_u32_e32 v138, 0x18800, v182
	v_mfma_f32_16x16x32_bf16 v[6:9], v[214:217], v[206:209], v[6:9]
	v_add_u32_e32 v142, 0x18c00, v182
	v_mfma_f32_16x16x32_bf16 v[2:5], v[222:225], v[206:209], v[2:5]
	s_setprio 0
	s_barrier
	ds_read_b128 v[130:133], v130
	ds_read_b128 v[134:137], v134
	ds_read_b128 v[138:141], v138
	ds_read_b128 v[142:145], v142
	s_add_u32 s10, s10, 0x100000
	s_addc_u32 s11, s11, 0
	s_mov_b32 m0, s42
	v_lshl_add_u64 v[210:211], s[10:11], 0, v[164:165]
	ds_read_b128 v[146:149], v181 offset:32768
	ds_read_b128 v[150:153], v181 offset:33792
	ds_read_b128 v[154:157], v181 offset:34816
	ds_read_b128 v[170:173], v181 offset:35840
	ds_read_b128 v[174:177], v181 offset:36864
	ds_read_b128 v[184:187], v181 offset:37888
	ds_read_b128 v[188:191], v181 offset:38912
	ds_read_b128 v[206:209], v181 offset:39936
	global_load_lds_dwordx4 v[210:211], off
	v_lshl_add_u64 v[210:211], s[10:11], 0, v[160:161]
	s_mov_b32 m0, s54
	s_nop 0
	global_load_lds_dwordx4 v[210:211], off
	s_waitcnt lgkmcnt(8)
	s_barrier
	s_waitcnt lgkmcnt(0)
	s_setprio 1
	v_mfma_f32_16x16x32_bf16 v[126:129], v[130:133], v[146:149], v[126:129]
	v_mfma_f32_16x16x32_bf16 v[122:125], v[138:141], v[146:149], v[122:125]
	v_mfma_f32_16x16x32_bf16 v[110:113], v[130:133], v[154:157], v[110:113]
	v_mfma_f32_16x16x32_bf16 v[106:109], v[138:141], v[154:157], v[106:109]
	v_mfma_f32_16x16x32_bf16 v[94:97], v[130:133], v[174:177], v[94:97]
	v_mfma_f32_16x16x32_bf16 v[90:93], v[138:141], v[174:177], v[90:93]
	v_mfma_f32_16x16x32_bf16 v[78:81], v[130:133], v[188:191], v[78:81]
	v_mfma_f32_16x16x32_bf16 v[74:77], v[138:141], v[188:191], v[74:77]
	v_mfma_f32_16x16x32_bf16 v[126:129], v[134:137], v[150:153], v[126:129]
	v_mfma_f32_16x16x32_bf16 v[122:125], v[142:145], v[150:153], v[122:125]
	v_mfma_f32_16x16x32_bf16 v[110:113], v[134:137], v[170:173], v[110:113]
	v_mfma_f32_16x16x32_bf16 v[106:109], v[142:145], v[170:173], v[106:109]
	v_mfma_f32_16x16x32_bf16 v[94:97], v[134:137], v[184:187], v[94:97]
	v_mfma_f32_16x16x32_bf16 v[90:93], v[142:145], v[184:187], v[90:93]
	v_mfma_f32_16x16x32_bf16 v[78:81], v[134:137], v[206:209], v[78:81]
	v_mfma_f32_16x16x32_bf16 v[74:77], v[142:145], v[206:209], v[74:77]
	s_setprio 0
	s_barrier
	v_or_b32_e32 v194, 0x1c000, v182
	s_mov_b32 m0, s55
	v_add_u32_e32 v197, 0x1c400, v182
	ds_read_b128 v[210:213], v194
	ds_read_b128 v[214:217], v197
	v_add_u32_e32 v194, 0x1c800, v182
	v_lshl_add_u64 v[178:179], v[178:179], 0, s[76:77]
	v_add_u32_e32 v197, 0x1cc00, v182
	ds_read_b128 v[218:221], v194
	ds_read_b128 v[222:225], v197
	global_load_lds_dwordx4 v[178:179], off
	v_lshl_add_u64 v[178:179], v[192:193], 0, s[76:77]
	s_mov_b32 m0, s56
	s_nop 0
	global_load_lds_dwordx4 v[178:179], off
	s_barrier
	s_waitcnt lgkmcnt(0)
	s_setprio 1
	v_mfma_f32_16x16x32_bf16 v[118:121], v[210:213], v[146:149], v[118:121]
	v_mfma_f32_16x16x32_bf16 v[114:117], v[218:221], v[146:149], v[114:117]
	v_mfma_f32_16x16x32_bf16 v[102:105], v[210:213], v[154:157], v[102:105]
	v_mfma_f32_16x16x32_bf16 v[98:101], v[218:221], v[154:157], v[98:101]
	v_mfma_f32_16x16x32_bf16 v[86:89], v[210:213], v[174:177], v[86:89]
	v_mfma_f32_16x16x32_bf16 v[82:85], v[218:221], v[174:177], v[82:85]
	v_mfma_f32_16x16x32_bf16 v[70:73], v[210:213], v[188:191], v[70:73]
	v_mfma_f32_16x16x32_bf16 v[66:69], v[218:221], v[188:191], v[66:69]
	v_mfma_f32_16x16x32_bf16 v[118:121], v[214:217], v[150:153], v[118:121]
	v_mfma_f32_16x16x32_bf16 v[114:117], v[222:225], v[150:153], v[114:117]
	v_mfma_f32_16x16x32_bf16 v[102:105], v[214:217], v[170:173], v[102:105]
	v_mfma_f32_16x16x32_bf16 v[98:101], v[222:225], v[170:173], v[98:101]
	v_mfma_f32_16x16x32_bf16 v[86:89], v[214:217], v[184:187], v[86:89]
	v_mfma_f32_16x16x32_bf16 v[82:85], v[222:225], v[184:187], v[82:85]
	s_mov_b32 m0, s57
	v_mfma_f32_16x16x32_bf16 v[70:73], v[214:217], v[206:209], v[70:73]
	v_lshl_add_u64 v[178:179], v[226:227], 0, s[76:77]
	v_mfma_f32_16x16x32_bf16 v[66:69], v[222:225], v[206:209], v[66:69]
	s_setprio 0
	s_barrier
	ds_read_b128 v[146:149], v181 offset:49152
	ds_read_b128 v[150:153], v181 offset:50176
	ds_read_b128 v[154:157], v181 offset:51200
	ds_read_b128 v[170:173], v181 offset:52224
	ds_read_b128 v[174:177], v181 offset:53248
	ds_read_b128 v[184:187], v181 offset:54272
	ds_read_b128 v[188:191], v181 offset:55296
	ds_read_b128 v[206:209], v181 offset:56320
	global_load_lds_dwordx4 v[178:179], off
	v_lshl_add_u64 v[178:179], v[228:229], 0, s[76:77]
	s_mov_b32 m0, s58
	s_nop 0
	global_load_lds_dwordx4 v[178:179], off
	s_barrier
	s_waitcnt lgkmcnt(0)
	s_setprio 1
	v_mfma_f32_16x16x32_bf16 v[62:65], v[130:133], v[146:149], v[62:65]
	v_mfma_f32_16x16x32_bf16 v[58:61], v[138:141], v[146:149], v[58:61]
	v_mfma_f32_16x16x32_bf16 v[46:49], v[130:133], v[154:157], v[46:49]
	v_mfma_f32_16x16x32_bf16 v[42:45], v[138:141], v[154:157], v[42:45]
	v_mfma_f32_16x16x32_bf16 v[30:33], v[130:133], v[174:177], v[30:33]
	v_mfma_f32_16x16x32_bf16 v[26:29], v[138:141], v[174:177], v[26:29]
	v_mfma_f32_16x16x32_bf16 v[14:17], v[130:133], v[188:191], v[14:17]
	v_mfma_f32_16x16x32_bf16 v[10:13], v[138:141], v[188:191], v[10:13]
	v_mfma_f32_16x16x32_bf16 v[62:65], v[134:137], v[150:153], v[62:65]
	v_mfma_f32_16x16x32_bf16 v[58:61], v[142:145], v[150:153], v[58:61]
	v_mfma_f32_16x16x32_bf16 v[46:49], v[134:137], v[170:173], v[46:49]
	v_mfma_f32_16x16x32_bf16 v[42:45], v[142:145], v[170:173], v[42:45]
	v_mfma_f32_16x16x32_bf16 v[30:33], v[134:137], v[184:187], v[30:33]
	v_mfma_f32_16x16x32_bf16 v[26:29], v[142:145], v[184:187], v[26:29]
	v_mfma_f32_16x16x32_bf16 v[14:17], v[134:137], v[206:209], v[14:17]
	v_mfma_f32_16x16x32_bf16 v[10:13], v[142:145], v[206:209], v[10:13]
	s_setprio 0
	s_barrier
	s_add_u32 s8, s8, 0x100080
	s_addc_u32 s9, s9, 0
	s_mov_b32 m0, s59
	v_lshl_add_u64 v[130:131], s[8:9], 0, v[162:163]
	global_load_lds_dwordx4 v[130:131], off
	v_lshl_add_u64 v[130:131], s[8:9], 0, v[158:159]
	s_mov_b32 m0, s67
	s_nop 0
	global_load_lds_dwordx4 v[130:131], off
	s_waitcnt vmcnt(6)
	s_barrier
	s_setprio 1
	v_mfma_f32_16x16x32_bf16 v[54:57], v[210:213], v[146:149], v[54:57]
	v_mfma_f32_16x16x32_bf16 v[50:53], v[218:221], v[146:149], v[50:53]
	v_mfma_f32_16x16x32_bf16 v[38:41], v[210:213], v[154:157], v[38:41]
	v_mfma_f32_16x16x32_bf16 v[34:37], v[218:221], v[154:157], v[34:37]
	v_mfma_f32_16x16x32_bf16 v[22:25], v[210:213], v[174:177], v[22:25]
	v_mfma_f32_16x16x32_bf16 v[18:21], v[218:221], v[174:177], v[18:21]
	v_mfma_f32_16x16x32_bf16 v[6:9], v[210:213], v[188:191], v[6:9]
	v_mfma_f32_16x16x32_bf16 v[2:5], v[218:221], v[188:191], v[2:5]
	v_mfma_f32_16x16x32_bf16 v[54:57], v[214:217], v[150:153], v[54:57]
	v_mfma_f32_16x16x32_bf16 v[50:53], v[222:225], v[150:153], v[50:53]
	v_mfma_f32_16x16x32_bf16 v[38:41], v[214:217], v[170:173], v[38:41]
	v_mfma_f32_16x16x32_bf16 v[34:37], v[222:225], v[170:173], v[34:37]
	v_mfma_f32_16x16x32_bf16 v[22:25], v[214:217], v[184:187], v[22:25]
	v_mfma_f32_16x16x32_bf16 v[18:21], v[222:225], v[184:187], v[18:21]
	v_mfma_f32_16x16x32_bf16 v[6:9], v[214:217], v[206:209], v[6:9]
	v_mfma_f32_16x16x32_bf16 v[2:5], v[222:225], v[206:209], v[2:5]
	s_setprio 0
	s_add_i32 s79, s79, 2
	s_add_u32 s6, s6, 0x100
	s_addc_u32 s7, s7, 0
	s_add_u32 s1, s1, 0x100
	s_addc_u32 s78, s78, 0
	s_cmp_gt_u32 s79, 61
	s_barrier
	s_cbranch_scc0 .LBB0_255
	s_lshl_b32 s1, s28, 9
	s_and_b32 s1, s1, 0xfffff800
	s_lshl_b32 s6, s29, 8
	s_add_i32 s1, s1, s6
	v_add_u32_e32 v172, s1, v180
	s_lshl_b32 s1, s28, 8
	s_and_b32 s1, s1, 0x300
	v_or_b32_e32 v132, s1, v183
	v_mov_b64_e32 v[170:171], s[50:51]
	v_mad_i64_i32 v[130:131], s[6:7], v172, s37, v[170:171]
	v_lshlrev_b32_e32 v194, 1, v132
	v_lshl_add_u64 v[130:131], v[130:131], 0, v[194:195]
	v_lshl_add_u64 v[132:133], v[130:131], 0, s[84:85]
	v_add_co_u32_e32 v130, vcc, s16, v130
	v_or_b32_e32 v178, 16, v172
	s_nop 0
	v_addc_co_u32_e32 v131, vcc, 0, v131, vcc
	global_load_dwordx4 v[184:187], v[130:131], off offset:2048
	global_load_dwordx4 v[154:157], v[132:133], off offset:256
	v_mad_i64_i32 v[130:131], s[6:7], v178, s37, v[170:171]
	v_lshl_add_u64 v[130:131], v[130:131], 0, v[194:195]
	v_lshl_add_u64 v[132:133], v[130:131], 0, s[84:85]
	v_add_co_u32_e32 v130, vcc, s16, v130
	v_or_b32_e32 v176, 32, v172
	s_nop 0
	v_addc_co_u32_e32 v131, vcc, 0, v131, vcc
	global_load_dwordx4 v[150:153], v[130:131], off offset:2048
	global_load_dwordx4 v[146:149], v[132:133], off offset:256
	v_mad_i64_i32 v[130:131], s[6:7], v176, s37, v[170:171]
	v_lshl_add_u64 v[130:131], v[130:131], 0, v[194:195]
	v_lshl_add_u64 v[132:133], v[130:131], 0, s[84:85]
	v_add_co_u32_e32 v130, vcc, s16, v130
	v_or_b32_e32 v174, 48, v172
	s_nop 0
	v_addc_co_u32_e32 v131, vcc, 0, v131, vcc
	global_load_dwordx4 v[142:145], v[130:131], off offset:2048
	global_load_dwordx4 v[138:141], v[132:133], off offset:256
	v_mad_i64_i32 v[130:131], s[6:7], v174, s37, v[170:171]
	v_lshl_add_u64 v[130:131], v[130:131], 0, v[194:195]
	v_lshl_add_u64 v[132:133], v[130:131], 0, s[84:85]
	v_add_co_u32_e32 v130, vcc, s16, v130
	v_pk_mul_f32 v[126:127], v[126:127], s[72:73] op_sel_hi:[1,0]
	s_nop 0
	v_addc_co_u32_e32 v131, vcc, 0, v131, vcc
	global_load_dwordx4 v[134:137], v[130:131], off offset:2048
	s_nop 0
	global_load_dwordx4 v[130:133], v[132:133], off offset:256
	v_pk_mul_f32 v[190:191], v[124:125], s[72:73] op_sel_hi:[1,0]
	v_pk_mul_f32 v[128:129], v[128:129], s[72:73] op_sel_hi:[1,0]
	v_pk_mul_f32 v[122:123], v[122:123], s[72:73] op_sel_hi:[1,0]
	v_ashrrev_i32_e32 v173, 31, v172
	v_lshlrev_b64 v[188:189], 11, v[172:173]
	v_pk_mul_f32 v[118:119], v[118:119], s[72:73] op_sel_hi:[1,0]
	v_pk_mul_f32 v[120:121], v[120:121], s[72:73] op_sel_hi:[1,0]
	v_pk_mul_f32 v[110:111], v[110:111], s[72:73] op_sel_hi:[1,0]
	v_pk_mul_f32 v[112:113], v[112:113], s[72:73] op_sel_hi:[1,0]
	v_ashrrev_i32_e32 v179, 31, v178
	v_pk_mul_f32 v[102:103], v[102:103], s[72:73] op_sel_hi:[1,0]
	v_pk_mul_f32 v[104:105], v[104:105], s[72:73] op_sel_hi:[1,0]
	v_pk_mul_f32 v[94:95], v[94:95], s[72:73] op_sel_hi:[1,0]
	v_pk_mul_f32 v[96:97], v[96:97], s[72:73] op_sel_hi:[1,0]
	v_ashrrev_i32_e32 v177, 31, v176
	v_pk_mul_f32 v[86:87], v[86:87], s[72:73] op_sel_hi:[1,0]
	v_pk_mul_f32 v[88:89], v[88:89], s[72:73] op_sel_hi:[1,0]
	v_pk_mul_f32 v[78:79], v[78:79], s[72:73] op_sel_hi:[1,0]
	v_pk_mul_f32 v[80:81], v[80:81], s[72:73] op_sel_hi:[1,0]
	v_ashrrev_i32_e32 v175, 31, v174
	v_pk_mul_f32 v[70:71], v[70:71], s[72:73] op_sel_hi:[1,0]
	v_pk_mul_f32 v[72:73], v[72:73], s[72:73] op_sel_hi:[1,0]
	s_waitcnt vmcnt(0)
	v_lshlrev_b32_e32 v124, 16, v184
	v_and_b32_e32 v125, 0xffff0000, v184
	v_mul_f32_e32 v124, v126, v124
	v_mul_f32_e32 v125, v127, v125
	v_cvt_pk_bf16_f32 v124, v124, v125
	v_lshlrev_b32_e32 v125, 16, v185
	v_and_b32_e32 v126, 0xffff0000, v185
	v_mul_f32_e32 v125, v128, v125
	v_mul_f32_e32 v126, v129, v126
	v_cvt_pk_bf16_f32 v125, v125, v126
	v_lshlrev_b32_e32 v126, 16, v186
	v_mul_f32_e32 v122, v122, v126
	v_and_b32_e32 v126, 0xffff0000, v186
	v_mul_f32_e32 v123, v123, v126
	v_cvt_pk_bf16_f32 v126, v122, v123
	v_lshlrev_b32_e32 v122, 16, v187
	v_and_b32_e32 v123, 0xffff0000, v187
	v_mul_f32_e32 v122, v190, v122
	v_mul_f32_e32 v123, v191, v123
	v_cvt_pk_bf16_f32 v127, v122, v123
	v_lshl_add_u64 v[122:123], s[74:75], 0, v[188:189]
	v_lshl_add_u64 v[122:123], v[122:123], 0, v[194:195]
	global_store_dwordx4 v[122:123], v[124:127], off
	s_nop 1
	v_pk_mul_f32 v[124:125], v[116:117], s[72:73] op_sel_hi:[1,0]
	v_pk_mul_f32 v[116:117], v[114:115], s[72:73] op_sel_hi:[1,0]
	v_lshlrev_b32_e32 v114, 16, v154
	v_and_b32_e32 v115, 0xffff0000, v154
	v_mul_f32_e32 v114, v118, v114
	v_mul_f32_e32 v115, v119, v115
	v_cvt_pk_bf16_f32 v114, v114, v115
	v_lshlrev_b32_e32 v115, 16, v155
	v_and_b32_e32 v118, 0xffff0000, v155
	v_mul_f32_e32 v115, v120, v115
	v_mul_f32_e32 v118, v121, v118
	v_cvt_pk_bf16_f32 v115, v115, v118
	v_lshlrev_b32_e32 v118, 16, v156
	v_mul_f32_e32 v116, v116, v118
	v_and_b32_e32 v118, 0xffff0000, v156
	v_mul_f32_e32 v117, v117, v118
	v_cvt_pk_bf16_f32 v116, v116, v117
	v_lshlrev_b32_e32 v117, 16, v157
	v_mul_f32_e32 v117, v124, v117
	v_and_b32_e32 v118, 0xffff0000, v157
	v_mul_f32_e32 v118, v125, v118
	v_cvt_pk_bf16_f32 v117, v117, v118
	global_store_dwordx4 v[122:123], v[114:117], off offset:256
	s_nop 1
	v_pk_mul_f32 v[116:117], v[108:109], s[72:73] op_sel_hi:[1,0]
	v_pk_mul_f32 v[108:109], v[106:107], s[72:73] op_sel_hi:[1,0]
	v_lshlrev_b32_e32 v106, 16, v150
	v_and_b32_e32 v107, 0xffff0000, v150
	v_mul_f32_e32 v106, v110, v106
	v_mul_f32_e32 v107, v111, v107
	v_cvt_pk_bf16_f32 v106, v106, v107
	v_lshlrev_b32_e32 v107, 16, v151
	v_and_b32_e32 v110, 0xffff0000, v151
	v_mul_f32_e32 v107, v112, v107
	v_mul_f32_e32 v110, v113, v110
	v_cvt_pk_bf16_f32 v107, v107, v110
	v_lshlrev_b32_e32 v110, 16, v152
	v_mul_f32_e32 v108, v108, v110
	v_and_b32_e32 v110, 0xffff0000, v152
	v_mul_f32_e32 v109, v109, v110
	v_cvt_pk_bf16_f32 v108, v108, v109
	v_lshlrev_b32_e32 v109, 16, v153
	v_and_b32_e32 v110, 0xffff0000, v153
	v_lshlrev_b64 v[114:115], 11, v[178:179]
	v_mul_f32_e32 v109, v116, v109
	v_mul_f32_e32 v110, v117, v110
	v_cvt_pk_bf16_f32 v109, v109, v110
	v_lshl_add_u64 v[110:111], s[74:75], 0, v[114:115]
	v_lshl_add_u64 v[110:111], v[110:111], 0, v[194:195]
	global_store_dwordx4 v[110:111], v[106:109], off
	s_nop 1
	v_pk_mul_f32 v[106:107], v[100:101], s[72:73] op_sel_hi:[1,0]
	v_pk_mul_f32 v[100:101], v[98:99], s[72:73] op_sel_hi:[1,0]
	v_lshlrev_b32_e32 v98, 16, v146
	v_and_b32_e32 v99, 0xffff0000, v146
	v_mul_f32_e32 v98, v102, v98
	v_mul_f32_e32 v99, v103, v99
	v_cvt_pk_bf16_f32 v98, v98, v99
	v_lshlrev_b32_e32 v99, 16, v147
	v_and_b32_e32 v102, 0xffff0000, v147
	v_mul_f32_e32 v99, v104, v99
	v_mul_f32_e32 v102, v105, v102
	v_cvt_pk_bf16_f32 v99, v99, v102
	v_lshlrev_b32_e32 v102, 16, v148
	v_mul_f32_e32 v100, v100, v102
	v_and_b32_e32 v102, 0xffff0000, v148
	v_mul_f32_e32 v101, v101, v102
	v_cvt_pk_bf16_f32 v100, v100, v101
	v_lshlrev_b32_e32 v101, 16, v149
	v_mul_f32_e32 v101, v106, v101
	v_and_b32_e32 v102, 0xffff0000, v149
	v_mul_f32_e32 v102, v107, v102
	v_cvt_pk_bf16_f32 v101, v101, v102
	global_store_dwordx4 v[110:111], v[98:101], off offset:256
	s_nop 1
	v_pk_mul_f32 v[100:101], v[92:93], s[72:73] op_sel_hi:[1,0]
	v_pk_mul_f32 v[92:93], v[90:91], s[72:73] op_sel_hi:[1,0]
	v_lshlrev_b32_e32 v90, 16, v142
	v_and_b32_e32 v91, 0xffff0000, v142
	v_mul_f32_e32 v90, v94, v90
	v_mul_f32_e32 v91, v95, v91
	v_cvt_pk_bf16_f32 v90, v90, v91
	v_lshlrev_b32_e32 v91, 16, v143
	v_and_b32_e32 v94, 0xffff0000, v143
	v_mul_f32_e32 v91, v96, v91
	v_mul_f32_e32 v94, v97, v94
	v_cvt_pk_bf16_f32 v91, v91, v94
	v_lshlrev_b32_e32 v94, 16, v144
	v_mul_f32_e32 v92, v92, v94
	v_and_b32_e32 v94, 0xffff0000, v144
	v_mul_f32_e32 v93, v93, v94
	v_cvt_pk_bf16_f32 v92, v92, v93
	v_lshlrev_b32_e32 v93, 16, v145
	v_and_b32_e32 v94, 0xffff0000, v145
	v_lshlrev_b64 v[98:99], 11, v[176:177]
	v_mul_f32_e32 v93, v100, v93
	v_mul_f32_e32 v94, v101, v94
	v_cvt_pk_bf16_f32 v93, v93, v94
	v_lshl_add_u64 v[94:95], s[74:75], 0, v[98:99]
	v_lshl_add_u64 v[94:95], v[94:95], 0, v[194:195]
	global_store_dwordx4 v[94:95], v[90:93], off
	s_nop 1
	v_pk_mul_f32 v[90:91], v[84:85], s[72:73] op_sel_hi:[1,0]
	v_pk_mul_f32 v[84:85], v[82:83], s[72:73] op_sel_hi:[1,0]
	v_lshlrev_b32_e32 v82, 16, v138
	v_and_b32_e32 v83, 0xffff0000, v138
	v_mul_f32_e32 v82, v86, v82
	v_mul_f32_e32 v83, v87, v83
	v_cvt_pk_bf16_f32 v82, v82, v83
	v_lshlrev_b32_e32 v83, 16, v139
	v_and_b32_e32 v86, 0xffff0000, v139
	v_mul_f32_e32 v83, v88, v83
	v_mul_f32_e32 v86, v89, v86
	v_cvt_pk_bf16_f32 v83, v83, v86
	v_lshlrev_b32_e32 v86, 16, v140
	v_mul_f32_e32 v84, v84, v86
	v_and_b32_e32 v86, 0xffff0000, v140
	v_mul_f32_e32 v85, v85, v86
	v_cvt_pk_bf16_f32 v84, v84, v85
	v_lshlrev_b32_e32 v85, 16, v141
	v_mul_f32_e32 v85, v90, v85
	v_and_b32_e32 v86, 0xffff0000, v141
	v_mul_f32_e32 v86, v91, v86
	v_cvt_pk_bf16_f32 v85, v85, v86
	global_store_dwordx4 v[94:95], v[82:85], off offset:256
	s_nop 1
	v_pk_mul_f32 v[84:85], v[76:77], s[72:73] op_sel_hi:[1,0]
	v_pk_mul_f32 v[76:77], v[74:75], s[72:73] op_sel_hi:[1,0]
	v_lshlrev_b32_e32 v74, 16, v134
	v_and_b32_e32 v75, 0xffff0000, v134
	v_mul_f32_e32 v74, v78, v74
	v_mul_f32_e32 v75, v79, v75
	v_cvt_pk_bf16_f32 v74, v74, v75
	v_lshlrev_b32_e32 v75, 16, v135
	v_and_b32_e32 v78, 0xffff0000, v135
	v_mul_f32_e32 v75, v80, v75
	v_mul_f32_e32 v78, v81, v78
	v_cvt_pk_bf16_f32 v75, v75, v78
	v_lshlrev_b32_e32 v78, 16, v136
	v_mul_f32_e32 v76, v76, v78
	v_and_b32_e32 v78, 0xffff0000, v136
	v_mul_f32_e32 v77, v77, v78
	v_cvt_pk_bf16_f32 v76, v76, v77
	v_lshlrev_b32_e32 v77, 16, v137
	v_and_b32_e32 v78, 0xffff0000, v137
	v_lshlrev_b64 v[82:83], 11, v[174:175]
	v_mul_f32_e32 v77, v84, v77
	v_mul_f32_e32 v78, v85, v78
	v_cvt_pk_bf16_f32 v77, v77, v78
	v_lshl_add_u64 v[78:79], s[74:75], 0, v[82:83]
	v_lshl_add_u64 v[78:79], v[78:79], 0, v[194:195]
	global_store_dwordx4 v[78:79], v[74:77], off
	s_nop 1
	v_pk_mul_f32 v[74:75], v[68:69], s[72:73] op_sel_hi:[1,0]
	v_pk_mul_f32 v[68:69], v[66:67], s[72:73] op_sel_hi:[1,0]
	v_lshlrev_b32_e32 v66, 16, v130
	v_and_b32_e32 v67, 0xffff0000, v130
	v_mul_f32_e32 v66, v70, v66
	v_mul_f32_e32 v67, v71, v67
	v_cvt_pk_bf16_f32 v66, v66, v67
	v_lshlrev_b32_e32 v67, 16, v131
	v_and_b32_e32 v70, 0xffff0000, v131
	v_mul_f32_e32 v67, v72, v67
	v_mul_f32_e32 v70, v73, v70
	v_cvt_pk_bf16_f32 v67, v67, v70
	v_lshlrev_b32_e32 v70, 16, v132
	v_mul_f32_e32 v68, v68, v70
	v_and_b32_e32 v70, 0xffff0000, v132
	v_mul_f32_e32 v69, v69, v70
	v_cvt_pk_bf16_f32 v68, v68, v69
	v_lshlrev_b32_e32 v69, 16, v133
	v_mul_f32_e32 v69, v74, v69
	v_and_b32_e32 v70, 0xffff0000, v133
	v_mul_f32_e32 v70, v75, v70
	v_cvt_pk_bf16_f32 v69, v69, v70
	global_store_dwordx4 v[78:79], v[66:69], off offset:256
	v_add_u32_e32 v78, 0x80, v172
	s_nop 0
	v_mad_i64_i32 v[66:67], s[6:7], v78, s37, v[170:171]
	v_lshl_add_u64 v[66:67], v[66:67], 0, v[194:195]
	v_add_co_u32_e32 v68, vcc, s16, v66
	v_add_u32_e32 v86, 0x90, v172
	s_nop 0
	v_addc_co_u32_e32 v69, vcc, 0, v67, vcc
	global_load_dwordx4 v[70:73], v[68:69], off offset:2048
	v_lshl_add_u64 v[66:67], v[66:67], 0, s[84:85]
	global_load_dwordx4 v[74:77], v[66:67], off offset:256
	v_pk_mul_f32 v[96:97], v[56:57], s[72:73] op_sel_hi:[1,0]
	v_mad_i64_i32 v[56:57], s[6:7], v86, s37, v[170:171]
	v_lshl_add_u64 v[56:57], v[56:57], 0, v[194:195]
	v_pk_mul_f32 v[94:95], v[58:59], s[72:73] op_sel_hi:[1,0]
	v_add_co_u32_e32 v58, vcc, s16, v56
	v_pk_mul_f32 v[92:93], v[60:61], s[72:73] op_sel_hi:[1,0]
	s_nop 0
	v_addc_co_u32_e32 v59, vcc, 0, v57, vcc
	global_load_dwordx4 v[58:61], v[58:59], off offset:2048
	v_add_u32_e32 v68, 0xa0, v172
	v_pk_mul_f32 v[102:103], v[50:51], s[72:73] op_sel_hi:[1,0]
	v_mad_i64_i32 v[50:51], s[6:7], v68, s37, v[170:171]
	v_add_u32_e32 v66, 0xb0, v172
	v_lshl_add_u64 v[50:51], v[50:51], 0, v[194:195]
	v_pk_mul_f32 v[100:101], v[52:53], s[72:73] op_sel_hi:[1,0]
	v_mad_i64_i32 v[52:53], s[6:7], v66, s37, v[170:171]
	v_lshl_add_u64 v[82:83], v[50:51], 0, s[84:85]
	v_add_co_u32_e32 v50, vcc, s16, v50
	v_lshl_add_u64 v[52:53], v[52:53], 0, v[194:195]
	s_nop 0
	v_addc_co_u32_e32 v51, vcc, 0, v51, vcc
	v_ashrrev_i32_e32 v79, 31, v78
	v_lshl_add_u64 v[104:105], v[52:53], 0, s[84:85]
	v_add_co_u32_e32 v52, vcc, s16, v52
	v_pk_mul_f32 v[98:99], v[54:55], s[72:73] op_sel_hi:[1,0]
	v_lshlrev_b64 v[54:55], 11, v[78:79]
	v_lshl_add_u64 v[56:57], v[56:57], 0, s[84:85]
	v_addc_co_u32_e32 v53, vcc, 0, v53, vcc
	v_pk_mul_f32 v[88:89], v[64:65], s[72:73] op_sel_hi:[1,0]
	v_pk_mul_f32 v[90:91], v[62:63], s[72:73] op_sel_hi:[1,0]
	v_lshl_add_u64 v[106:107], s[74:75], 0, v[54:55]
	global_load_dwordx4 v[62:65], v[56:57], off offset:256
	global_load_dwordx4 v[78:81], v[50:51], off offset:2048
	s_nop 0
	global_load_dwordx4 v[82:85], v[82:83], off offset:256
	s_nop 0
	global_load_dwordx4 v[54:57], v[52:53], off offset:2048
	s_nop 0
	global_load_dwordx4 v[50:53], v[104:105], off offset:256
	v_lshl_add_u64 v[104:105], v[106:107], 0, v[194:195]
	v_pk_mul_f32 v[46:47], v[46:47], s[72:73] op_sel_hi:[1,0]
	v_pk_mul_f32 v[48:49], v[48:49], s[72:73] op_sel_hi:[1,0]
	v_ashrrev_i32_e32 v87, 31, v86
	v_pk_mul_f32 v[38:39], v[38:39], s[72:73] op_sel_hi:[1,0]
	v_pk_mul_f32 v[40:41], v[40:41], s[72:73] op_sel_hi:[1,0]
	v_pk_mul_f32 v[30:31], v[30:31], s[72:73] op_sel_hi:[1,0]
	v_pk_mul_f32 v[32:33], v[32:33], s[72:73] op_sel_hi:[1,0]
	v_ashrrev_i32_e32 v69, 31, v68
	v_pk_mul_f32 v[22:23], v[22:23], s[72:73] op_sel_hi:[1,0]
	v_pk_mul_f32 v[24:25], v[24:25], s[72:73] op_sel_hi:[1,0]
	v_pk_mul_f32 v[14:15], v[14:15], s[72:73] op_sel_hi:[1,0]
	v_pk_mul_f32 v[16:17], v[16:17], s[72:73] op_sel_hi:[1,0]
	v_ashrrev_i32_e32 v67, 31, v66
	v_pk_mul_f32 v[6:7], v[6:7], s[72:73] op_sel_hi:[1,0]
	v_pk_mul_f32 v[8:9], v[8:9], s[72:73] op_sel_hi:[1,0]
	s_waitcnt vmcnt(0)
	v_lshlrev_b32_e32 v106, 16, v70
	v_and_b32_e32 v70, 0xffff0000, v70
	v_lshlrev_b32_e32 v107, 16, v71
	v_and_b32_e32 v71, 0xffff0000, v71
	v_lshlrev_b32_e32 v108, 16, v72
	v_and_b32_e32 v72, 0xffff0000, v72
	v_lshlrev_b32_e32 v109, 16, v73
	v_and_b32_e32 v73, 0xffff0000, v73
	v_mul_f32_e32 v70, v91, v70
	v_mul_f32_e32 v71, v89, v71
	v_mul_f32_e32 v72, v95, v72
	v_mul_f32_e32 v73, v93, v73
	v_mul_f32_e32 v90, v90, v106
	v_mul_f32_e32 v88, v88, v107
	v_mul_f32_e32 v89, v94, v108
	v_mul_f32_e32 v91, v92, v109
	v_cvt_pk_bf16_f32 v70, v90, v70
	v_cvt_pk_bf16_f32 v71, v88, v71
	v_cvt_pk_bf16_f32 v72, v89, v72
	v_cvt_pk_bf16_f32 v73, v91, v73
	v_lshlrev_b32_e32 v111, 16, v75
	v_and_b32_e32 v75, 0xffff0000, v75
	global_store_dwordx4 v[104:105], v[70:73], off
	v_lshlrev_b32_e32 v110, 16, v74
	v_and_b32_e32 v74, 0xffff0000, v74
	v_lshlrev_b32_e32 v72, 16, v76
	v_and_b32_e32 v73, 0xffff0000, v76
	v_mul_f32_e32 v71, v97, v75
	v_mul_f32_e32 v72, v102, v72
	v_mul_f32_e32 v73, v103, v73
	v_mul_f32_e32 v92, v98, v110
	v_mul_f32_e32 v74, v99, v74
	v_mul_f32_e32 v93, v96, v111
	v_cvt_pk_bf16_f32 v70, v92, v74
	v_cvt_pk_bf16_f32 v71, v93, v71
	v_cvt_pk_bf16_f32 v72, v72, v73
	v_lshlrev_b32_e32 v73, 16, v77
	v_mul_f32_e32 v73, v100, v73
	v_and_b32_e32 v74, 0xffff0000, v77
	v_mul_f32_e32 v74, v101, v74
	v_cvt_pk_bf16_f32 v73, v73, v74
	global_store_dwordx4 v[104:105], v[70:73], off offset:256
	s_nop 1
	v_pk_mul_f32 v[72:73], v[44:45], s[72:73] op_sel_hi:[1,0]
	v_pk_mul_f32 v[44:45], v[42:43], s[72:73] op_sel_hi:[1,0]
	v_lshlrev_b32_e32 v42, 16, v58
	v_and_b32_e32 v43, 0xffff0000, v58
	v_mul_f32_e32 v42, v46, v42
	v_mul_f32_e32 v43, v47, v43
	v_cvt_pk_bf16_f32 v42, v42, v43
	v_lshlrev_b32_e32 v43, 16, v59
	v_and_b32_e32 v46, 0xffff0000, v59
	v_mul_f32_e32 v43, v48, v43
	v_mul_f32_e32 v46, v49, v46
	v_cvt_pk_bf16_f32 v43, v43, v46
	v_lshlrev_b32_e32 v46, 16, v60
	v_mul_f32_e32 v44, v44, v46
	v_and_b32_e32 v46, 0xffff0000, v60
	v_mul_f32_e32 v45, v45, v46
	v_cvt_pk_bf16_f32 v44, v44, v45
	v_lshlrev_b32_e32 v45, 16, v61
	v_and_b32_e32 v46, 0xffff0000, v61
	v_lshlrev_b64 v[70:71], 11, v[86:87]
	v_mul_f32_e32 v45, v72, v45
	v_mul_f32_e32 v46, v73, v46
	v_cvt_pk_bf16_f32 v45, v45, v46
	v_lshl_add_u64 v[46:47], s[74:75], 0, v[70:71]
	v_lshl_add_u64 v[46:47], v[46:47], 0, v[194:195]
	global_store_dwordx4 v[46:47], v[42:45], off
	s_nop 1
	v_pk_mul_f32 v[42:43], v[36:37], s[72:73] op_sel_hi:[1,0]
	v_pk_mul_f32 v[36:37], v[34:35], s[72:73] op_sel_hi:[1,0]
	v_lshlrev_b32_e32 v34, 16, v62
	v_and_b32_e32 v35, 0xffff0000, v62
	v_mul_f32_e32 v34, v38, v34
	v_mul_f32_e32 v35, v39, v35
	v_cvt_pk_bf16_f32 v34, v34, v35
	v_lshlrev_b32_e32 v35, 16, v63
	v_and_b32_e32 v38, 0xffff0000, v63
	v_mul_f32_e32 v35, v40, v35
	v_mul_f32_e32 v38, v41, v38
	v_cvt_pk_bf16_f32 v35, v35, v38
	v_lshlrev_b32_e32 v38, 16, v64
	v_mul_f32_e32 v36, v36, v38
	v_and_b32_e32 v38, 0xffff0000, v64
	v_mul_f32_e32 v37, v37, v38
	v_cvt_pk_bf16_f32 v36, v36, v37
	v_lshlrev_b32_e32 v37, 16, v65
	v_mul_f32_e32 v37, v42, v37
	v_and_b32_e32 v38, 0xffff0000, v65
	v_mul_f32_e32 v38, v43, v38
	v_cvt_pk_bf16_f32 v37, v37, v38
	global_store_dwordx4 v[46:47], v[34:37], off offset:256
	s_nop 1
	v_pk_mul_f32 v[36:37], v[28:29], s[72:73] op_sel_hi:[1,0]
	v_pk_mul_f32 v[28:29], v[26:27], s[72:73] op_sel_hi:[1,0]
	v_lshlrev_b32_e32 v26, 16, v78
	v_and_b32_e32 v27, 0xffff0000, v78
	v_mul_f32_e32 v26, v30, v26
	v_mul_f32_e32 v27, v31, v27
	v_cvt_pk_bf16_f32 v26, v26, v27
	v_lshlrev_b32_e32 v27, 16, v79
	v_and_b32_e32 v30, 0xffff0000, v79
	v_mul_f32_e32 v27, v32, v27
	v_mul_f32_e32 v30, v33, v30
	v_cvt_pk_bf16_f32 v27, v27, v30
	v_lshlrev_b32_e32 v30, 16, v80
	v_mul_f32_e32 v28, v28, v30
	v_and_b32_e32 v30, 0xffff0000, v80
	v_mul_f32_e32 v29, v29, v30
	v_cvt_pk_bf16_f32 v28, v28, v29
	v_lshlrev_b32_e32 v29, 16, v81
	v_and_b32_e32 v30, 0xffff0000, v81
	v_lshlrev_b64 v[34:35], 11, v[68:69]
	v_mul_f32_e32 v29, v36, v29
	v_mul_f32_e32 v30, v37, v30
	v_cvt_pk_bf16_f32 v29, v29, v30
	v_lshl_add_u64 v[30:31], s[74:75], 0, v[34:35]
	v_lshl_add_u64 v[30:31], v[30:31], 0, v[194:195]
	global_store_dwordx4 v[30:31], v[26:29], off
	s_nop 1
	v_pk_mul_f32 v[26:27], v[20:21], s[72:73] op_sel_hi:[1,0]
	v_pk_mul_f32 v[20:21], v[18:19], s[72:73] op_sel_hi:[1,0]
	v_lshlrev_b32_e32 v18, 16, v82
	v_and_b32_e32 v19, 0xffff0000, v82
	v_mul_f32_e32 v18, v22, v18
	v_mul_f32_e32 v19, v23, v19
	v_cvt_pk_bf16_f32 v18, v18, v19
	v_lshlrev_b32_e32 v19, 16, v83
	v_and_b32_e32 v22, 0xffff0000, v83
	v_mul_f32_e32 v19, v24, v19
	v_mul_f32_e32 v22, v25, v22
	v_cvt_pk_bf16_f32 v19, v19, v22
	v_lshlrev_b32_e32 v22, 16, v84
	v_mul_f32_e32 v20, v20, v22
	v_and_b32_e32 v22, 0xffff0000, v84
	v_mul_f32_e32 v21, v21, v22
	v_cvt_pk_bf16_f32 v20, v20, v21
	v_lshlrev_b32_e32 v21, 16, v85
	v_mul_f32_e32 v21, v26, v21
	v_and_b32_e32 v22, 0xffff0000, v85
	v_mul_f32_e32 v22, v27, v22
	v_cvt_pk_bf16_f32 v21, v21, v22
	global_store_dwordx4 v[30:31], v[18:21], off offset:256
	s_nop 1
	v_pk_mul_f32 v[20:21], v[12:13], s[72:73] op_sel_hi:[1,0]
	v_pk_mul_f32 v[12:13], v[10:11], s[72:73] op_sel_hi:[1,0]
	v_lshlrev_b32_e32 v10, 16, v54
	v_and_b32_e32 v11, 0xffff0000, v54
	v_mul_f32_e32 v10, v14, v10
	v_mul_f32_e32 v11, v15, v11
	v_cvt_pk_bf16_f32 v10, v10, v11
	v_lshlrev_b32_e32 v11, 16, v55
	v_and_b32_e32 v14, 0xffff0000, v55
	v_mul_f32_e32 v11, v16, v11
	v_mul_f32_e32 v14, v17, v14
	v_cvt_pk_bf16_f32 v11, v11, v14
	v_lshlrev_b32_e32 v14, 16, v56
	v_mul_f32_e32 v12, v12, v14
	v_and_b32_e32 v14, 0xffff0000, v56
	v_mul_f32_e32 v13, v13, v14
	v_cvt_pk_bf16_f32 v12, v12, v13
	v_lshlrev_b32_e32 v13, 16, v57
	v_and_b32_e32 v14, 0xffff0000, v57
	v_lshlrev_b64 v[18:19], 11, v[66:67]
	v_mul_f32_e32 v13, v20, v13
	v_mul_f32_e32 v14, v21, v14
	v_cvt_pk_bf16_f32 v13, v13, v14
	v_lshl_add_u64 v[14:15], s[74:75], 0, v[18:19]
	v_lshl_add_u64 v[14:15], v[14:15], 0, v[194:195]
	global_store_dwordx4 v[14:15], v[10:13], off
	s_nop 1
	v_pk_mul_f32 v[10:11], v[4:5], s[72:73] op_sel_hi:[1,0]
	v_pk_mul_f32 v[4:5], v[2:3], s[72:73] op_sel_hi:[1,0]
	v_lshlrev_b32_e32 v2, 16, v50
	v_and_b32_e32 v3, 0xffff0000, v50
	v_mul_f32_e32 v2, v6, v2
	v_mul_f32_e32 v3, v7, v3
	v_cvt_pk_bf16_f32 v2, v2, v3
	v_lshlrev_b32_e32 v3, 16, v51
	v_and_b32_e32 v6, 0xffff0000, v51
	v_mul_f32_e32 v3, v8, v3
	v_mul_f32_e32 v6, v9, v6
	v_cvt_pk_bf16_f32 v3, v3, v6
	v_lshlrev_b32_e32 v6, 16, v52
	v_mul_f32_e32 v4, v4, v6
	v_and_b32_e32 v6, 0xffff0000, v52
	v_mul_f32_e32 v5, v5, v6
	v_cvt_pk_bf16_f32 v4, v4, v5
	v_lshlrev_b32_e32 v5, 16, v53
	v_mul_f32_e32 v5, v10, v5
	v_and_b32_e32 v6, 0xffff0000, v53
	v_mul_f32_e32 v6, v11, v6
	v_cvt_pk_bf16_f32 v5, v5, v6
	global_store_dwordx4 v[14:15], v[2:5], off offset:256
	s_and_b64 vcc, exec, s[62:63]
	s_mov_b32 s29, s71
	s_mov_b32 s28, s0
	s_mov_b64 s[8:9], s[60:61]
	s_mov_b64 s[6:7], s[52:53]
	s_cbranch_vccz .LBB0_252
	s_waitcnt vmcnt(0)
	v_readlane_b32 s28, v250, 12
	s_cmpk_gt_u32 s4, 0xff
	v_readlane_b32 s29, v250, 13
	s_mov_b32 s70, 0x800000
	s_cbranch_scc1 .LBB0_259
	s_barrier

.LBB0_266:
	s_add_u32 s8, s6, 0x100
	s_addc_u32 s9, s7, 0
	v_or_b32_e32 v142, 0x10000, v147
	v_add_u32_e32 v150, 0x10400, v147
	v_add_u32_e32 v154, 0x10800, v147
	v_add_u32_e32 v158, 0x10c00, v147
	s_add_u32 s10, s71, s6
	ds_read_b128 v[142:145], v142
	ds_read_b128 v[150:153], v150
	ds_read_b128 v[154:157], v154
	ds_read_b128 v[158:161], v158
	s_addc_u32 s11, s78, s7
	s_cmp_eq_u32 s79, 4
	s_cselect_b32 s81, 0, s8
	s_cselect_b32 s80, 0, s9
	s_cselect_b32 s54, s29, s10
	s_cselect_b32 s55, s5, s11
	s_add_u32 s10, s18, s81
	s_addc_u32 s11, s19, s80
	v_lshl_add_u64 v[206:207], v[138:139], 0, s[6:7]
	s_add_i32 m0, s17, 0xc000
	ds_read_b128 v[162:165], v146
	ds_read_b128 v[166:169], v146 offset:1024
	ds_read_b128 v[170:173], v146 offset:2048
	ds_read_b128 v[174:177], v146 offset:3072
	ds_read_b128 v[178:181], v146 offset:4096
	ds_read_b128 v[182:185], v146 offset:5120
	ds_read_b128 v[186:189], v146 offset:6144
	ds_read_b128 v[190:193], v146 offset:7168
	global_load_lds_dwordx4 v[206:207], off
	v_lshl_add_u64 v[206:207], v[140:141], 0, s[6:7]
	s_add_i32 m0, s17, 0xe000
	s_nop 0
	global_load_lds_dwordx4 v[206:207], off
	s_waitcnt lgkmcnt(8)
	s_barrier
	s_waitcnt lgkmcnt(0)
	s_setprio 1
	v_mfma_f32_16x16x32_bf16 v[126:129], v[142:145], v[162:165], v[126:129]
	v_mfma_f32_16x16x32_bf16 v[122:125], v[154:157], v[162:165], v[122:125]
	v_mfma_f32_16x16x32_bf16 v[110:113], v[142:145], v[170:173], v[110:113]
	v_mfma_f32_16x16x32_bf16 v[106:109], v[154:157], v[170:173], v[106:109]
	v_mfma_f32_16x16x32_bf16 v[94:97], v[142:145], v[178:181], v[94:97]
	v_mfma_f32_16x16x32_bf16 v[90:93], v[154:157], v[178:181], v[90:93]
	v_mfma_f32_16x16x32_bf16 v[78:81], v[142:145], v[186:189], v[78:81]
	v_mfma_f32_16x16x32_bf16 v[74:77], v[154:157], v[186:189], v[74:77]
	v_mfma_f32_16x16x32_bf16 v[126:129], v[150:153], v[166:169], v[126:129]
	v_mfma_f32_16x16x32_bf16 v[122:125], v[158:161], v[166:169], v[122:125]
	v_mfma_f32_16x16x32_bf16 v[110:113], v[150:153], v[174:177], v[110:113]
	v_mfma_f32_16x16x32_bf16 v[106:109], v[158:161], v[174:177], v[106:109]
	v_mfma_f32_16x16x32_bf16 v[94:97], v[150:153], v[182:185], v[94:97]
	v_mfma_f32_16x16x32_bf16 v[90:93], v[158:161], v[182:185], v[90:93]
	v_mfma_f32_16x16x32_bf16 v[78:81], v[150:153], v[190:193], v[78:81]
	v_mfma_f32_16x16x32_bf16 v[74:77], v[158:161], v[190:193], v[74:77]
	s_setprio 0
	s_barrier
	v_or_b32_e32 v194, 0x14000, v147
	s_mov_b32 m0, s26
	v_add_u32_e32 v197, 0x14400, v147
	ds_read_b128 v[206:209], v194
	ds_read_b128 v[210:213], v197
	v_add_u32_e32 v194, 0x14800, v147
	v_lshl_add_u64 v[222:223], s[54:55], 0, v[134:135]
	v_add_u32_e32 v197, 0x14c00, v147
	ds_read_b128 v[214:217], v194
	ds_read_b128 v[218:221], v197
	global_load_lds_dwordx4 v[222:223], off
	v_lshl_add_u64 v[224:225], s[54:55], 0, v[130:131]
	s_mov_b32 m0, s34
	s_nop 0
	global_load_lds_dwordx4 v[224:225], off
	s_barrier
	s_waitcnt lgkmcnt(0)
	s_setprio 1
	v_mfma_f32_16x16x32_bf16 v[118:121], v[206:209], v[162:165], v[118:121]
	v_mfma_f32_16x16x32_bf16 v[114:117], v[214:217], v[162:165], v[114:117]
	v_mfma_f32_16x16x32_bf16 v[102:105], v[206:209], v[170:173], v[102:105]
	v_mfma_f32_16x16x32_bf16 v[98:101], v[214:217], v[170:173], v[98:101]
	v_mfma_f32_16x16x32_bf16 v[86:89], v[206:209], v[178:181], v[86:89]
	v_mfma_f32_16x16x32_bf16 v[82:85], v[214:217], v[178:181], v[82:85]
	v_mfma_f32_16x16x32_bf16 v[70:73], v[206:209], v[186:189], v[70:73]
	v_mfma_f32_16x16x32_bf16 v[66:69], v[214:217], v[186:189], v[66:69]
	v_mfma_f32_16x16x32_bf16 v[118:121], v[210:213], v[166:169], v[118:121]
	v_mfma_f32_16x16x32_bf16 v[114:117], v[218:221], v[166:169], v[114:117]
	v_mfma_f32_16x16x32_bf16 v[102:105], v[210:213], v[174:177], v[102:105]
	v_mfma_f32_16x16x32_bf16 v[98:101], v[218:221], v[174:177], v[98:101]
	v_mfma_f32_16x16x32_bf16 v[86:89], v[210:213], v[182:185], v[86:89]
	v_mfma_f32_16x16x32_bf16 v[82:85], v[218:221], v[182:185], v[82:85]
	s_mov_b32 m0, s17
	v_mfma_f32_16x16x32_bf16 v[70:73], v[210:213], v[190:193], v[70:73]
	v_lshl_add_u64 v[226:227], s[10:11], 0, v[136:137]
	v_mfma_f32_16x16x32_bf16 v[66:69], v[218:221], v[190:193], v[66:69]
	s_setprio 0
	s_barrier
	ds_read_b128 v[162:165], v146 offset:16384
	ds_read_b128 v[166:169], v146 offset:17408
	ds_read_b128 v[170:173], v146 offset:18432
	ds_read_b128 v[174:177], v146 offset:19456
	ds_read_b128 v[178:181], v146 offset:20480
	ds_read_b128 v[182:185], v146 offset:21504
	ds_read_b128 v[186:189], v146 offset:22528
	ds_read_b128 v[190:193], v146 offset:23552
	global_load_lds_dwordx4 v[226:227], off
	v_lshl_add_u64 v[228:229], s[10:11], 0, v[132:133]
	s_mov_b32 m0, s35
	s_nop 0
	global_load_lds_dwordx4 v[228:229], off
	s_barrier
	s_waitcnt lgkmcnt(0)
	s_setprio 1
	v_mfma_f32_16x16x32_bf16 v[62:65], v[142:145], v[162:165], v[62:65]
	v_mfma_f32_16x16x32_bf16 v[58:61], v[154:157], v[162:165], v[58:61]
	v_mfma_f32_16x16x32_bf16 v[46:49], v[142:145], v[170:173], v[46:49]
	v_mfma_f32_16x16x32_bf16 v[42:45], v[154:157], v[170:173], v[42:45]
	v_mfma_f32_16x16x32_bf16 v[30:33], v[142:145], v[178:181], v[30:33]
	v_mfma_f32_16x16x32_bf16 v[26:29], v[154:157], v[178:181], v[26:29]
	v_mfma_f32_16x16x32_bf16 v[14:17], v[142:145], v[186:189], v[14:17]
	v_mfma_f32_16x16x32_bf16 v[10:13], v[154:157], v[186:189], v[10:13]
	v_mfma_f32_16x16x32_bf16 v[62:65], v[150:153], v[166:169], v[62:65]
	v_mfma_f32_16x16x32_bf16 v[58:61], v[158:161], v[166:169], v[58:61]
	v_mfma_f32_16x16x32_bf16 v[46:49], v[150:153], v[174:177], v[46:49]
	v_mfma_f32_16x16x32_bf16 v[42:45], v[158:161], v[174:177], v[42:45]
	v_mfma_f32_16x16x32_bf16 v[30:33], v[150:153], v[182:185], v[30:33]
	v_mfma_f32_16x16x32_bf16 v[26:29], v[158:161], v[182:185], v[26:29]
	v_mfma_f32_16x16x32_bf16 v[14:17], v[150:153], v[190:193], v[14:17]
	v_mfma_f32_16x16x32_bf16 v[10:13], v[158:161], v[190:193], v[10:13]
	s_setprio 0
	s_barrier
	s_add_u32 s6, s54, 0x20000
	s_addc_u32 s7, s55, 0
	s_mov_b32 m0, s42
	v_lshl_add_u64 v[142:143], s[6:7], 0, v[134:135]
	global_load_lds_dwordx4 v[142:143], off
	v_lshl_add_u64 v[142:143], s[6:7], 0, v[130:131]
	s_mov_b32 m0, s56
	s_nop 0
	global_load_lds_dwordx4 v[142:143], off
	s_waitcnt vmcnt(6)
	s_barrier
	s_setprio 1
	v_mfma_f32_16x16x32_bf16 v[54:57], v[206:209], v[162:165], v[54:57]
	v_mfma_f32_16x16x32_bf16 v[50:53], v[214:217], v[162:165], v[50:53]
	v_mfma_f32_16x16x32_bf16 v[38:41], v[206:209], v[170:173], v[38:41]
	v_mfma_f32_16x16x32_bf16 v[34:37], v[214:217], v[170:173], v[34:37]
	v_mfma_f32_16x16x32_bf16 v[22:25], v[206:209], v[178:181], v[22:25]
	v_mfma_f32_16x16x32_bf16 v[18:21], v[214:217], v[178:181], v[18:21]
	v_mfma_f32_16x16x32_bf16 v[6:9], v[206:209], v[186:189], v[6:9]
	v_mfma_f32_16x16x32_bf16 v[2:5], v[214:217], v[186:189], v[2:5]
	v_mfma_f32_16x16x32_bf16 v[54:57], v[210:213], v[166:169], v[54:57]
	v_mfma_f32_16x16x32_bf16 v[50:53], v[218:221], v[166:169], v[50:53]
	v_mfma_f32_16x16x32_bf16 v[38:41], v[210:213], v[174:177], v[38:41]
	v_mfma_f32_16x16x32_bf16 v[34:37], v[218:221], v[174:177], v[34:37]
	v_or_b32_e32 v142, 0x18000, v147
	v_mfma_f32_16x16x32_bf16 v[22:25], v[210:213], v[182:185], v[22:25]
	v_add_u32_e32 v150, 0x18400, v147
	v_mfma_f32_16x16x32_bf16 v[18:21], v[218:221], v[182:185], v[18:21]
	v_add_u32_e32 v154, 0x18800, v147
	v_mfma_f32_16x16x32_bf16 v[6:9], v[210:213], v[190:193], v[6:9]
	v_add_u32_e32 v158, 0x18c00, v147
	v_mfma_f32_16x16x32_bf16 v[2:5], v[218:221], v[190:193], v[2:5]
	s_setprio 0
	s_barrier
	ds_read_b128 v[142:145], v142
	ds_read_b128 v[150:153], v150
	ds_read_b128 v[154:157], v154
	ds_read_b128 v[158:161], v158
	s_add_u32 s6, s10, 0x20000
	s_addc_u32 s7, s11, 0
	s_mov_b32 m0, s57
	v_lshl_add_u64 v[206:207], s[6:7], 0, v[136:137]
	ds_read_b128 v[162:165], v146 offset:32768
	ds_read_b128 v[166:169], v146 offset:33792
	ds_read_b128 v[170:173], v146 offset:34816
	ds_read_b128 v[174:177], v146 offset:35840
	ds_read_b128 v[178:181], v146 offset:36864
	ds_read_b128 v[182:185], v146 offset:37888
	ds_read_b128 v[186:189], v146 offset:38912
	ds_read_b128 v[190:193], v146 offset:39936
	global_load_lds_dwordx4 v[206:207], off
	v_lshl_add_u64 v[206:207], s[6:7], 0, v[132:133]
	s_mov_b32 m0, s58
	s_nop 0
	global_load_lds_dwordx4 v[206:207], off
	s_waitcnt lgkmcnt(8)
	s_barrier
	s_waitcnt lgkmcnt(0)
	s_setprio 1
	v_mfma_f32_16x16x32_bf16 v[126:129], v[142:145], v[162:165], v[126:129]
	v_mfma_f32_16x16x32_bf16 v[122:125], v[154:157], v[162:165], v[122:125]
	v_mfma_f32_16x16x32_bf16 v[110:113], v[142:145], v[170:173], v[110:113]
	v_mfma_f32_16x16x32_bf16 v[106:109], v[154:157], v[170:173], v[106:109]
	v_mfma_f32_16x16x32_bf16 v[94:97], v[142:145], v[178:181], v[94:97]
	v_mfma_f32_16x16x32_bf16 v[90:93], v[154:157], v[178:181], v[90:93]
	v_mfma_f32_16x16x32_bf16 v[78:81], v[142:145], v[186:189], v[78:81]
	v_mfma_f32_16x16x32_bf16 v[74:77], v[154:157], v[186:189], v[74:77]
	v_mfma_f32_16x16x32_bf16 v[126:129], v[150:153], v[166:169], v[126:129]
	v_mfma_f32_16x16x32_bf16 v[122:125], v[158:161], v[166:169], v[122:125]
	v_mfma_f32_16x16x32_bf16 v[110:113], v[150:153], v[174:177], v[110:113]
	v_mfma_f32_16x16x32_bf16 v[106:109], v[158:161], v[174:177], v[106:109]
	v_mfma_f32_16x16x32_bf16 v[94:97], v[150:153], v[182:185], v[94:97]
	v_mfma_f32_16x16x32_bf16 v[90:93], v[158:161], v[182:185], v[90:93]
	v_mfma_f32_16x16x32_bf16 v[78:81], v[150:153], v[190:193], v[78:81]
	v_mfma_f32_16x16x32_bf16 v[74:77], v[158:161], v[190:193], v[74:77]
	s_setprio 0
	s_barrier
	v_or_b32_e32 v194, 0x1c000, v147
	s_mov_b32 m0, s59
	v_add_u32_e32 v197, 0x1c400, v147
	ds_read_b128 v[206:209], v194
	ds_read_b128 v[210:213], v197
	v_add_u32_e32 v194, 0x1c800, v147
	v_lshl_add_u64 v[222:223], v[222:223], 0, s[76:77]
	v_add_u32_e32 v197, 0x1cc00, v147
	ds_read_b128 v[214:217], v194
	ds_read_b128 v[218:221], v197
	global_load_lds_dwordx4 v[222:223], off
	v_lshl_add_u64 v[222:223], v[224:225], 0, s[76:77]
	s_mov_b32 m0, s60
	s_nop 0
	global_load_lds_dwordx4 v[222:223], off
	s_barrier
	s_waitcnt lgkmcnt(0)
	s_setprio 1
	v_mfma_f32_16x16x32_bf16 v[118:121], v[206:209], v[162:165], v[118:121]
	v_mfma_f32_16x16x32_bf16 v[114:117], v[214:217], v[162:165], v[114:117]
	v_mfma_f32_16x16x32_bf16 v[102:105], v[206:209], v[170:173], v[102:105]
	v_mfma_f32_16x16x32_bf16 v[98:101], v[214:217], v[170:173], v[98:101]
	v_mfma_f32_16x16x32_bf16 v[86:89], v[206:209], v[178:181], v[86:89]
	v_mfma_f32_16x16x32_bf16 v[82:85], v[214:217], v[178:181], v[82:85]
	v_mfma_f32_16x16x32_bf16 v[70:73], v[206:209], v[186:189], v[70:73]
	v_mfma_f32_16x16x32_bf16 v[66:69], v[214:217], v[186:189], v[66:69]
	v_mfma_f32_16x16x32_bf16 v[118:121], v[210:213], v[166:169], v[118:121]
	v_mfma_f32_16x16x32_bf16 v[114:117], v[218:221], v[166:169], v[114:117]
	v_mfma_f32_16x16x32_bf16 v[102:105], v[210:213], v[174:177], v[102:105]
	v_mfma_f32_16x16x32_bf16 v[98:101], v[218:221], v[174:177], v[98:101]
	v_mfma_f32_16x16x32_bf16 v[86:89], v[210:213], v[182:185], v[86:89]
	v_mfma_f32_16x16x32_bf16 v[82:85], v[218:221], v[182:185], v[82:85]
	s_mov_b32 m0, s61
	v_mfma_f32_16x16x32_bf16 v[70:73], v[210:213], v[190:193], v[70:73]
	v_lshl_add_u64 v[222:223], v[226:227], 0, s[76:77]
	v_mfma_f32_16x16x32_bf16 v[66:69], v[218:221], v[190:193], v[66:69]
	s_setprio 0
	s_barrier
	ds_read_b128 v[162:165], v146 offset:49152
	ds_read_b128 v[166:169], v146 offset:50176
	ds_read_b128 v[170:173], v146 offset:51200
	ds_read_b128 v[174:177], v146 offset:52224
	ds_read_b128 v[178:181], v146 offset:53248
	ds_read_b128 v[182:185], v146 offset:54272
	ds_read_b128 v[186:189], v146 offset:55296
	ds_read_b128 v[190:193], v146 offset:56320
	global_load_lds_dwordx4 v[222:223], off
	v_lshl_add_u64 v[222:223], v[228:229], 0, s[76:77]
	s_mov_b32 m0, s62
	s_nop 0
	global_load_lds_dwordx4 v[222:223], off
	s_barrier
	s_waitcnt lgkmcnt(0)
	s_setprio 1
	v_mfma_f32_16x16x32_bf16 v[62:65], v[142:145], v[162:165], v[62:65]
	v_mfma_f32_16x16x32_bf16 v[58:61], v[154:157], v[162:165], v[58:61]
	v_mfma_f32_16x16x32_bf16 v[46:49], v[142:145], v[170:173], v[46:49]
	v_mfma_f32_16x16x32_bf16 v[42:45], v[154:157], v[170:173], v[42:45]
	v_mfma_f32_16x16x32_bf16 v[30:33], v[142:145], v[178:181], v[30:33]
	v_mfma_f32_16x16x32_bf16 v[26:29], v[154:157], v[178:181], v[26:29]
	v_mfma_f32_16x16x32_bf16 v[14:17], v[142:145], v[186:189], v[14:17]
	v_mfma_f32_16x16x32_bf16 v[10:13], v[154:157], v[186:189], v[10:13]
	v_mfma_f32_16x16x32_bf16 v[62:65], v[150:153], v[166:169], v[62:65]
	v_mfma_f32_16x16x32_bf16 v[58:61], v[158:161], v[166:169], v[58:61]
	v_mfma_f32_16x16x32_bf16 v[46:49], v[150:153], v[174:177], v[46:49]
	v_mfma_f32_16x16x32_bf16 v[42:45], v[158:161], v[174:177], v[42:45]
	v_mfma_f32_16x16x32_bf16 v[30:33], v[150:153], v[182:185], v[30:33]
	v_mfma_f32_16x16x32_bf16 v[26:29], v[158:161], v[182:185], v[26:29]
	v_mfma_f32_16x16x32_bf16 v[14:17], v[150:153], v[190:193], v[14:17]
	v_mfma_f32_16x16x32_bf16 v[10:13], v[158:161], v[190:193], v[10:13]
	s_setprio 0
	s_barrier
	s_add_u32 s6, s54, 0x20080
	s_addc_u32 s7, s55, 0
	s_mov_b32 m0, s63
	v_lshl_add_u64 v[142:143], s[6:7], 0, v[134:135]
	global_load_lds_dwordx4 v[142:143], off
	v_lshl_add_u64 v[142:143], s[6:7], 0, v[130:131]
	s_mov_b32 m0, s67
	s_nop 0
	global_load_lds_dwordx4 v[142:143], off
	s_waitcnt vmcnt(6)
	s_barrier
	s_setprio 1
	v_mfma_f32_16x16x32_bf16 v[54:57], v[206:209], v[162:165], v[54:57]
	v_mfma_f32_16x16x32_bf16 v[50:53], v[214:217], v[162:165], v[50:53]
	v_mfma_f32_16x16x32_bf16 v[38:41], v[206:209], v[170:173], v[38:41]
	v_mfma_f32_16x16x32_bf16 v[34:37], v[214:217], v[170:173], v[34:37]
	v_mfma_f32_16x16x32_bf16 v[22:25], v[206:209], v[178:181], v[22:25]
	v_mfma_f32_16x16x32_bf16 v[18:21], v[214:217], v[178:181], v[18:21]
	v_mfma_f32_16x16x32_bf16 v[6:9], v[206:209], v[186:189], v[6:9]
	v_mfma_f32_16x16x32_bf16 v[2:5], v[214:217], v[186:189], v[2:5]
	v_mfma_f32_16x16x32_bf16 v[54:57], v[210:213], v[166:169], v[54:57]
	v_mfma_f32_16x16x32_bf16 v[50:53], v[218:221], v[166:169], v[50:53]
	v_mfma_f32_16x16x32_bf16 v[38:41], v[210:213], v[174:177], v[38:41]
	v_mfma_f32_16x16x32_bf16 v[34:37], v[218:221], v[174:177], v[34:37]
	v_mfma_f32_16x16x32_bf16 v[22:25], v[210:213], v[182:185], v[22:25]
	v_mfma_f32_16x16x32_bf16 v[18:21], v[218:221], v[182:185], v[18:21]
	v_mfma_f32_16x16x32_bf16 v[6:9], v[210:213], v[190:193], v[6:9]
	v_mfma_f32_16x16x32_bf16 v[2:5], v[218:221], v[190:193], v[2:5]
	s_setprio 0
	s_add_i32 s79, s79, 2
	s_cmp_gt_u32 s79, 5
	s_mov_b64 s[6:7], s[8:9]
	s_barrier
	s_cbranch_scc0 .LBB0_266
	s_lshl_b32 s5, s28, 6
	s_and_b32 s5, s5, 0xffffff00
	v_add_u32_e32 v144, s5, v148
	s_lshl_b32 s5, s28, 8
	s_and_b32 s5, s5, 0x300
	v_or_b32_e32 v145, s5, v149
	v_mov_b64_e32 v[142:143], s[50:51]
	v_mad_i64_i32 v[150:151], s[6:7], v144, s37, v[142:143]
	v_lshlrev_b32_e32 v194, 1, v145
	v_lshl_add_u64 v[154:155], v[150:151], 0, v[194:195]
	v_add_co_u32_e32 v150, vcc, 0x1000, v154
	v_or_b32_e32 v184, 16, v144
	s_nop 0
	v_addc_co_u32_e32 v151, vcc, 0, v155, vcc
	global_load_dwordx4 v[150:153], v[150:151], off offset:2048
	v_lshl_add_u64 v[154:155], v[154:155], 0, s[84:85]
	global_load_dwordx4 v[154:157], v[154:155], off offset:256
	v_pk_mul_f32 v[182:183], v[114:115], s[36:37] op_sel_hi:[1,0]
	v_mad_i64_i32 v[114:115], s[6:7], v184, s37, v[142:143]
	v_lshl_add_u64 v[114:115], v[114:115], 0, v[194:195]
	v_pk_mul_f32 v[180:181], v[116:117], s[36:37] op_sel_hi:[1,0]
	v_add_co_u32_e32 v116, vcc, 0x1000, v114
	v_pk_mul_f32 v[170:171], v[126:127], s[36:37] op_sel_hi:[1,0]
	s_nop 0
	v_addc_co_u32_e32 v117, vcc, 0, v115, vcc
	v_pk_mul_f32 v[172:173], v[124:125], s[36:37] op_sel_hi:[1,0]
	global_load_dwordx4 v[124:127], v[116:117], off offset:2048
	v_lshl_add_u64 v[114:115], v[114:115], 0, s[84:85]
	global_load_dwordx4 v[158:161], v[114:115], off offset:256
	v_or_b32_e32 v186, 32, v144
	v_mad_i64_i32 v[116:117], s[6:7], v186, s37, v[142:143]
	v_lshl_add_u64 v[116:117], v[116:117], 0, v[194:195]
	v_lshl_add_u64 v[166:167], v[116:117], 0, s[84:85]
	v_add_co_u32_e32 v116, vcc, 0x1000, v116
	v_pk_mul_f32 v[174:175], v[122:123], s[36:37] op_sel_hi:[1,0]
	s_nop 0
	v_addc_co_u32_e32 v117, vcc, 0, v117, vcc
	global_load_dwordx4 v[162:165], v[116:117], off offset:2048
	s_nop 0
	global_load_dwordx4 v[166:169], v[166:167], off offset:256
	v_or_b32_e32 v122, 48, v144
	v_pk_mul_f32 v[178:179], v[118:119], s[36:37] op_sel_hi:[1,0]
	v_mad_i64_i32 v[118:119], s[6:7], v122, s37, v[142:143]
	v_ashrrev_i32_e32 v145, 31, v144
	v_lshl_add_u64 v[118:119], v[118:119], 0, v[194:195]
	v_pk_mul_f32 v[176:177], v[120:121], s[36:37] op_sel_hi:[1,0]
	v_lshlrev_b64 v[120:121], 11, v[144:145]
	v_add_co_u32_e32 v114, vcc, 0x1000, v118
	v_lshl_add_u64 v[120:121], s[74:75], 0, v[120:121]
	s_nop 0
	v_addc_co_u32_e32 v115, vcc, 0, v119, vcc
	v_lshl_add_u64 v[188:189], v[118:119], 0, s[84:85]
	v_lshl_add_u64 v[190:191], v[120:121], 0, v[194:195]
	global_load_dwordx4 v[118:121], v[114:115], off offset:2048
	s_nop 0
	global_load_dwordx4 v[114:117], v[188:189], off offset:256
	v_pk_mul_f32 v[128:129], v[128:129], s[36:37] op_sel_hi:[1,0]
	v_pk_mul_f32 v[110:111], v[110:111], s[36:37] op_sel_hi:[1,0]
	v_pk_mul_f32 v[112:113], v[112:113], s[36:37] op_sel_hi:[1,0]
	v_ashrrev_i32_e32 v185, 31, v184
	v_pk_mul_f32 v[102:103], v[102:103], s[36:37] op_sel_hi:[1,0]
	v_pk_mul_f32 v[104:105], v[104:105], s[36:37] op_sel_hi:[1,0]
	v_pk_mul_f32 v[94:95], v[94:95], s[36:37] op_sel_hi:[1,0]
	v_pk_mul_f32 v[96:97], v[96:97], s[36:37] op_sel_hi:[1,0]
	v_ashrrev_i32_e32 v187, 31, v186
	v_pk_mul_f32 v[86:87], v[86:87], s[36:37] op_sel_hi:[1,0]
	v_pk_mul_f32 v[88:89], v[88:89], s[36:37] op_sel_hi:[1,0]
	v_pk_mul_f32 v[78:79], v[78:79], s[36:37] op_sel_hi:[1,0]
	v_pk_mul_f32 v[80:81], v[80:81], s[36:37] op_sel_hi:[1,0]
	v_ashrrev_i32_e32 v123, 31, v122
	v_pk_mul_f32 v[70:71], v[70:71], s[36:37] op_sel_hi:[1,0]
	v_pk_mul_f32 v[72:73], v[72:73], s[36:37] op_sel_hi:[1,0]
	s_waitcnt vmcnt(0)
	v_lshlrev_b32_e32 v145, 16, v150
	v_and_b32_e32 v150, 0xffff0000, v150
	v_lshlrev_b32_e32 v188, 16, v151
	v_and_b32_e32 v151, 0xffff0000, v151
	v_mul_f32_e32 v150, v171, v150
	v_mul_f32_e32 v128, v128, v188
	v_mul_f32_e32 v129, v129, v151
	v_lshlrev_b32_e32 v189, 16, v152
	v_and_b32_e32 v152, 0xffff0000, v152
	v_lshlrev_b32_e32 v192, 16, v153
	v_and_b32_e32 v153, 0xffff0000, v153
	v_mul_f32_e32 v145, v170, v145
	v_cvt_pk_bf16_f32 v150, v145, v150
	v_cvt_pk_bf16_f32 v151, v128, v129
	v_lshlrev_b32_e32 v128, 16, v154
	v_and_b32_e32 v129, 0xffff0000, v154
	v_mul_f32_e32 v152, v175, v152
	v_mul_f32_e32 v153, v173, v153
	v_mul_f32_e32 v128, v178, v128
	v_mul_f32_e32 v129, v179, v129
	v_mul_f32_e32 v170, v174, v189
	v_mul_f32_e32 v171, v172, v192
	v_cvt_pk_bf16_f32 v152, v170, v152
	v_cvt_pk_bf16_f32 v153, v171, v153
	global_store_dwordx4 v[190:191], v[150:153], off
	s_nop 1
	v_cvt_pk_bf16_f32 v150, v128, v129
	v_lshlrev_b32_e32 v128, 16, v155
	v_and_b32_e32 v129, 0xffff0000, v155
	v_mul_f32_e32 v128, v176, v128
	v_mul_f32_e32 v129, v177, v129
	v_cvt_pk_bf16_f32 v151, v128, v129
	v_lshlrev_b32_e32 v128, 16, v156
	v_and_b32_e32 v129, 0xffff0000, v156
	v_mul_f32_e32 v128, v182, v128
	v_mul_f32_e32 v129, v183, v129
	v_cvt_pk_bf16_f32 v152, v128, v129
	v_lshlrev_b32_e32 v128, 16, v157
	v_and_b32_e32 v129, 0xffff0000, v157
	v_mul_f32_e32 v128, v180, v128
	v_mul_f32_e32 v129, v181, v129
	v_cvt_pk_bf16_f32 v153, v128, v129
	global_store_dwordx4 v[190:191], v[150:153], off offset:256
	v_lshlrev_b64 v[128:129], 11, v[184:185]
	s_nop 0
	v_pk_mul_f32 v[150:151], v[108:109], s[36:37] op_sel_hi:[1,0]
	v_pk_mul_f32 v[108:109], v[106:107], s[36:37] op_sel_hi:[1,0]
	v_lshlrev_b32_e32 v106, 16, v124
	v_and_b32_e32 v107, 0xffff0000, v124
	v_mul_f32_e32 v106, v110, v106
	v_mul_f32_e32 v107, v111, v107
	v_cvt_pk_bf16_f32 v106, v106, v107
	v_lshlrev_b32_e32 v107, 16, v125
	v_and_b32_e32 v110, 0xffff0000, v125
	v_mul_f32_e32 v107, v112, v107
	v_mul_f32_e32 v110, v113, v110
	v_cvt_pk_bf16_f32 v107, v107, v110
	v_lshlrev_b32_e32 v110, 16, v126
	v_mul_f32_e32 v108, v108, v110
	v_and_b32_e32 v110, 0xffff0000, v126
	v_mul_f32_e32 v109, v109, v110
	v_cvt_pk_bf16_f32 v108, v108, v109
	v_lshlrev_b32_e32 v109, 16, v127
	v_and_b32_e32 v110, 0xffff0000, v127
	v_mul_f32_e32 v109, v150, v109
	v_mul_f32_e32 v110, v151, v110
	v_cvt_pk_bf16_f32 v109, v109, v110
	v_lshl_add_u64 v[110:111], s[74:75], 0, v[128:129]
	v_lshl_add_u64 v[110:111], v[110:111], 0, v[194:195]
	global_store_dwordx4 v[110:111], v[106:109], off
	s_nop 1
	v_pk_mul_f32 v[106:107], v[100:101], s[36:37] op_sel_hi:[1,0]
	v_pk_mul_f32 v[100:101], v[98:99], s[36:37] op_sel_hi:[1,0]
	v_lshlrev_b32_e32 v98, 16, v158
	v_and_b32_e32 v99, 0xffff0000, v158
	v_mul_f32_e32 v98, v102, v98
	v_mul_f32_e32 v99, v103, v99
	v_cvt_pk_bf16_f32 v98, v98, v99
	v_lshlrev_b32_e32 v99, 16, v159
	v_and_b32_e32 v102, 0xffff0000, v159
	v_mul_f32_e32 v99, v104, v99
	v_mul_f32_e32 v102, v105, v102
	v_cvt_pk_bf16_f32 v99, v99, v102
	v_lshlrev_b32_e32 v102, 16, v160
	v_mul_f32_e32 v100, v100, v102
	v_and_b32_e32 v102, 0xffff0000, v160
	v_mul_f32_e32 v101, v101, v102
	v_cvt_pk_bf16_f32 v100, v100, v101
	v_lshlrev_b32_e32 v101, 16, v161
	v_mul_f32_e32 v101, v106, v101
	v_and_b32_e32 v102, 0xffff0000, v161
	v_mul_f32_e32 v102, v107, v102
	v_cvt_pk_bf16_f32 v101, v101, v102
	global_store_dwordx4 v[110:111], v[98:101], off offset:256
	s_nop 1
	v_pk_mul_f32 v[100:101], v[92:93], s[36:37] op_sel_hi:[1,0]
	v_pk_mul_f32 v[92:93], v[90:91], s[36:37] op_sel_hi:[1,0]
	v_lshlrev_b32_e32 v90, 16, v162
	v_and_b32_e32 v91, 0xffff0000, v162
	v_mul_f32_e32 v90, v94, v90
	v_mul_f32_e32 v91, v95, v91
	v_cvt_pk_bf16_f32 v90, v90, v91
	v_lshlrev_b32_e32 v91, 16, v163
	v_and_b32_e32 v94, 0xffff0000, v163
	v_mul_f32_e32 v91, v96, v91
	v_mul_f32_e32 v94, v97, v94
	v_cvt_pk_bf16_f32 v91, v91, v94
	v_lshlrev_b32_e32 v94, 16, v164
	v_mul_f32_e32 v92, v92, v94
	v_and_b32_e32 v94, 0xffff0000, v164
	v_mul_f32_e32 v93, v93, v94
	v_cvt_pk_bf16_f32 v92, v92, v93
	v_lshlrev_b32_e32 v93, 16, v165
	v_and_b32_e32 v94, 0xffff0000, v165
	v_lshlrev_b64 v[98:99], 11, v[186:187]
	v_mul_f32_e32 v93, v100, v93
	v_mul_f32_e32 v94, v101, v94
	v_cvt_pk_bf16_f32 v93, v93, v94
	v_lshl_add_u64 v[94:95], s[74:75], 0, v[98:99]
	v_lshl_add_u64 v[94:95], v[94:95], 0, v[194:195]
	global_store_dwordx4 v[94:95], v[90:93], off
	s_nop 1
	v_pk_mul_f32 v[90:91], v[84:85], s[36:37] op_sel_hi:[1,0]
	v_pk_mul_f32 v[84:85], v[82:83], s[36:37] op_sel_hi:[1,0]
	v_lshlrev_b32_e32 v82, 16, v166
	v_and_b32_e32 v83, 0xffff0000, v166
	v_mul_f32_e32 v82, v86, v82
	v_mul_f32_e32 v83, v87, v83
	v_cvt_pk_bf16_f32 v82, v82, v83
	v_lshlrev_b32_e32 v83, 16, v167
	v_and_b32_e32 v86, 0xffff0000, v167
	v_mul_f32_e32 v83, v88, v83
	v_mul_f32_e32 v86, v89, v86
	v_cvt_pk_bf16_f32 v83, v83, v86
	v_lshlrev_b32_e32 v86, 16, v168
	v_mul_f32_e32 v84, v84, v86
	v_and_b32_e32 v86, 0xffff0000, v168
	v_mul_f32_e32 v85, v85, v86
	v_cvt_pk_bf16_f32 v84, v84, v85
	v_lshlrev_b32_e32 v85, 16, v169
	v_mul_f32_e32 v85, v90, v85
	v_and_b32_e32 v86, 0xffff0000, v169
	v_mul_f32_e32 v86, v91, v86
	v_cvt_pk_bf16_f32 v85, v85, v86
	global_store_dwordx4 v[94:95], v[82:85], off offset:256
	s_nop 1
	v_pk_mul_f32 v[84:85], v[76:77], s[36:37] op_sel_hi:[1,0]
	v_pk_mul_f32 v[76:77], v[74:75], s[36:37] op_sel_hi:[1,0]
	v_lshlrev_b32_e32 v74, 16, v118
	v_and_b32_e32 v75, 0xffff0000, v118
	v_mul_f32_e32 v74, v78, v74
	v_mul_f32_e32 v75, v79, v75
	v_cvt_pk_bf16_f32 v74, v74, v75
	v_lshlrev_b32_e32 v75, 16, v119
	v_and_b32_e32 v78, 0xffff0000, v119
	v_mul_f32_e32 v75, v80, v75
	v_mul_f32_e32 v78, v81, v78
	v_cvt_pk_bf16_f32 v75, v75, v78
	v_lshlrev_b32_e32 v78, 16, v120
	v_mul_f32_e32 v76, v76, v78
	v_and_b32_e32 v78, 0xffff0000, v120
	v_mul_f32_e32 v77, v77, v78
	v_cvt_pk_bf16_f32 v76, v76, v77
	v_lshlrev_b32_e32 v77, 16, v121
	v_and_b32_e32 v78, 0xffff0000, v121
	v_lshlrev_b64 v[82:83], 11, v[122:123]
	v_mul_f32_e32 v77, v84, v77
	v_mul_f32_e32 v78, v85, v78
	v_cvt_pk_bf16_f32 v77, v77, v78
	v_lshl_add_u64 v[78:79], s[74:75], 0, v[82:83]
	v_lshl_add_u64 v[78:79], v[78:79], 0, v[194:195]
	global_store_dwordx4 v[78:79], v[74:77], off
	s_nop 1
	v_pk_mul_f32 v[74:75], v[68:69], s[36:37] op_sel_hi:[1,0]
	v_pk_mul_f32 v[68:69], v[66:67], s[36:37] op_sel_hi:[1,0]
	v_lshlrev_b32_e32 v66, 16, v114
	v_and_b32_e32 v67, 0xffff0000, v114
	v_mul_f32_e32 v66, v70, v66
	v_mul_f32_e32 v67, v71, v67
	v_cvt_pk_bf16_f32 v66, v66, v67
	v_lshlrev_b32_e32 v67, 16, v115
	v_and_b32_e32 v70, 0xffff0000, v115
	v_mul_f32_e32 v67, v72, v67
	v_mul_f32_e32 v70, v73, v70
	v_cvt_pk_bf16_f32 v67, v67, v70
	v_lshlrev_b32_e32 v70, 16, v116
	v_mul_f32_e32 v68, v68, v70
	v_and_b32_e32 v70, 0xffff0000, v116
	v_mul_f32_e32 v69, v69, v70
	v_cvt_pk_bf16_f32 v68, v68, v69
	v_lshlrev_b32_e32 v69, 16, v117
	v_mul_f32_e32 v69, v74, v69
	v_and_b32_e32 v70, 0xffff0000, v117
	v_mul_f32_e32 v70, v75, v70
	v_cvt_pk_bf16_f32 v69, v69, v70
	global_store_dwordx4 v[78:79], v[66:69], off offset:256
	v_add_u32_e32 v78, 0x80, v144
	s_nop 0
	v_mad_i64_i32 v[66:67], s[6:7], v78, s37, v[142:143]
	v_lshl_add_u64 v[66:67], v[66:67], 0, v[194:195]
	v_add_co_u32_e32 v68, vcc, s16, v66
	v_add_u32_e32 v86, 0x90, v144
	s_nop 0
	v_addc_co_u32_e32 v69, vcc, 0, v67, vcc
	global_load_dwordx4 v[70:73], v[68:69], off offset:2048
	v_lshl_add_u64 v[66:67], v[66:67], 0, s[84:85]
	global_load_dwordx4 v[74:77], v[66:67], off offset:256
	v_pk_mul_f32 v[96:97], v[56:57], s[36:37] op_sel_hi:[1,0]
	v_mad_i64_i32 v[56:57], s[6:7], v86, s37, v[142:143]
	v_lshl_add_u64 v[56:57], v[56:57], 0, v[194:195]
	v_pk_mul_f32 v[94:95], v[58:59], s[36:37] op_sel_hi:[1,0]
	v_add_co_u32_e32 v58, vcc, s16, v56
	v_pk_mul_f32 v[92:93], v[60:61], s[36:37] op_sel_hi:[1,0]
	s_nop 0
	v_addc_co_u32_e32 v59, vcc, 0, v57, vcc
	global_load_dwordx4 v[58:61], v[58:59], off offset:2048
	v_add_u32_e32 v68, 0xa0, v144
	v_pk_mul_f32 v[102:103], v[50:51], s[36:37] op_sel_hi:[1,0]
	v_mad_i64_i32 v[50:51], s[6:7], v68, s37, v[142:143]
	v_add_u32_e32 v66, 0xb0, v144
	v_lshl_add_u64 v[50:51], v[50:51], 0, v[194:195]
	v_pk_mul_f32 v[100:101], v[52:53], s[36:37] op_sel_hi:[1,0]
	v_mad_i64_i32 v[52:53], s[6:7], v66, s37, v[142:143]
	v_lshl_add_u64 v[82:83], v[50:51], 0, s[84:85]
	v_add_co_u32_e32 v50, vcc, s16, v50
	v_lshl_add_u64 v[52:53], v[52:53], 0, v[194:195]
	s_nop 0
	v_addc_co_u32_e32 v51, vcc, 0, v51, vcc
	v_ashrrev_i32_e32 v79, 31, v78
	v_lshl_add_u64 v[104:105], v[52:53], 0, s[84:85]
	v_add_co_u32_e32 v52, vcc, s16, v52
	v_pk_mul_f32 v[98:99], v[54:55], s[36:37] op_sel_hi:[1,0]
	v_lshlrev_b64 v[54:55], 11, v[78:79]
	v_lshl_add_u64 v[56:57], v[56:57], 0, s[84:85]
	v_addc_co_u32_e32 v53, vcc, 0, v53, vcc
	v_pk_mul_f32 v[88:89], v[64:65], s[36:37] op_sel_hi:[1,0]
	v_pk_mul_f32 v[90:91], v[62:63], s[36:37] op_sel_hi:[1,0]
	v_lshl_add_u64 v[106:107], s[74:75], 0, v[54:55]
	global_load_dwordx4 v[62:65], v[56:57], off offset:256
	global_load_dwordx4 v[78:81], v[50:51], off offset:2048
	s_nop 0
	global_load_dwordx4 v[82:85], v[82:83], off offset:256
	s_nop 0
	global_load_dwordx4 v[54:57], v[52:53], off offset:2048
	s_nop 0
	global_load_dwordx4 v[50:53], v[104:105], off offset:256
	v_lshl_add_u64 v[104:105], v[106:107], 0, v[194:195]
	v_pk_mul_f32 v[46:47], v[46:47], s[36:37] op_sel_hi:[1,0]
	v_pk_mul_f32 v[48:49], v[48:49], s[36:37] op_sel_hi:[1,0]
	v_ashrrev_i32_e32 v87, 31, v86
	v_pk_mul_f32 v[38:39], v[38:39], s[36:37] op_sel_hi:[1,0]
	v_pk_mul_f32 v[40:41], v[40:41], s[36:37] op_sel_hi:[1,0]
	v_pk_mul_f32 v[30:31], v[30:31], s[36:37] op_sel_hi:[1,0]
	v_pk_mul_f32 v[32:33], v[32:33], s[36:37] op_sel_hi:[1,0]
	v_ashrrev_i32_e32 v69, 31, v68
	v_pk_mul_f32 v[22:23], v[22:23], s[36:37] op_sel_hi:[1,0]
	v_pk_mul_f32 v[24:25], v[24:25], s[36:37] op_sel_hi:[1,0]
	v_pk_mul_f32 v[14:15], v[14:15], s[36:37] op_sel_hi:[1,0]
	v_pk_mul_f32 v[16:17], v[16:17], s[36:37] op_sel_hi:[1,0]
	v_ashrrev_i32_e32 v67, 31, v66
	v_pk_mul_f32 v[6:7], v[6:7], s[36:37] op_sel_hi:[1,0]
	v_pk_mul_f32 v[8:9], v[8:9], s[36:37] op_sel_hi:[1,0]
	s_waitcnt vmcnt(0)
	v_lshlrev_b32_e32 v106, 16, v70
	v_and_b32_e32 v70, 0xffff0000, v70
	v_lshlrev_b32_e32 v107, 16, v71
	v_and_b32_e32 v71, 0xffff0000, v71
	v_lshlrev_b32_e32 v108, 16, v72
	v_and_b32_e32 v72, 0xffff0000, v72
	v_lshlrev_b32_e32 v109, 16, v73
	v_and_b32_e32 v73, 0xffff0000, v73
	v_mul_f32_e32 v70, v91, v70
	v_mul_f32_e32 v71, v89, v71
	v_mul_f32_e32 v72, v95, v72
	v_mul_f32_e32 v73, v93, v73
	v_mul_f32_e32 v90, v90, v106
	v_mul_f32_e32 v88, v88, v107
	v_mul_f32_e32 v89, v94, v108
	v_mul_f32_e32 v91, v92, v109
	v_cvt_pk_bf16_f32 v70, v90, v70
	v_cvt_pk_bf16_f32 v71, v88, v71
	v_cvt_pk_bf16_f32 v72, v89, v72
	v_cvt_pk_bf16_f32 v73, v91, v73
	v_lshlrev_b32_e32 v111, 16, v75
	v_and_b32_e32 v75, 0xffff0000, v75
	global_store_dwordx4 v[104:105], v[70:73], off
	v_lshlrev_b32_e32 v110, 16, v74
	v_and_b32_e32 v74, 0xffff0000, v74
	v_lshlrev_b32_e32 v72, 16, v76
	v_and_b32_e32 v73, 0xffff0000, v76
	v_mul_f32_e32 v71, v97, v75
	v_mul_f32_e32 v72, v102, v72
	v_mul_f32_e32 v73, v103, v73
	v_mul_f32_e32 v92, v98, v110
	v_mul_f32_e32 v74, v99, v74
	v_mul_f32_e32 v93, v96, v111
	v_cvt_pk_bf16_f32 v70, v92, v74
	v_cvt_pk_bf16_f32 v71, v93, v71
	v_cvt_pk_bf16_f32 v72, v72, v73
	v_lshlrev_b32_e32 v73, 16, v77
	v_mul_f32_e32 v73, v100, v73
	v_and_b32_e32 v74, 0xffff0000, v77
	v_mul_f32_e32 v74, v101, v74
	v_cvt_pk_bf16_f32 v73, v73, v74
	global_store_dwordx4 v[104:105], v[70:73], off offset:256
	s_nop 1
	v_pk_mul_f32 v[72:73], v[44:45], s[36:37] op_sel_hi:[1,0]
	v_pk_mul_f32 v[44:45], v[42:43], s[36:37] op_sel_hi:[1,0]
	v_lshlrev_b32_e32 v42, 16, v58
	v_and_b32_e32 v43, 0xffff0000, v58
	v_mul_f32_e32 v42, v46, v42
	v_mul_f32_e32 v43, v47, v43
	v_cvt_pk_bf16_f32 v42, v42, v43
	v_lshlrev_b32_e32 v43, 16, v59
	v_and_b32_e32 v46, 0xffff0000, v59
	v_mul_f32_e32 v43, v48, v43
	v_mul_f32_e32 v46, v49, v46
	v_cvt_pk_bf16_f32 v43, v43, v46
	v_lshlrev_b32_e32 v46, 16, v60
	v_mul_f32_e32 v44, v44, v46
	v_and_b32_e32 v46, 0xffff0000, v60
	v_mul_f32_e32 v45, v45, v46
	v_cvt_pk_bf16_f32 v44, v44, v45
	v_lshlrev_b32_e32 v45, 16, v61
	v_and_b32_e32 v46, 0xffff0000, v61
	v_lshlrev_b64 v[70:71], 11, v[86:87]
	v_mul_f32_e32 v45, v72, v45
	v_mul_f32_e32 v46, v73, v46
	v_cvt_pk_bf16_f32 v45, v45, v46
	v_lshl_add_u64 v[46:47], s[74:75], 0, v[70:71]
	v_lshl_add_u64 v[46:47], v[46:47], 0, v[194:195]
	global_store_dwordx4 v[46:47], v[42:45], off
	s_nop 1
	v_pk_mul_f32 v[42:43], v[36:37], s[36:37] op_sel_hi:[1,0]
	v_pk_mul_f32 v[36:37], v[34:35], s[36:37] op_sel_hi:[1,0]
	v_lshlrev_b32_e32 v34, 16, v62
	v_and_b32_e32 v35, 0xffff0000, v62
	v_mul_f32_e32 v34, v38, v34
	v_mul_f32_e32 v35, v39, v35
	v_cvt_pk_bf16_f32 v34, v34, v35
	v_lshlrev_b32_e32 v35, 16, v63
	v_and_b32_e32 v38, 0xffff0000, v63
	v_mul_f32_e32 v35, v40, v35
	v_mul_f32_e32 v38, v41, v38
	v_cvt_pk_bf16_f32 v35, v35, v38
	v_lshlrev_b32_e32 v38, 16, v64
	v_mul_f32_e32 v36, v36, v38
	v_and_b32_e32 v38, 0xffff0000, v64
	v_mul_f32_e32 v37, v37, v38
	v_cvt_pk_bf16_f32 v36, v36, v37
	v_lshlrev_b32_e32 v37, 16, v65
	v_mul_f32_e32 v37, v42, v37
	v_and_b32_e32 v38, 0xffff0000, v65
	v_mul_f32_e32 v38, v43, v38
	v_cvt_pk_bf16_f32 v37, v37, v38
	global_store_dwordx4 v[46:47], v[34:37], off offset:256
	s_nop 1
	v_pk_mul_f32 v[36:37], v[28:29], s[36:37] op_sel_hi:[1,0]
	v_pk_mul_f32 v[28:29], v[26:27], s[36:37] op_sel_hi:[1,0]
	v_lshlrev_b32_e32 v26, 16, v78
	v_and_b32_e32 v27, 0xffff0000, v78
	v_mul_f32_e32 v26, v30, v26
	v_mul_f32_e32 v27, v31, v27
	v_cvt_pk_bf16_f32 v26, v26, v27
	v_lshlrev_b32_e32 v27, 16, v79
	v_and_b32_e32 v30, 0xffff0000, v79
	v_mul_f32_e32 v27, v32, v27
	v_mul_f32_e32 v30, v33, v30
	v_cvt_pk_bf16_f32 v27, v27, v30
	v_lshlrev_b32_e32 v30, 16, v80
	v_mul_f32_e32 v28, v28, v30
	v_and_b32_e32 v30, 0xffff0000, v80
	v_mul_f32_e32 v29, v29, v30
	v_cvt_pk_bf16_f32 v28, v28, v29
	v_lshlrev_b32_e32 v29, 16, v81
	v_and_b32_e32 v30, 0xffff0000, v81
	v_lshlrev_b64 v[34:35], 11, v[68:69]
	v_mul_f32_e32 v29, v36, v29
	v_mul_f32_e32 v30, v37, v30
	v_cvt_pk_bf16_f32 v29, v29, v30
	v_lshl_add_u64 v[30:31], s[74:75], 0, v[34:35]
	v_lshl_add_u64 v[30:31], v[30:31], 0, v[194:195]
	global_store_dwordx4 v[30:31], v[26:29], off
	s_nop 1
	v_pk_mul_f32 v[26:27], v[20:21], s[36:37] op_sel_hi:[1,0]
	v_pk_mul_f32 v[20:21], v[18:19], s[36:37] op_sel_hi:[1,0]
	v_lshlrev_b32_e32 v18, 16, v82
	v_and_b32_e32 v19, 0xffff0000, v82
	v_mul_f32_e32 v18, v22, v18
	v_mul_f32_e32 v19, v23, v19
	v_cvt_pk_bf16_f32 v18, v18, v19
	v_lshlrev_b32_e32 v19, 16, v83
	v_and_b32_e32 v22, 0xffff0000, v83
	v_mul_f32_e32 v19, v24, v19
	v_mul_f32_e32 v22, v25, v22
	v_cvt_pk_bf16_f32 v19, v19, v22
	v_lshlrev_b32_e32 v22, 16, v84
	v_mul_f32_e32 v20, v20, v22
	v_and_b32_e32 v22, 0xffff0000, v84
	v_mul_f32_e32 v21, v21, v22
	v_cvt_pk_bf16_f32 v20, v20, v21
	v_lshlrev_b32_e32 v21, 16, v85
	v_mul_f32_e32 v21, v26, v21
	v_and_b32_e32 v22, 0xffff0000, v85
	v_mul_f32_e32 v22, v27, v22
	v_cvt_pk_bf16_f32 v21, v21, v22
	global_store_dwordx4 v[30:31], v[18:21], off offset:256
	s_nop 1
	v_pk_mul_f32 v[20:21], v[12:13], s[36:37] op_sel_hi:[1,0]
	v_pk_mul_f32 v[12:13], v[10:11], s[36:37] op_sel_hi:[1,0]
	v_lshlrev_b32_e32 v10, 16, v54
	v_and_b32_e32 v11, 0xffff0000, v54
	v_mul_f32_e32 v10, v14, v10
	v_mul_f32_e32 v11, v15, v11
	v_cvt_pk_bf16_f32 v10, v10, v11
	v_lshlrev_b32_e32 v11, 16, v55
	v_and_b32_e32 v14, 0xffff0000, v55
	v_mul_f32_e32 v11, v16, v11
	v_mul_f32_e32 v14, v17, v14
	v_cvt_pk_bf16_f32 v11, v11, v14
	v_lshlrev_b32_e32 v14, 16, v56
	v_mul_f32_e32 v12, v12, v14
	v_and_b32_e32 v14, 0xffff0000, v56
	v_mul_f32_e32 v13, v13, v14
	v_cvt_pk_bf16_f32 v12, v12, v13
	v_lshlrev_b32_e32 v13, 16, v57
	v_and_b32_e32 v14, 0xffff0000, v57
	v_lshlrev_b64 v[18:19], 11, v[66:67]
	v_mul_f32_e32 v13, v20, v13
	v_mul_f32_e32 v14, v21, v14
	v_cvt_pk_bf16_f32 v13, v13, v14
	v_lshl_add_u64 v[14:15], s[74:75], 0, v[18:19]
	v_lshl_add_u64 v[14:15], v[14:15], 0, v[194:195]
	global_store_dwordx4 v[14:15], v[10:13], off
	s_nop 1
	v_pk_mul_f32 v[10:11], v[4:5], s[36:37] op_sel_hi:[1,0]
	v_pk_mul_f32 v[4:5], v[2:3], s[36:37] op_sel_hi:[1,0]
	v_lshlrev_b32_e32 v2, 16, v50
	v_and_b32_e32 v3, 0xffff0000, v50
	v_mul_f32_e32 v2, v6, v2
	v_mul_f32_e32 v3, v7, v3
	v_cvt_pk_bf16_f32 v2, v2, v3
	v_lshlrev_b32_e32 v3, 16, v51
	v_and_b32_e32 v6, 0xffff0000, v51
	v_mul_f32_e32 v3, v8, v3
	v_mul_f32_e32 v6, v9, v6
	v_cvt_pk_bf16_f32 v3, v3, v6
	v_lshlrev_b32_e32 v6, 16, v52
	v_mul_f32_e32 v4, v4, v6
	v_and_b32_e32 v6, 0xffff0000, v52
	v_mul_f32_e32 v5, v5, v6
	v_cvt_pk_bf16_f32 v4, v4, v5
	v_lshlrev_b32_e32 v5, 16, v53
	v_mul_f32_e32 v5, v10, v5
	v_and_b32_e32 v6, 0xffff0000, v53
	v_mul_f32_e32 v6, v11, v6
	v_cvt_pk_bf16_f32 v5, v5, v6
	global_store_dwordx4 v[14:15], v[2:5], off offset:256
	s_and_b64 vcc, exec, s[52:53]
	s_mov_b32 s28, s4
	s_cbranch_vccz .LBB0_265
	s_waitcnt vmcnt(0)
	v_readlane_b32 s28, v250, 12
	s_cmpk_gt_u32 s12, 0xff
	v_readlane_b32 s29, v250, 13
	s_mov_b32 s70, 0x800000
	s_cbranch_scc1 .LBB0_270
	s_barrier

.LBB0_368:
	v_or_b32_e32 v130, 0x10000, v201
	v_add_u32_e32 v134, 0x10400, v201
	v_add_u32_e32 v138, 0x10800, v201
	v_add_u32_e32 v142, 0x10c00, v201
	ds_read_b128 v[130:133], v130
	ds_read_b128 v[134:137], v134
	ds_read_b128 v[138:141], v138
	ds_read_b128 v[142:145], v142
	s_add_u32 s10, s8, 0xfffc0080
	s_addc_u32 s11, s9, -1
	s_cmp_eq_u32 s29, 12
	s_cselect_b32 s11, s81, s11
	s_cselect_b32 s10, s80, s10
	s_cselect_b32 s53, s83, s28
	s_cselect_b32 s52, s82, s7
	v_lshl_add_u64 v[178:179], s[8:9], 0, v[212:213]
	s_add_i32 m0, s34, 0xc000
	ds_read_b128 v[146:149], v199
	ds_read_b128 v[150:153], v199 offset:1024
	ds_read_b128 v[154:157], v199 offset:2048
	ds_read_b128 v[158:161], v199 offset:3072
	ds_read_b128 v[162:165], v199 offset:4096
	ds_read_b128 v[166:169], v199 offset:5120
	ds_read_b128 v[170:173], v199 offset:6144
	ds_read_b128 v[174:177], v199 offset:7168
	global_load_lds_dwordx4 v[178:179], off
	v_lshl_add_u64 v[178:179], s[8:9], 0, v[214:215]
	s_add_i32 m0, s34, 0xe000
	s_nop 0
	global_load_lds_dwordx4 v[178:179], off
	s_waitcnt lgkmcnt(8)
	s_barrier
	s_waitcnt lgkmcnt(0)
	s_setprio 1
	v_mfma_f32_16x16x32_bf16 v[126:129], v[130:133], v[146:149], v[126:129]
	v_mfma_f32_16x16x32_bf16 v[122:125], v[138:141], v[146:149], v[122:125]
	v_mfma_f32_16x16x32_bf16 v[118:121], v[130:133], v[154:157], v[118:121]
	v_mfma_f32_16x16x32_bf16 v[114:117], v[138:141], v[154:157], v[114:117]
	v_mfma_f32_16x16x32_bf16 v[110:113], v[130:133], v[162:165], v[110:113]
	v_mfma_f32_16x16x32_bf16 v[106:109], v[138:141], v[162:165], v[106:109]
	v_mfma_f32_16x16x32_bf16 v[102:105], v[130:133], v[170:173], v[102:105]
	v_mfma_f32_16x16x32_bf16 v[98:101], v[138:141], v[170:173], v[98:101]
	v_mfma_f32_16x16x32_bf16 v[126:129], v[134:137], v[150:153], v[126:129]
	v_mfma_f32_16x16x32_bf16 v[122:125], v[142:145], v[150:153], v[122:125]
	v_mfma_f32_16x16x32_bf16 v[118:121], v[134:137], v[158:161], v[118:121]
	v_mfma_f32_16x16x32_bf16 v[114:117], v[142:145], v[158:161], v[114:117]
	v_mfma_f32_16x16x32_bf16 v[110:113], v[134:137], v[166:169], v[110:113]
	v_mfma_f32_16x16x32_bf16 v[106:109], v[142:145], v[166:169], v[106:109]
	v_mfma_f32_16x16x32_bf16 v[102:105], v[134:137], v[174:177], v[102:105]
	v_mfma_f32_16x16x32_bf16 v[98:101], v[142:145], v[174:177], v[98:101]
	s_setprio 0
	s_barrier
	s_mov_b32 m0, s35
	v_or_b32_e32 v178, 0x14000, v201
	v_add_u32_e32 v182, 0x14400, v201
	v_add_u32_e32 v186, 0x14800, v201
	v_add_u32_e32 v190, 0x14c00, v201
	v_lshl_add_u64 v[216:217], s[52:53], 0, v[194:195]
	ds_read_b128 v[178:181], v178
	ds_read_b128 v[182:185], v182
	ds_read_b128 v[186:189], v186
	ds_read_b128 v[190:193], v190
	global_load_lds_dwordx4 v[216:217], off
	v_lshl_add_u64 v[218:219], s[52:53], 0, v[210:211]
	s_mov_b32 m0, s42
	s_nop 0
	global_load_lds_dwordx4 v[218:219], off
	s_barrier
	s_waitcnt lgkmcnt(0)
	s_setprio 1
	v_mfma_f32_16x16x32_bf16 v[94:97], v[178:181], v[146:149], v[94:97]
	v_mfma_f32_16x16x32_bf16 v[90:93], v[186:189], v[146:149], v[90:93]
	v_mfma_f32_16x16x32_bf16 v[86:89], v[178:181], v[154:157], v[86:89]
	v_mfma_f32_16x16x32_bf16 v[82:85], v[186:189], v[154:157], v[82:85]
	v_mfma_f32_16x16x32_bf16 v[78:81], v[178:181], v[162:165], v[78:81]
	v_mfma_f32_16x16x32_bf16 v[74:77], v[186:189], v[162:165], v[74:77]
	v_mfma_f32_16x16x32_bf16 v[70:73], v[178:181], v[170:173], v[70:73]
	v_mfma_f32_16x16x32_bf16 v[66:69], v[186:189], v[170:173], v[66:69]
	v_mfma_f32_16x16x32_bf16 v[94:97], v[182:185], v[150:153], v[94:97]
	v_mfma_f32_16x16x32_bf16 v[90:93], v[190:193], v[150:153], v[90:93]
	v_mfma_f32_16x16x32_bf16 v[86:89], v[182:185], v[158:161], v[86:89]
	v_mfma_f32_16x16x32_bf16 v[82:85], v[190:193], v[158:161], v[82:85]
	v_mfma_f32_16x16x32_bf16 v[78:81], v[182:185], v[166:169], v[78:81]
	v_mfma_f32_16x16x32_bf16 v[74:77], v[190:193], v[166:169], v[74:77]
	s_mov_b32 m0, s34
	v_mfma_f32_16x16x32_bf16 v[70:73], v[182:185], v[174:177], v[70:73]
	v_lshl_add_u64 v[220:221], s[10:11], 0, v[206:207]
	v_mfma_f32_16x16x32_bf16 v[66:69], v[190:193], v[174:177], v[66:69]
	s_setprio 0
	s_barrier
	ds_read_b128 v[146:149], v199 offset:16384
	ds_read_b128 v[150:153], v199 offset:17408
	ds_read_b128 v[154:157], v199 offset:18432
	ds_read_b128 v[158:161], v199 offset:19456
	ds_read_b128 v[162:165], v199 offset:20480
	ds_read_b128 v[166:169], v199 offset:21504
	ds_read_b128 v[170:173], v199 offset:22528
	ds_read_b128 v[174:177], v199 offset:23552
	global_load_lds_dwordx4 v[220:221], off
	v_lshl_add_u64 v[222:223], s[10:11], 0, v[208:209]
	s_mov_b32 m0, s56
	s_nop 0
	global_load_lds_dwordx4 v[222:223], off
	s_barrier
	s_waitcnt lgkmcnt(0)
	s_setprio 1
	v_mfma_f32_16x16x32_bf16 v[62:65], v[130:133], v[146:149], v[62:65]
	v_mfma_f32_16x16x32_bf16 v[58:61], v[138:141], v[146:149], v[58:61]
	v_mfma_f32_16x16x32_bf16 v[54:57], v[130:133], v[154:157], v[54:57]
	v_mfma_f32_16x16x32_bf16 v[50:53], v[138:141], v[154:157], v[50:53]
	v_mfma_f32_16x16x32_bf16 v[46:49], v[130:133], v[162:165], v[46:49]
	v_mfma_f32_16x16x32_bf16 v[42:45], v[138:141], v[162:165], v[42:45]
	v_mfma_f32_16x16x32_bf16 v[38:41], v[130:133], v[170:173], v[38:41]
	v_mfma_f32_16x16x32_bf16 v[34:37], v[138:141], v[170:173], v[34:37]
	v_mfma_f32_16x16x32_bf16 v[62:65], v[134:137], v[150:153], v[62:65]
	v_mfma_f32_16x16x32_bf16 v[58:61], v[142:145], v[150:153], v[58:61]
	v_mfma_f32_16x16x32_bf16 v[54:57], v[134:137], v[158:161], v[54:57]
	v_mfma_f32_16x16x32_bf16 v[50:53], v[142:145], v[158:161], v[50:53]
	v_mfma_f32_16x16x32_bf16 v[46:49], v[134:137], v[166:169], v[46:49]
	v_mfma_f32_16x16x32_bf16 v[42:45], v[142:145], v[166:169], v[42:45]
	v_mfma_f32_16x16x32_bf16 v[38:41], v[134:137], v[174:177], v[38:41]
	v_mfma_f32_16x16x32_bf16 v[34:37], v[142:145], v[174:177], v[34:37]
	s_setprio 0
	s_barrier
	s_add_u32 s86, s52, 0x40000
	s_addc_u32 s87, s53, 0
	s_mov_b32 m0, s57
	v_lshl_add_u64 v[130:131], s[86:87], 0, v[194:195]
	global_load_lds_dwordx4 v[130:131], off
	v_lshl_add_u64 v[130:131], s[86:87], 0, v[210:211]
	s_mov_b32 m0, s67
	s_nop 0
	global_load_lds_dwordx4 v[130:131], off
	s_waitcnt vmcnt(6)
	s_barrier
	s_setprio 1
	v_mfma_f32_16x16x32_bf16 v[30:33], v[178:181], v[146:149], v[30:33]
	v_mfma_f32_16x16x32_bf16 v[26:29], v[186:189], v[146:149], v[26:29]
	v_mfma_f32_16x16x32_bf16 v[22:25], v[178:181], v[154:157], v[22:25]
	v_mfma_f32_16x16x32_bf16 v[18:21], v[186:189], v[154:157], v[18:21]
	v_mfma_f32_16x16x32_bf16 v[14:17], v[178:181], v[162:165], v[14:17]
	v_mfma_f32_16x16x32_bf16 v[10:13], v[186:189], v[162:165], v[10:13]
	v_mfma_f32_16x16x32_bf16 v[6:9], v[178:181], v[170:173], v[6:9]
	v_mfma_f32_16x16x32_bf16 v[2:5], v[186:189], v[170:173], v[2:5]
	v_mfma_f32_16x16x32_bf16 v[30:33], v[182:185], v[150:153], v[30:33]
	v_mfma_f32_16x16x32_bf16 v[26:29], v[190:193], v[150:153], v[26:29]
	v_mfma_f32_16x16x32_bf16 v[22:25], v[182:185], v[158:161], v[22:25]
	v_mfma_f32_16x16x32_bf16 v[18:21], v[190:193], v[158:161], v[18:21]
	v_or_b32_e32 v130, 0x18000, v201
	v_mfma_f32_16x16x32_bf16 v[14:17], v[182:185], v[166:169], v[14:17]
	v_add_u32_e32 v134, 0x18400, v201
	v_mfma_f32_16x16x32_bf16 v[10:13], v[190:193], v[166:169], v[10:13]
	v_add_u32_e32 v138, 0x18800, v201
	v_mfma_f32_16x16x32_bf16 v[6:9], v[182:185], v[174:177], v[6:9]
	v_add_u32_e32 v142, 0x18c00, v201
	v_mfma_f32_16x16x32_bf16 v[2:5], v[190:193], v[174:177], v[2:5]
	s_setprio 0
	s_barrier
	ds_read_b128 v[130:133], v130
	ds_read_b128 v[134:137], v134
	ds_read_b128 v[138:141], v138
	ds_read_b128 v[142:145], v142
	s_add_u32 s10, s10, 0x40000
	s_addc_u32 s11, s11, 0
	s_mov_b32 m0, s70
	v_lshl_add_u64 v[178:179], s[10:11], 0, v[206:207]
	ds_read_b128 v[146:149], v199 offset:32768
	ds_read_b128 v[150:153], v199 offset:33792
	ds_read_b128 v[154:157], v199 offset:34816
	ds_read_b128 v[158:161], v199 offset:35840
	ds_read_b128 v[162:165], v199 offset:36864
	ds_read_b128 v[166:169], v199 offset:37888
	ds_read_b128 v[170:173], v199 offset:38912
	ds_read_b128 v[174:177], v199 offset:39936
	global_load_lds_dwordx4 v[178:179], off
	v_lshl_add_u64 v[178:179], s[10:11], 0, v[208:209]
	s_mov_b32 m0, s71
	s_nop 0
	global_load_lds_dwordx4 v[178:179], off
	s_waitcnt lgkmcnt(8)
	s_barrier
	s_waitcnt lgkmcnt(0)
	s_setprio 1
	v_mfma_f32_16x16x32_bf16 v[126:129], v[130:133], v[146:149], v[126:129]
	v_mfma_f32_16x16x32_bf16 v[122:125], v[138:141], v[146:149], v[122:125]
	v_mfma_f32_16x16x32_bf16 v[118:121], v[130:133], v[154:157], v[118:121]
	v_mfma_f32_16x16x32_bf16 v[114:117], v[138:141], v[154:157], v[114:117]
	v_mfma_f32_16x16x32_bf16 v[110:113], v[130:133], v[162:165], v[110:113]
	v_mfma_f32_16x16x32_bf16 v[106:109], v[138:141], v[162:165], v[106:109]
	v_mfma_f32_16x16x32_bf16 v[102:105], v[130:133], v[170:173], v[102:105]
	v_mfma_f32_16x16x32_bf16 v[98:101], v[138:141], v[170:173], v[98:101]
	v_mfma_f32_16x16x32_bf16 v[126:129], v[134:137], v[150:153], v[126:129]
	v_mfma_f32_16x16x32_bf16 v[122:125], v[142:145], v[150:153], v[122:125]
	v_mfma_f32_16x16x32_bf16 v[118:121], v[134:137], v[158:161], v[118:121]
	v_mfma_f32_16x16x32_bf16 v[114:117], v[142:145], v[158:161], v[114:117]
	v_mfma_f32_16x16x32_bf16 v[110:113], v[134:137], v[166:169], v[110:113]
	v_mfma_f32_16x16x32_bf16 v[106:109], v[142:145], v[166:169], v[106:109]
	v_mfma_f32_16x16x32_bf16 v[102:105], v[134:137], v[174:177], v[102:105]
	v_mfma_f32_16x16x32_bf16 v[98:101], v[142:145], v[174:177], v[98:101]
	s_setprio 0
	s_barrier
	s_mov_b32 m0, s78
	v_or_b32_e32 v178, 0x1c000, v201
	v_add_u32_e32 v182, 0x1c400, v201
	v_add_u32_e32 v186, 0x1c800, v201
	v_add_u32_e32 v190, 0x1cc00, v201
	v_lshl_add_u64 v[216:217], v[216:217], 0, s[76:77]
	ds_read_b128 v[178:181], v178
	ds_read_b128 v[182:185], v182
	ds_read_b128 v[186:189], v186
	ds_read_b128 v[190:193], v190
	global_load_lds_dwordx4 v[216:217], off
	v_lshl_add_u64 v[216:217], v[218:219], 0, s[76:77]
	s_mov_b32 m0, s79
	s_nop 0
	global_load_lds_dwordx4 v[216:217], off
	s_barrier
	s_waitcnt lgkmcnt(0)
	s_setprio 1
	v_mfma_f32_16x16x32_bf16 v[94:97], v[178:181], v[146:149], v[94:97]
	v_mfma_f32_16x16x32_bf16 v[90:93], v[186:189], v[146:149], v[90:93]
	v_mfma_f32_16x16x32_bf16 v[86:89], v[178:181], v[154:157], v[86:89]
	v_mfma_f32_16x16x32_bf16 v[82:85], v[186:189], v[154:157], v[82:85]
	v_mfma_f32_16x16x32_bf16 v[78:81], v[178:181], v[162:165], v[78:81]
	v_mfma_f32_16x16x32_bf16 v[74:77], v[186:189], v[162:165], v[74:77]
	v_mfma_f32_16x16x32_bf16 v[70:73], v[178:181], v[170:173], v[70:73]
	v_mfma_f32_16x16x32_bf16 v[66:69], v[186:189], v[170:173], v[66:69]
	v_mfma_f32_16x16x32_bf16 v[94:97], v[182:185], v[150:153], v[94:97]
	v_mfma_f32_16x16x32_bf16 v[90:93], v[190:193], v[150:153], v[90:93]
	v_mfma_f32_16x16x32_bf16 v[86:89], v[182:185], v[158:161], v[86:89]
	v_mfma_f32_16x16x32_bf16 v[82:85], v[190:193], v[158:161], v[82:85]
	v_mfma_f32_16x16x32_bf16 v[78:81], v[182:185], v[166:169], v[78:81]
	v_mfma_f32_16x16x32_bf16 v[74:77], v[190:193], v[166:169], v[74:77]
	s_mov_b32 m0, s26
	v_mfma_f32_16x16x32_bf16 v[70:73], v[182:185], v[174:177], v[70:73]
	v_lshl_add_u64 v[216:217], v[220:221], 0, s[76:77]
	v_mfma_f32_16x16x32_bf16 v[66:69], v[190:193], v[174:177], v[66:69]
	s_setprio 0
	s_barrier
	ds_read_b128 v[146:149], v199 offset:49152
	ds_read_b128 v[150:153], v199 offset:50176
	ds_read_b128 v[154:157], v199 offset:51200
	ds_read_b128 v[158:161], v199 offset:52224
	ds_read_b128 v[162:165], v199 offset:53248
	ds_read_b128 v[166:169], v199 offset:54272
	ds_read_b128 v[170:173], v199 offset:55296
	ds_read_b128 v[174:177], v199 offset:56320
	global_load_lds_dwordx4 v[216:217], off
	v_lshl_add_u64 v[216:217], v[222:223], 0, s[76:77]
	s_mov_b32 m0, s4
	s_nop 0
	global_load_lds_dwordx4 v[216:217], off
	s_barrier
	s_waitcnt lgkmcnt(0)
	s_setprio 1
	v_mfma_f32_16x16x32_bf16 v[62:65], v[130:133], v[146:149], v[62:65]
	v_mfma_f32_16x16x32_bf16 v[58:61], v[138:141], v[146:149], v[58:61]
	v_mfma_f32_16x16x32_bf16 v[54:57], v[130:133], v[154:157], v[54:57]
	v_mfma_f32_16x16x32_bf16 v[50:53], v[138:141], v[154:157], v[50:53]
	v_mfma_f32_16x16x32_bf16 v[46:49], v[130:133], v[162:165], v[46:49]
	v_mfma_f32_16x16x32_bf16 v[42:45], v[138:141], v[162:165], v[42:45]
	v_mfma_f32_16x16x32_bf16 v[38:41], v[130:133], v[170:173], v[38:41]
	v_mfma_f32_16x16x32_bf16 v[34:37], v[138:141], v[170:173], v[34:37]
	v_mfma_f32_16x16x32_bf16 v[62:65], v[134:137], v[150:153], v[62:65]
	v_mfma_f32_16x16x32_bf16 v[58:61], v[142:145], v[150:153], v[58:61]
	v_mfma_f32_16x16x32_bf16 v[54:57], v[134:137], v[158:161], v[54:57]
	v_mfma_f32_16x16x32_bf16 v[50:53], v[142:145], v[158:161], v[50:53]
	v_mfma_f32_16x16x32_bf16 v[46:49], v[134:137], v[166:169], v[46:49]
	v_mfma_f32_16x16x32_bf16 v[42:45], v[142:145], v[166:169], v[42:45]
	v_mfma_f32_16x16x32_bf16 v[38:41], v[134:137], v[174:177], v[38:41]
	v_mfma_f32_16x16x32_bf16 v[34:37], v[142:145], v[174:177], v[34:37]
	s_setprio 0
	s_barrier
	s_add_u32 s10, s52, 0x40080
	s_addc_u32 s11, s53, 0
	s_mov_b32 m0, s5
	v_lshl_add_u64 v[130:131], s[10:11], 0, v[194:195]
	global_load_lds_dwordx4 v[130:131], off
	v_lshl_add_u64 v[130:131], s[10:11], 0, v[210:211]
	s_mov_b32 m0, s58
	s_nop 0
	global_load_lds_dwordx4 v[130:131], off
	s_waitcnt vmcnt(6)
	s_barrier
	s_setprio 1
	v_mfma_f32_16x16x32_bf16 v[30:33], v[178:181], v[146:149], v[30:33]
	v_mfma_f32_16x16x32_bf16 v[26:29], v[186:189], v[146:149], v[26:29]
	v_mfma_f32_16x16x32_bf16 v[22:25], v[178:181], v[154:157], v[22:25]
	v_mfma_f32_16x16x32_bf16 v[18:21], v[186:189], v[154:157], v[18:21]
	v_mfma_f32_16x16x32_bf16 v[14:17], v[178:181], v[162:165], v[14:17]
	v_mfma_f32_16x16x32_bf16 v[10:13], v[186:189], v[162:165], v[10:13]
	v_mfma_f32_16x16x32_bf16 v[6:9], v[178:181], v[170:173], v[6:9]
	v_mfma_f32_16x16x32_bf16 v[2:5], v[186:189], v[170:173], v[2:5]
	v_mfma_f32_16x16x32_bf16 v[30:33], v[182:185], v[150:153], v[30:33]
	v_mfma_f32_16x16x32_bf16 v[26:29], v[190:193], v[150:153], v[26:29]
	v_mfma_f32_16x16x32_bf16 v[22:25], v[182:185], v[158:161], v[22:25]
	v_mfma_f32_16x16x32_bf16 v[18:21], v[190:193], v[158:161], v[18:21]
	v_mfma_f32_16x16x32_bf16 v[14:17], v[182:185], v[166:169], v[14:17]
	v_mfma_f32_16x16x32_bf16 v[10:13], v[190:193], v[166:169], v[10:13]
	v_mfma_f32_16x16x32_bf16 v[6:9], v[182:185], v[174:177], v[6:9]
	v_mfma_f32_16x16x32_bf16 v[2:5], v[190:193], v[174:177], v[2:5]
	s_setprio 0
	s_add_i32 s29, s29, 2
	s_add_u32 s8, s8, 0x100
	s_addc_u32 s9, s9, 0
	s_add_u32 s7, s7, 0x100
	s_addc_u32 s28, s28, 0
	s_cmp_gt_u32 s29, 13
	s_barrier
	s_cbranch_scc0 .LBB0_368
	s_cmp_gt_i32 s95, 1
	s_cselect_b64 s[52:53], -1, 0
	s_mul_i32 s7, s6, 0x680000
	s_lshl_b32 s8, s95, 12
	s_lshl_b32 s9, s54, 9
	s_add_i32 s7, s7, s8
	s_add_i32 s7, s7, s9
	s_add_i32 s7, s7, 0x3800
	s_add_u32 s20, s50, s7
	s_addc_u32 s21, s51, 0
	s_lshl_b32 s7, s6, 20
	s_add_i32 s7, s7, s9
	s_add_u32 s10, s96, s7
	s_addc_u32 s11, s97, 0
	s_mov_b32 s86, 0xbfb8aa3b
	s_mov_b32 s87, 0xbfb8aa3b
	v_mul_u32_u24_e32 v253, 0x6800, v197
	v_lshlrev_b32_e32 v255, 12, v197
	v_lshl_add_u32 v253, v203, 1, v253
	v_lshl_add_u32 v255, v203, 1, v255
	v_add_u32_e32 v254, 0x1000, v253
	s_cmp_eq_u32 s95, 2
	s_cbranch_scc1 .Lem_br2
	global_load_dwordx4 v[130:133], v253, s[20:21]
	global_load_dwordx4 v[134:137], v254, s[20:21]
	global_load_dwordx4 v[138:141], v253, s[20:21] offset:256
	global_load_dwordx4 v[142:145], v254, s[20:21] offset:256
	s_add_u32 s28, s20, 0x68000
	s_addc_u32 s29, s21, 0
	global_load_dwordx4 v[146:149], v253, s[28:29]
	global_load_dwordx4 v[150:153], v254, s[28:29]
	global_load_dwordx4 v[154:157], v253, s[28:29] offset:256
	global_load_dwordx4 v[158:161], v254, s[28:29] offset:256
	s_add_u32 s28, s20, 0xd0000
	s_addc_u32 s29, s21, 0
	global_load_dwordx4 v[162:165], v253, s[28:29]
	global_load_dwordx4 v[166:169], v254, s[28:29]
	global_load_dwordx4 v[170:173], v253, s[28:29] offset:256
	global_load_dwordx4 v[174:177], v254, s[28:29] offset:256
	s_add_u32 s28, s20, 0x138000
	s_addc_u32 s29, s21, 0
	global_load_dwordx4 v[178:181], v253, s[28:29]
	global_load_dwordx4 v[182:185], v254, s[28:29]
	global_load_dwordx4 v[186:189], v253, s[28:29] offset:256
	global_load_dwordx4 v[190:193], v254, s[28:29] offset:256
	s_waitcnt vmcnt(12)
	v_lshlrev_b32_e32 v216, 16, v130
	v_and_b32_e32 v217, 0xffff0000, v130
	v_lshlrev_b32_e32 v218, 16, v131
	v_and_b32_e32 v219, 0xffff0000, v131
	v_lshlrev_b32_e32 v220, 16, v132
	v_and_b32_e32 v221, 0xffff0000, v132
	v_lshlrev_b32_e32 v222, 16, v133
	v_and_b32_e32 v223, 0xffff0000, v133
	v_pk_mul_f32 v[216:217], v[216:217], s[86:87] op_sel_hi:[1,0]
	v_pk_mul_f32 v[218:219], v[218:219], s[86:87] op_sel_hi:[1,0]
	v_pk_mul_f32 v[220:221], v[220:221], s[86:87] op_sel_hi:[1,0]
	v_pk_mul_f32 v[222:223], v[222:223], s[86:87] op_sel_hi:[1,0]
	v_exp_f32_e32 v216, v216
	v_exp_f32_e32 v217, v217
	v_exp_f32_e32 v218, v218
	v_exp_f32_e32 v219, v219
	v_exp_f32_e32 v220, v220
	v_exp_f32_e32 v221, v221
	v_exp_f32_e32 v222, v222
	v_exp_f32_e32 v223, v223
	v_pk_add_f32 v[216:217], v[216:217], 1.0 op_sel_hi:[1,0]
	v_pk_add_f32 v[218:219], v[218:219], 1.0 op_sel_hi:[1,0]
	v_pk_add_f32 v[220:221], v[220:221], 1.0 op_sel_hi:[1,0]
	v_pk_add_f32 v[222:223], v[222:223], 1.0 op_sel_hi:[1,0]
	v_rcp_f32_e32 v216, v216
	v_rcp_f32_e32 v217, v217
	v_rcp_f32_e32 v218, v218
	v_rcp_f32_e32 v219, v219
	v_rcp_f32_e32 v220, v220
	v_rcp_f32_e32 v221, v221
	v_rcp_f32_e32 v222, v222
	v_rcp_f32_e32 v223, v223
	v_lshlrev_b32_e32 v242, 16, v134
	v_and_b32_e32 v243, 0xffff0000, v134
	v_lshlrev_b32_e32 v244, 16, v135
	v_and_b32_e32 v245, 0xffff0000, v135
	v_lshlrev_b32_e32 v246, 16, v136
	v_and_b32_e32 v247, 0xffff0000, v136
	v_lshlrev_b32_e32 v248, 16, v137
	v_and_b32_e32 v249, 0xffff0000, v137
	v_pk_mul_f32 v[242:243], v[242:243], s[86:87] op_sel_hi:[1,0]
	v_pk_mul_f32 v[244:245], v[244:245], s[86:87] op_sel_hi:[1,0]
	v_pk_mul_f32 v[246:247], v[246:247], s[86:87] op_sel_hi:[1,0]
	v_pk_mul_f32 v[248:249], v[248:249], s[86:87] op_sel_hi:[1,0]
	v_exp_f32_e32 v242, v242
	v_exp_f32_e32 v243, v243
	v_exp_f32_e32 v244, v244
	v_exp_f32_e32 v245, v245
	v_exp_f32_e32 v246, v246
	v_exp_f32_e32 v247, v247
	v_exp_f32_e32 v248, v248
	v_exp_f32_e32 v249, v249
	v_pk_add_f32 v[242:243], v[242:243], 1.0 op_sel_hi:[1,0]
	v_pk_add_f32 v[244:245], v[244:245], 1.0 op_sel_hi:[1,0]
	v_pk_add_f32 v[246:247], v[246:247], 1.0 op_sel_hi:[1,0]
	v_pk_add_f32 v[248:249], v[248:249], 1.0 op_sel_hi:[1,0]
	v_pk_mul_f32 v[216:217], v[216:217], v[242:243]
	v_pk_mul_f32 v[218:219], v[218:219], v[244:245]
	v_pk_mul_f32 v[220:221], v[220:221], v[246:247]
	v_pk_mul_f32 v[222:223], v[222:223], v[248:249]
	v_pk_mul_f32 v[126:127], v[126:127], v[216:217]
	v_pk_mul_f32 v[128:129], v[128:129], v[218:219]
	v_pk_mul_f32 v[122:123], v[122:123], v[220:221]
	v_pk_mul_f32 v[124:125], v[124:125], v[222:223]
	v_lshlrev_b32_e32 v216, 16, v138
	v_and_b32_e32 v217, 0xffff0000, v138
	v_lshlrev_b32_e32 v218, 16, v139
	v_and_b32_e32 v219, 0xffff0000, v139
	v_lshlrev_b32_e32 v220, 16, v140
	v_and_b32_e32 v221, 0xffff0000, v140
	v_lshlrev_b32_e32 v222, 16, v141
	v_and_b32_e32 v223, 0xffff0000, v141
	v_pk_mul_f32 v[216:217], v[216:217], s[86:87] op_sel_hi:[1,0]
	v_pk_mul_f32 v[218:219], v[218:219], s[86:87] op_sel_hi:[1,0]
	v_pk_mul_f32 v[220:221], v[220:221], s[86:87] op_sel_hi:[1,0]
	v_pk_mul_f32 v[222:223], v[222:223], s[86:87] op_sel_hi:[1,0]
	v_exp_f32_e32 v216, v216
	v_exp_f32_e32 v217, v217
	v_exp_f32_e32 v218, v218
	v_exp_f32_e32 v219, v219
	v_exp_f32_e32 v220, v220
	v_exp_f32_e32 v221, v221
	v_exp_f32_e32 v222, v222
	v_exp_f32_e32 v223, v223
	v_pk_add_f32 v[216:217], v[216:217], 1.0 op_sel_hi:[1,0]
	v_pk_add_f32 v[218:219], v[218:219], 1.0 op_sel_hi:[1,0]
	v_pk_add_f32 v[220:221], v[220:221], 1.0 op_sel_hi:[1,0]
	v_pk_add_f32 v[222:223], v[222:223], 1.0 op_sel_hi:[1,0]
	v_rcp_f32_e32 v216, v216
	v_rcp_f32_e32 v217, v217
	v_rcp_f32_e32 v218, v218
	v_rcp_f32_e32 v219, v219
	v_rcp_f32_e32 v220, v220
	v_rcp_f32_e32 v221, v221
	v_rcp_f32_e32 v222, v222
	v_rcp_f32_e32 v223, v223
	v_lshlrev_b32_e32 v242, 16, v142
	v_and_b32_e32 v243, 0xffff0000, v142
	v_lshlrev_b32_e32 v244, 16, v143
	v_and_b32_e32 v245, 0xffff0000, v143
	v_lshlrev_b32_e32 v246, 16, v144
	v_and_b32_e32 v247, 0xffff0000, v144
	v_lshlrev_b32_e32 v248, 16, v145
	v_and_b32_e32 v249, 0xffff0000, v145
	v_pk_mul_f32 v[242:243], v[242:243], s[86:87] op_sel_hi:[1,0]
	v_pk_mul_f32 v[244:245], v[244:245], s[86:87] op_sel_hi:[1,0]
	v_pk_mul_f32 v[246:247], v[246:247], s[86:87] op_sel_hi:[1,0]
	v_pk_mul_f32 v[248:249], v[248:249], s[86:87] op_sel_hi:[1,0]
	v_exp_f32_e32 v242, v242
	v_exp_f32_e32 v243, v243
	v_exp_f32_e32 v244, v244
	v_exp_f32_e32 v245, v245
	v_exp_f32_e32 v246, v246
	v_exp_f32_e32 v247, v247
	v_exp_f32_e32 v248, v248
	v_exp_f32_e32 v249, v249
	v_pk_add_f32 v[242:243], v[242:243], 1.0 op_sel_hi:[1,0]
	v_pk_add_f32 v[244:245], v[244:245], 1.0 op_sel_hi:[1,0]
	v_pk_add_f32 v[246:247], v[246:247], 1.0 op_sel_hi:[1,0]
	v_pk_add_f32 v[248:249], v[248:249], 1.0 op_sel_hi:[1,0]
	v_pk_mul_f32 v[216:217], v[216:217], v[242:243]
	v_pk_mul_f32 v[218:219], v[218:219], v[244:245]
	v_pk_mul_f32 v[220:221], v[220:221], v[246:247]
	v_pk_mul_f32 v[222:223], v[222:223], v[248:249]
	v_pk_mul_f32 v[94:95], v[94:95], v[216:217]
	v_pk_mul_f32 v[96:97], v[96:97], v[218:219]
	v_pk_mul_f32 v[90:91], v[90:91], v[220:221]
	v_pk_mul_f32 v[92:93], v[92:93], v[222:223]
	s_add_u32 s28, s20, 0x340000
	s_addc_u32 s29, s21, 0
	global_load_dwordx4 v[130:133], v253, s[28:29]
	global_load_dwordx4 v[134:137], v254, s[28:29]
	global_load_dwordx4 v[138:141], v253, s[28:29] offset:256
	global_load_dwordx4 v[142:145], v254, s[28:29] offset:256
	s_waitcnt vmcnt(12)
	v_lshlrev_b32_e32 v216, 16, v146
	v_and_b32_e32 v217, 0xffff0000, v146
	v_lshlrev_b32_e32 v218, 16, v147
	v_and_b32_e32 v219, 0xffff0000, v147
	v_lshlrev_b32_e32 v220, 16, v148
	v_and_b32_e32 v221, 0xffff0000, v148
	v_lshlrev_b32_e32 v222, 16, v149
	v_and_b32_e32 v223, 0xffff0000, v149
	v_pk_mul_f32 v[216:217], v[216:217], s[86:87] op_sel_hi:[1,0]
	v_pk_mul_f32 v[218:219], v[218:219], s[86:87] op_sel_hi:[1,0]
	v_pk_mul_f32 v[220:221], v[220:221], s[86:87] op_sel_hi:[1,0]
	v_pk_mul_f32 v[222:223], v[222:223], s[86:87] op_sel_hi:[1,0]
	v_exp_f32_e32 v216, v216
	v_exp_f32_e32 v217, v217
	v_exp_f32_e32 v218, v218
	v_exp_f32_e32 v219, v219
	v_exp_f32_e32 v220, v220
	v_exp_f32_e32 v221, v221
	v_exp_f32_e32 v222, v222
	v_exp_f32_e32 v223, v223
	v_pk_add_f32 v[216:217], v[216:217], 1.0 op_sel_hi:[1,0]
	v_pk_add_f32 v[218:219], v[218:219], 1.0 op_sel_hi:[1,0]
	v_pk_add_f32 v[220:221], v[220:221], 1.0 op_sel_hi:[1,0]
	v_pk_add_f32 v[222:223], v[222:223], 1.0 op_sel_hi:[1,0]
	v_rcp_f32_e32 v216, v216
	v_rcp_f32_e32 v217, v217
	v_rcp_f32_e32 v218, v218
	v_rcp_f32_e32 v219, v219
	v_rcp_f32_e32 v220, v220
	v_rcp_f32_e32 v221, v221
	v_rcp_f32_e32 v222, v222
	v_rcp_f32_e32 v223, v223
	v_lshlrev_b32_e32 v242, 16, v150
	v_and_b32_e32 v243, 0xffff0000, v150
	v_lshlrev_b32_e32 v244, 16, v151
	v_and_b32_e32 v245, 0xffff0000, v151
	v_lshlrev_b32_e32 v246, 16, v152
	v_and_b32_e32 v247, 0xffff0000, v152
	v_lshlrev_b32_e32 v248, 16, v153
	v_and_b32_e32 v249, 0xffff0000, v153
	v_pk_mul_f32 v[242:243], v[242:243], s[86:87] op_sel_hi:[1,0]
	v_pk_mul_f32 v[244:245], v[244:245], s[86:87] op_sel_hi:[1,0]
	v_pk_mul_f32 v[246:247], v[246:247], s[86:87] op_sel_hi:[1,0]
	v_pk_mul_f32 v[248:249], v[248:249], s[86:87] op_sel_hi:[1,0]
	v_exp_f32_e32 v242, v242
	v_exp_f32_e32 v243, v243
	v_exp_f32_e32 v244, v244
	v_exp_f32_e32 v245, v245
	v_exp_f32_e32 v246, v246
	v_exp_f32_e32 v247, v247
	v_exp_f32_e32 v248, v248
	v_exp_f32_e32 v249, v249
	v_pk_add_f32 v[242:243], v[242:243], 1.0 op_sel_hi:[1,0]
	v_pk_add_f32 v[244:245], v[244:245], 1.0 op_sel_hi:[1,0]
	v_pk_add_f32 v[246:247], v[246:247], 1.0 op_sel_hi:[1,0]
	v_pk_add_f32 v[248:249], v[248:249], 1.0 op_sel_hi:[1,0]
	v_pk_mul_f32 v[216:217], v[216:217], v[242:243]
	v_pk_mul_f32 v[218:219], v[218:219], v[244:245]
	v_pk_mul_f32 v[220:221], v[220:221], v[246:247]
	v_pk_mul_f32 v[222:223], v[222:223], v[248:249]
	v_pk_mul_f32 v[118:119], v[118:119], v[216:217]
	v_pk_mul_f32 v[120:121], v[120:121], v[218:219]
	v_pk_mul_f32 v[114:115], v[114:115], v[220:221]
	v_pk_mul_f32 v[116:117], v[116:117], v[222:223]
	v_lshlrev_b32_e32 v216, 16, v154
	v_and_b32_e32 v217, 0xffff0000, v154
	v_lshlrev_b32_e32 v218, 16, v155
	v_and_b32_e32 v219, 0xffff0000, v155
	v_lshlrev_b32_e32 v220, 16, v156
	v_and_b32_e32 v221, 0xffff0000, v156
	v_lshlrev_b32_e32 v222, 16, v157
	v_and_b32_e32 v223, 0xffff0000, v157
	v_pk_mul_f32 v[216:217], v[216:217], s[86:87] op_sel_hi:[1,0]
	v_pk_mul_f32 v[218:219], v[218:219], s[86:87] op_sel_hi:[1,0]
	v_pk_mul_f32 v[220:221], v[220:221], s[86:87] op_sel_hi:[1,0]
	v_pk_mul_f32 v[222:223], v[222:223], s[86:87] op_sel_hi:[1,0]
	v_exp_f32_e32 v216, v216
	v_exp_f32_e32 v217, v217
	v_exp_f32_e32 v218, v218
	v_exp_f32_e32 v219, v219
	v_exp_f32_e32 v220, v220
	v_exp_f32_e32 v221, v221
	v_exp_f32_e32 v222, v222
	v_exp_f32_e32 v223, v223
	v_pk_add_f32 v[216:217], v[216:217], 1.0 op_sel_hi:[1,0]
	v_pk_add_f32 v[218:219], v[218:219], 1.0 op_sel_hi:[1,0]
	v_pk_add_f32 v[220:221], v[220:221], 1.0 op_sel_hi:[1,0]
	v_pk_add_f32 v[222:223], v[222:223], 1.0 op_sel_hi:[1,0]
	v_rcp_f32_e32 v216, v216
	v_rcp_f32_e32 v217, v217
	v_rcp_f32_e32 v218, v218
	v_rcp_f32_e32 v219, v219
	v_rcp_f32_e32 v220, v220
	v_rcp_f32_e32 v221, v221
	v_rcp_f32_e32 v222, v222
	v_rcp_f32_e32 v223, v223
	v_lshlrev_b32_e32 v242, 16, v158
	v_and_b32_e32 v243, 0xffff0000, v158
	v_lshlrev_b32_e32 v244, 16, v159
	v_and_b32_e32 v245, 0xffff0000, v159
	v_lshlrev_b32_e32 v246, 16, v160
	v_and_b32_e32 v247, 0xffff0000, v160
	v_lshlrev_b32_e32 v248, 16, v161
	v_and_b32_e32 v249, 0xffff0000, v161
	v_pk_mul_f32 v[242:243], v[242:243], s[86:87] op_sel_hi:[1,0]
	v_pk_mul_f32 v[244:245], v[244:245], s[86:87] op_sel_hi:[1,0]
	v_pk_mul_f32 v[246:247], v[246:247], s[86:87] op_sel_hi:[1,0]
	v_pk_mul_f32 v[248:249], v[248:249], s[86:87] op_sel_hi:[1,0]
	v_exp_f32_e32 v242, v242
	v_exp_f32_e32 v243, v243
	v_exp_f32_e32 v244, v244
	v_exp_f32_e32 v245, v245
	v_exp_f32_e32 v246, v246
	v_exp_f32_e32 v247, v247
	v_exp_f32_e32 v248, v248
	v_exp_f32_e32 v249, v249
	v_pk_add_f32 v[242:243], v[242:243], 1.0 op_sel_hi:[1,0]
	v_pk_add_f32 v[244:245], v[244:245], 1.0 op_sel_hi:[1,0]
	v_pk_add_f32 v[246:247], v[246:247], 1.0 op_sel_hi:[1,0]
	v_pk_add_f32 v[248:249], v[248:249], 1.0 op_sel_hi:[1,0]
	v_pk_mul_f32 v[216:217], v[216:217], v[242:243]
	v_pk_mul_f32 v[218:219], v[218:219], v[244:245]
	v_pk_mul_f32 v[220:221], v[220:221], v[246:247]
	v_pk_mul_f32 v[222:223], v[222:223], v[248:249]
	v_pk_mul_f32 v[86:87], v[86:87], v[216:217]
	v_pk_mul_f32 v[88:89], v[88:89], v[218:219]
	v_pk_mul_f32 v[82:83], v[82:83], v[220:221]
	v_pk_mul_f32 v[84:85], v[84:85], v[222:223]
	s_add_u32 s28, s20, 0x3a8000
	s_addc_u32 s29, s21, 0
	global_load_dwordx4 v[146:149], v253, s[28:29]
	global_load_dwordx4 v[150:153], v254, s[28:29]
	global_load_dwordx4 v[154:157], v253, s[28:29] offset:256
	global_load_dwordx4 v[158:161], v254, s[28:29] offset:256
	s_waitcnt vmcnt(12)
	v_lshlrev_b32_e32 v216, 16, v162
	v_and_b32_e32 v217, 0xffff0000, v162
	v_lshlrev_b32_e32 v218, 16, v163
	v_and_b32_e32 v219, 0xffff0000, v163
	v_lshlrev_b32_e32 v220, 16, v164
	v_and_b32_e32 v221, 0xffff0000, v164
	v_lshlrev_b32_e32 v222, 16, v165
	v_and_b32_e32 v223, 0xffff0000, v165
	v_pk_mul_f32 v[216:217], v[216:217], s[86:87] op_sel_hi:[1,0]
	v_pk_mul_f32 v[218:219], v[218:219], s[86:87] op_sel_hi:[1,0]
	v_pk_mul_f32 v[220:221], v[220:221], s[86:87] op_sel_hi:[1,0]
	v_pk_mul_f32 v[222:223], v[222:223], s[86:87] op_sel_hi:[1,0]
	v_exp_f32_e32 v216, v216
	v_exp_f32_e32 v217, v217
	v_exp_f32_e32 v218, v218
	v_exp_f32_e32 v219, v219
	v_exp_f32_e32 v220, v220
	v_exp_f32_e32 v221, v221
	v_exp_f32_e32 v222, v222
	v_exp_f32_e32 v223, v223
	v_pk_add_f32 v[216:217], v[216:217], 1.0 op_sel_hi:[1,0]
	v_pk_add_f32 v[218:219], v[218:219], 1.0 op_sel_hi:[1,0]
	v_pk_add_f32 v[220:221], v[220:221], 1.0 op_sel_hi:[1,0]
	v_pk_add_f32 v[222:223], v[222:223], 1.0 op_sel_hi:[1,0]
	v_rcp_f32_e32 v216, v216
	v_rcp_f32_e32 v217, v217
	v_rcp_f32_e32 v218, v218
	v_rcp_f32_e32 v219, v219
	v_rcp_f32_e32 v220, v220
	v_rcp_f32_e32 v221, v221
	v_rcp_f32_e32 v222, v222
	v_rcp_f32_e32 v223, v223
	v_lshlrev_b32_e32 v242, 16, v166
	v_and_b32_e32 v243, 0xffff0000, v166
	v_lshlrev_b32_e32 v244, 16, v167
	v_and_b32_e32 v245, 0xffff0000, v167
	v_lshlrev_b32_e32 v246, 16, v168
	v_and_b32_e32 v247, 0xffff0000, v168
	v_lshlrev_b32_e32 v248, 16, v169
	v_and_b32_e32 v249, 0xffff0000, v169
	v_pk_mul_f32 v[242:243], v[242:243], s[86:87] op_sel_hi:[1,0]
	v_pk_mul_f32 v[244:245], v[244:245], s[86:87] op_sel_hi:[1,0]
	v_pk_mul_f32 v[246:247], v[246:247], s[86:87] op_sel_hi:[1,0]
	v_pk_mul_f32 v[248:249], v[248:249], s[86:87] op_sel_hi:[1,0]
	v_exp_f32_e32 v242, v242
	v_exp_f32_e32 v243, v243
	v_exp_f32_e32 v244, v244
	v_exp_f32_e32 v245, v245
	v_exp_f32_e32 v246, v246
	v_exp_f32_e32 v247, v247
	v_exp_f32_e32 v248, v248
	v_exp_f32_e32 v249, v249
	v_pk_add_f32 v[242:243], v[242:243], 1.0 op_sel_hi:[1,0]
	v_pk_add_f32 v[244:245], v[244:245], 1.0 op_sel_hi:[1,0]
	v_pk_add_f32 v[246:247], v[246:247], 1.0 op_sel_hi:[1,0]
	v_pk_add_f32 v[248:249], v[248:249], 1.0 op_sel_hi:[1,0]
	v_pk_mul_f32 v[216:217], v[216:217], v[242:243]
	v_pk_mul_f32 v[218:219], v[218:219], v[244:245]
	v_pk_mul_f32 v[220:221], v[220:221], v[246:247]
	v_pk_mul_f32 v[222:223], v[222:223], v[248:249]
	v_pk_mul_f32 v[110:111], v[110:111], v[216:217]
	v_pk_mul_f32 v[112:113], v[112:113], v[218:219]
	v_pk_mul_f32 v[106:107], v[106:107], v[220:221]
	v_pk_mul_f32 v[108:109], v[108:109], v[222:223]
	v_lshlrev_b32_e32 v216, 16, v170
	v_and_b32_e32 v217, 0xffff0000, v170
	v_lshlrev_b32_e32 v218, 16, v171
	v_and_b32_e32 v219, 0xffff0000, v171
	v_lshlrev_b32_e32 v220, 16, v172
	v_and_b32_e32 v221, 0xffff0000, v172
	v_lshlrev_b32_e32 v222, 16, v173
	v_and_b32_e32 v223, 0xffff0000, v173
	v_pk_mul_f32 v[216:217], v[216:217], s[86:87] op_sel_hi:[1,0]
	v_pk_mul_f32 v[218:219], v[218:219], s[86:87] op_sel_hi:[1,0]
	v_pk_mul_f32 v[220:221], v[220:221], s[86:87] op_sel_hi:[1,0]
	v_pk_mul_f32 v[222:223], v[222:223], s[86:87] op_sel_hi:[1,0]
	v_exp_f32_e32 v216, v216
	v_exp_f32_e32 v217, v217
	v_exp_f32_e32 v218, v218
	v_exp_f32_e32 v219, v219
	v_exp_f32_e32 v220, v220
	v_exp_f32_e32 v221, v221
	v_exp_f32_e32 v222, v222
	v_exp_f32_e32 v223, v223
	v_pk_add_f32 v[216:217], v[216:217], 1.0 op_sel_hi:[1,0]
	v_pk_add_f32 v[218:219], v[218:219], 1.0 op_sel_hi:[1,0]
	v_pk_add_f32 v[220:221], v[220:221], 1.0 op_sel_hi:[1,0]
	v_pk_add_f32 v[222:223], v[222:223], 1.0 op_sel_hi:[1,0]
	v_rcp_f32_e32 v216, v216
	v_rcp_f32_e32 v217, v217
	v_rcp_f32_e32 v218, v218
	v_rcp_f32_e32 v219, v219
	v_rcp_f32_e32 v220, v220
	v_rcp_f32_e32 v221, v221
	v_rcp_f32_e32 v222, v222
	v_rcp_f32_e32 v223, v223
	v_lshlrev_b32_e32 v242, 16, v174
	v_and_b32_e32 v243, 0xffff0000, v174
	v_lshlrev_b32_e32 v244, 16, v175
	v_and_b32_e32 v245, 0xffff0000, v175
	v_lshlrev_b32_e32 v246, 16, v176
	v_and_b32_e32 v247, 0xffff0000, v176
	v_lshlrev_b32_e32 v248, 16, v177
	v_and_b32_e32 v249, 0xffff0000, v177
	v_pk_mul_f32 v[242:243], v[242:243], s[86:87] op_sel_hi:[1,0]
	v_pk_mul_f32 v[244:245], v[244:245], s[86:87] op_sel_hi:[1,0]
	v_pk_mul_f32 v[246:247], v[246:247], s[86:87] op_sel_hi:[1,0]
	v_pk_mul_f32 v[248:249], v[248:249], s[86:87] op_sel_hi:[1,0]
	v_exp_f32_e32 v242, v242
	v_exp_f32_e32 v243, v243
	v_exp_f32_e32 v244, v244
	v_exp_f32_e32 v245, v245
	v_exp_f32_e32 v246, v246
	v_exp_f32_e32 v247, v247
	v_exp_f32_e32 v248, v248
	v_exp_f32_e32 v249, v249
	v_pk_add_f32 v[242:243], v[242:243], 1.0 op_sel_hi:[1,0]
	v_pk_add_f32 v[244:245], v[244:245], 1.0 op_sel_hi:[1,0]
	v_pk_add_f32 v[246:247], v[246:247], 1.0 op_sel_hi:[1,0]
	v_pk_add_f32 v[248:249], v[248:249], 1.0 op_sel_hi:[1,0]
	v_pk_mul_f32 v[216:217], v[216:217], v[242:243]
	v_pk_mul_f32 v[218:219], v[218:219], v[244:245]
	v_pk_mul_f32 v[220:221], v[220:221], v[246:247]
	v_pk_mul_f32 v[222:223], v[222:223], v[248:249]
	v_pk_mul_f32 v[78:79], v[78:79], v[216:217]
	v_pk_mul_f32 v[80:81], v[80:81], v[218:219]
	v_pk_mul_f32 v[74:75], v[74:75], v[220:221]
	v_pk_mul_f32 v[76:77], v[76:77], v[222:223]
	s_add_u32 s28, s20, 0x410000
	s_addc_u32 s29, s21, 0
	global_load_dwordx4 v[162:165], v253, s[28:29]
	global_load_dwordx4 v[166:169], v254, s[28:29]
	global_load_dwordx4 v[170:173], v253, s[28:29] offset:256
	global_load_dwordx4 v[174:177], v254, s[28:29] offset:256
	s_waitcnt vmcnt(12)
	v_lshlrev_b32_e32 v216, 16, v178
	v_and_b32_e32 v217, 0xffff0000, v178
	v_lshlrev_b32_e32 v218, 16, v179
	v_and_b32_e32 v219, 0xffff0000, v179
	v_lshlrev_b32_e32 v220, 16, v180
	v_and_b32_e32 v221, 0xffff0000, v180
	v_lshlrev_b32_e32 v222, 16, v181
	v_and_b32_e32 v223, 0xffff0000, v181
	v_pk_mul_f32 v[216:217], v[216:217], s[86:87] op_sel_hi:[1,0]
	v_pk_mul_f32 v[218:219], v[218:219], s[86:87] op_sel_hi:[1,0]
	v_pk_mul_f32 v[220:221], v[220:221], s[86:87] op_sel_hi:[1,0]
	v_pk_mul_f32 v[222:223], v[222:223], s[86:87] op_sel_hi:[1,0]
	v_exp_f32_e32 v216, v216
	v_exp_f32_e32 v217, v217
	v_exp_f32_e32 v218, v218
	v_exp_f32_e32 v219, v219
	v_exp_f32_e32 v220, v220
	v_exp_f32_e32 v221, v221
	v_exp_f32_e32 v222, v222
	v_exp_f32_e32 v223, v223
	v_pk_add_f32 v[216:217], v[216:217], 1.0 op_sel_hi:[1,0]
	v_pk_add_f32 v[218:219], v[218:219], 1.0 op_sel_hi:[1,0]
	v_pk_add_f32 v[220:221], v[220:221], 1.0 op_sel_hi:[1,0]
	v_pk_add_f32 v[222:223], v[222:223], 1.0 op_sel_hi:[1,0]
	v_rcp_f32_e32 v216, v216
	v_rcp_f32_e32 v217, v217
	v_rcp_f32_e32 v218, v218
	v_rcp_f32_e32 v219, v219
	v_rcp_f32_e32 v220, v220
	v_rcp_f32_e32 v221, v221
	v_rcp_f32_e32 v222, v222
	v_rcp_f32_e32 v223, v223
	v_lshlrev_b32_e32 v242, 16, v182
	v_and_b32_e32 v243, 0xffff0000, v182
	v_lshlrev_b32_e32 v244, 16, v183
	v_and_b32_e32 v245, 0xffff0000, v183
	v_lshlrev_b32_e32 v246, 16, v184
	v_and_b32_e32 v247, 0xffff0000, v184
	v_lshlrev_b32_e32 v248, 16, v185
	v_and_b32_e32 v249, 0xffff0000, v185
	v_pk_mul_f32 v[242:243], v[242:243], s[86:87] op_sel_hi:[1,0]
	v_pk_mul_f32 v[244:245], v[244:245], s[86:87] op_sel_hi:[1,0]
	v_pk_mul_f32 v[246:247], v[246:247], s[86:87] op_sel_hi:[1,0]
	v_pk_mul_f32 v[248:249], v[248:249], s[86:87] op_sel_hi:[1,0]
	v_exp_f32_e32 v242, v242
	v_exp_f32_e32 v243, v243
	v_exp_f32_e32 v244, v244
	v_exp_f32_e32 v245, v245
	v_exp_f32_e32 v246, v246
	v_exp_f32_e32 v247, v247
	v_exp_f32_e32 v248, v248
	v_exp_f32_e32 v249, v249
	v_pk_add_f32 v[242:243], v[242:243], 1.0 op_sel_hi:[1,0]
	v_pk_add_f32 v[244:245], v[244:245], 1.0 op_sel_hi:[1,0]
	v_pk_add_f32 v[246:247], v[246:247], 1.0 op_sel_hi:[1,0]
	v_pk_add_f32 v[248:249], v[248:249], 1.0 op_sel_hi:[1,0]
	v_pk_mul_f32 v[216:217], v[216:217], v[242:243]
	v_pk_mul_f32 v[218:219], v[218:219], v[244:245]
	v_pk_mul_f32 v[220:221], v[220:221], v[246:247]
	v_pk_mul_f32 v[222:223], v[222:223], v[248:249]
	v_pk_mul_f32 v[102:103], v[102:103], v[216:217]
	v_pk_mul_f32 v[104:105], v[104:105], v[218:219]
	v_pk_mul_f32 v[98:99], v[98:99], v[220:221]
	v_pk_mul_f32 v[100:101], v[100:101], v[222:223]
	v_lshlrev_b32_e32 v216, 16, v186
	v_and_b32_e32 v217, 0xffff0000, v186
	v_lshlrev_b32_e32 v218, 16, v187
	v_and_b32_e32 v219, 0xffff0000, v187
	v_lshlrev_b32_e32 v220, 16, v188
	v_and_b32_e32 v221, 0xffff0000, v188
	v_lshlrev_b32_e32 v222, 16, v189
	v_and_b32_e32 v223, 0xffff0000, v189
	v_pk_mul_f32 v[216:217], v[216:217], s[86:87] op_sel_hi:[1,0]
	v_pk_mul_f32 v[218:219], v[218:219], s[86:87] op_sel_hi:[1,0]
	v_pk_mul_f32 v[220:221], v[220:221], s[86:87] op_sel_hi:[1,0]
	v_pk_mul_f32 v[222:223], v[222:223], s[86:87] op_sel_hi:[1,0]
	v_exp_f32_e32 v216, v216
	v_exp_f32_e32 v217, v217
	v_exp_f32_e32 v218, v218
	v_exp_f32_e32 v219, v219
	v_exp_f32_e32 v220, v220
	v_exp_f32_e32 v221, v221
	v_exp_f32_e32 v222, v222
	v_exp_f32_e32 v223, v223
	v_pk_add_f32 v[216:217], v[216:217], 1.0 op_sel_hi:[1,0]
	v_pk_add_f32 v[218:219], v[218:219], 1.0 op_sel_hi:[1,0]
	v_pk_add_f32 v[220:221], v[220:221], 1.0 op_sel_hi:[1,0]
	v_pk_add_f32 v[222:223], v[222:223], 1.0 op_sel_hi:[1,0]
	v_rcp_f32_e32 v216, v216
	v_rcp_f32_e32 v217, v217
	v_rcp_f32_e32 v218, v218
	v_rcp_f32_e32 v219, v219
	v_rcp_f32_e32 v220, v220
	v_rcp_f32_e32 v221, v221
	v_rcp_f32_e32 v222, v222
	v_rcp_f32_e32 v223, v223
	v_lshlrev_b32_e32 v242, 16, v190
	v_and_b32_e32 v243, 0xffff0000, v190
	v_lshlrev_b32_e32 v244, 16, v191
	v_and_b32_e32 v245, 0xffff0000, v191
	v_lshlrev_b32_e32 v246, 16, v192
	v_and_b32_e32 v247, 0xffff0000, v192
	v_lshlrev_b32_e32 v248, 16, v193
	v_and_b32_e32 v249, 0xffff0000, v193
	v_pk_mul_f32 v[242:243], v[242:243], s[86:87] op_sel_hi:[1,0]
	v_pk_mul_f32 v[244:245], v[244:245], s[86:87] op_sel_hi:[1,0]
	v_pk_mul_f32 v[246:247], v[246:247], s[86:87] op_sel_hi:[1,0]
	v_pk_mul_f32 v[248:249], v[248:249], s[86:87] op_sel_hi:[1,0]
	v_exp_f32_e32 v242, v242
	v_exp_f32_e32 v243, v243
	v_exp_f32_e32 v244, v244
	v_exp_f32_e32 v245, v245
	v_exp_f32_e32 v246, v246
	v_exp_f32_e32 v247, v247
	v_exp_f32_e32 v248, v248
	v_exp_f32_e32 v249, v249
	v_pk_add_f32 v[242:243], v[242:243], 1.0 op_sel_hi:[1,0]
	v_pk_add_f32 v[244:245], v[244:245], 1.0 op_sel_hi:[1,0]
	v_pk_add_f32 v[246:247], v[246:247], 1.0 op_sel_hi:[1,0]
	v_pk_add_f32 v[248:249], v[248:249], 1.0 op_sel_hi:[1,0]
	v_pk_mul_f32 v[216:217], v[216:217], v[242:243]
	v_pk_mul_f32 v[218:219], v[218:219], v[244:245]
	v_pk_mul_f32 v[220:221], v[220:221], v[246:247]
	v_pk_mul_f32 v[222:223], v[222:223], v[248:249]
	v_pk_mul_f32 v[70:71], v[70:71], v[216:217]
	v_pk_mul_f32 v[72:73], v[72:73], v[218:219]
	v_pk_mul_f32 v[66:67], v[66:67], v[220:221]
	v_pk_mul_f32 v[68:69], v[68:69], v[222:223]
	s_add_u32 s28, s20, 0x478000
	s_addc_u32 s29, s21, 0
	global_load_dwordx4 v[178:181], v253, s[28:29]
	global_load_dwordx4 v[182:185], v254, s[28:29]
	global_load_dwordx4 v[186:189], v253, s[28:29] offset:256
	global_load_dwordx4 v[190:193], v254, s[28:29] offset:256
	s_waitcnt vmcnt(12)
	v_lshlrev_b32_e32 v216, 16, v130
	v_and_b32_e32 v217, 0xffff0000, v130
	v_lshlrev_b32_e32 v218, 16, v131
	v_and_b32_e32 v219, 0xffff0000, v131
	v_lshlrev_b32_e32 v220, 16, v132
	v_and_b32_e32 v221, 0xffff0000, v132
	v_lshlrev_b32_e32 v222, 16, v133
	v_and_b32_e32 v223, 0xffff0000, v133
	v_pk_mul_f32 v[216:217], v[216:217], s[86:87] op_sel_hi:[1,0]
	v_pk_mul_f32 v[218:219], v[218:219], s[86:87] op_sel_hi:[1,0]
	v_pk_mul_f32 v[220:221], v[220:221], s[86:87] op_sel_hi:[1,0]
	v_pk_mul_f32 v[222:223], v[222:223], s[86:87] op_sel_hi:[1,0]
	v_exp_f32_e32 v216, v216
	v_exp_f32_e32 v217, v217
	v_exp_f32_e32 v218, v218
	v_exp_f32_e32 v219, v219
	v_exp_f32_e32 v220, v220
	v_exp_f32_e32 v221, v221
	v_exp_f32_e32 v222, v222
	v_exp_f32_e32 v223, v223
	v_pk_add_f32 v[216:217], v[216:217], 1.0 op_sel_hi:[1,0]
	v_pk_add_f32 v[218:219], v[218:219], 1.0 op_sel_hi:[1,0]
	v_pk_add_f32 v[220:221], v[220:221], 1.0 op_sel_hi:[1,0]
	v_pk_add_f32 v[222:223], v[222:223], 1.0 op_sel_hi:[1,0]
	v_rcp_f32_e32 v216, v216
	v_rcp_f32_e32 v217, v217
	v_rcp_f32_e32 v218, v218
	v_rcp_f32_e32 v219, v219
	v_rcp_f32_e32 v220, v220
	v_rcp_f32_e32 v221, v221
	v_rcp_f32_e32 v222, v222
	v_rcp_f32_e32 v223, v223
	v_lshlrev_b32_e32 v242, 16, v134
	v_and_b32_e32 v243, 0xffff0000, v134
	v_lshlrev_b32_e32 v244, 16, v135
	v_and_b32_e32 v245, 0xffff0000, v135
	v_lshlrev_b32_e32 v246, 16, v136
	v_and_b32_e32 v247, 0xffff0000, v136
	v_lshlrev_b32_e32 v248, 16, v137
	v_and_b32_e32 v249, 0xffff0000, v137
	v_pk_mul_f32 v[242:243], v[242:243], s[86:87] op_sel_hi:[1,0]
	v_pk_mul_f32 v[244:245], v[244:245], s[86:87] op_sel_hi:[1,0]
	v_pk_mul_f32 v[246:247], v[246:247], s[86:87] op_sel_hi:[1,0]
	v_pk_mul_f32 v[248:249], v[248:249], s[86:87] op_sel_hi:[1,0]
	v_exp_f32_e32 v242, v242
	v_exp_f32_e32 v243, v243
	v_exp_f32_e32 v244, v244
	v_exp_f32_e32 v245, v245
	v_exp_f32_e32 v246, v246
	v_exp_f32_e32 v247, v247
	v_exp_f32_e32 v248, v248
	v_exp_f32_e32 v249, v249
	v_pk_add_f32 v[242:243], v[242:243], 1.0 op_sel_hi:[1,0]
	v_pk_add_f32 v[244:245], v[244:245], 1.0 op_sel_hi:[1,0]
	v_pk_add_f32 v[246:247], v[246:247], 1.0 op_sel_hi:[1,0]
	v_pk_add_f32 v[248:249], v[248:249], 1.0 op_sel_hi:[1,0]
	v_pk_mul_f32 v[216:217], v[216:217], v[242:243]
	v_pk_mul_f32 v[218:219], v[218:219], v[244:245]
	v_pk_mul_f32 v[220:221], v[220:221], v[246:247]
	v_pk_mul_f32 v[222:223], v[222:223], v[248:249]
	v_pk_mul_f32 v[62:63], v[62:63], v[216:217]
	v_pk_mul_f32 v[64:65], v[64:65], v[218:219]
	v_pk_mul_f32 v[58:59], v[58:59], v[220:221]
	v_pk_mul_f32 v[60:61], v[60:61], v[222:223]
	v_lshlrev_b32_e32 v216, 16, v138
	v_and_b32_e32 v217, 0xffff0000, v138
	v_lshlrev_b32_e32 v218, 16, v139
	v_and_b32_e32 v219, 0xffff0000, v139
	v_lshlrev_b32_e32 v220, 16, v140
	v_and_b32_e32 v221, 0xffff0000, v140
	v_lshlrev_b32_e32 v222, 16, v141
	v_and_b32_e32 v223, 0xffff0000, v141
	v_pk_mul_f32 v[216:217], v[216:217], s[86:87] op_sel_hi:[1,0]
	v_pk_mul_f32 v[218:219], v[218:219], s[86:87] op_sel_hi:[1,0]
	v_pk_mul_f32 v[220:221], v[220:221], s[86:87] op_sel_hi:[1,0]
	v_pk_mul_f32 v[222:223], v[222:223], s[86:87] op_sel_hi:[1,0]
	v_exp_f32_e32 v216, v216
	v_exp_f32_e32 v217, v217
	v_exp_f32_e32 v218, v218
	v_exp_f32_e32 v219, v219
	v_exp_f32_e32 v220, v220
	v_exp_f32_e32 v221, v221
	v_exp_f32_e32 v222, v222
	v_exp_f32_e32 v223, v223
	v_pk_add_f32 v[216:217], v[216:217], 1.0 op_sel_hi:[1,0]
	v_pk_add_f32 v[218:219], v[218:219], 1.0 op_sel_hi:[1,0]
	v_pk_add_f32 v[220:221], v[220:221], 1.0 op_sel_hi:[1,0]
	v_pk_add_f32 v[222:223], v[222:223], 1.0 op_sel_hi:[1,0]
	v_rcp_f32_e32 v216, v216
	v_rcp_f32_e32 v217, v217
	v_rcp_f32_e32 v218, v218
	v_rcp_f32_e32 v219, v219
	v_rcp_f32_e32 v220, v220
	v_rcp_f32_e32 v221, v221
	v_rcp_f32_e32 v222, v222
	v_rcp_f32_e32 v223, v223
	v_lshlrev_b32_e32 v242, 16, v142
	v_and_b32_e32 v243, 0xffff0000, v142
	v_lshlrev_b32_e32 v244, 16, v143
	v_and_b32_e32 v245, 0xffff0000, v143
	v_lshlrev_b32_e32 v246, 16, v144
	v_and_b32_e32 v247, 0xffff0000, v144
	v_lshlrev_b32_e32 v248, 16, v145
	v_and_b32_e32 v249, 0xffff0000, v145
	v_pk_mul_f32 v[242:243], v[242:243], s[86:87] op_sel_hi:[1,0]
	v_pk_mul_f32 v[244:245], v[244:245], s[86:87] op_sel_hi:[1,0]
	v_pk_mul_f32 v[246:247], v[246:247], s[86:87] op_sel_hi:[1,0]
	v_pk_mul_f32 v[248:249], v[248:249], s[86:87] op_sel_hi:[1,0]
	v_exp_f32_e32 v242, v242
	v_exp_f32_e32 v243, v243
	v_exp_f32_e32 v244, v244
	v_exp_f32_e32 v245, v245
	v_exp_f32_e32 v246, v246
	v_exp_f32_e32 v247, v247
	v_exp_f32_e32 v248, v248
	v_exp_f32_e32 v249, v249
	v_pk_add_f32 v[242:243], v[242:243], 1.0 op_sel_hi:[1,0]
	v_pk_add_f32 v[244:245], v[244:245], 1.0 op_sel_hi:[1,0]
	v_pk_add_f32 v[246:247], v[246:247], 1.0 op_sel_hi:[1,0]
	v_pk_add_f32 v[248:249], v[248:249], 1.0 op_sel_hi:[1,0]
	v_pk_mul_f32 v[216:217], v[216:217], v[242:243]
	v_pk_mul_f32 v[218:219], v[218:219], v[244:245]
	v_pk_mul_f32 v[220:221], v[220:221], v[246:247]
	v_pk_mul_f32 v[222:223], v[222:223], v[248:249]
	v_pk_mul_f32 v[30:31], v[30:31], v[216:217]
	v_pk_mul_f32 v[32:33], v[32:33], v[218:219]
	v_pk_mul_f32 v[26:27], v[26:27], v[220:221]
	v_pk_mul_f32 v[28:29], v[28:29], v[222:223]
	s_waitcnt vmcnt(8)
	v_lshlrev_b32_e32 v216, 16, v146
	v_and_b32_e32 v217, 0xffff0000, v146
	v_lshlrev_b32_e32 v218, 16, v147
	v_and_b32_e32 v219, 0xffff0000, v147
	v_lshlrev_b32_e32 v220, 16, v148
	v_and_b32_e32 v221, 0xffff0000, v148
	v_lshlrev_b32_e32 v222, 16, v149
	v_and_b32_e32 v223, 0xffff0000, v149
	v_pk_mul_f32 v[216:217], v[216:217], s[86:87] op_sel_hi:[1,0]
	v_pk_mul_f32 v[218:219], v[218:219], s[86:87] op_sel_hi:[1,0]
	v_pk_mul_f32 v[220:221], v[220:221], s[86:87] op_sel_hi:[1,0]
	v_pk_mul_f32 v[222:223], v[222:223], s[86:87] op_sel_hi:[1,0]
	v_exp_f32_e32 v216, v216
	v_exp_f32_e32 v217, v217
	v_exp_f32_e32 v218, v218
	v_exp_f32_e32 v219, v219
	v_exp_f32_e32 v220, v220
	v_exp_f32_e32 v221, v221
	v_exp_f32_e32 v222, v222
	v_exp_f32_e32 v223, v223
	v_pk_add_f32 v[216:217], v[216:217], 1.0 op_sel_hi:[1,0]
	v_pk_add_f32 v[218:219], v[218:219], 1.0 op_sel_hi:[1,0]
	v_pk_add_f32 v[220:221], v[220:221], 1.0 op_sel_hi:[1,0]
	v_pk_add_f32 v[222:223], v[222:223], 1.0 op_sel_hi:[1,0]
	v_rcp_f32_e32 v216, v216
	v_rcp_f32_e32 v217, v217
	v_rcp_f32_e32 v218, v218
	v_rcp_f32_e32 v219, v219
	v_rcp_f32_e32 v220, v220
	v_rcp_f32_e32 v221, v221
	v_rcp_f32_e32 v222, v222
	v_rcp_f32_e32 v223, v223
	v_lshlrev_b32_e32 v242, 16, v150
	v_and_b32_e32 v243, 0xffff0000, v150
	v_lshlrev_b32_e32 v244, 16, v151
	v_and_b32_e32 v245, 0xffff0000, v151
	v_lshlrev_b32_e32 v246, 16, v152
	v_and_b32_e32 v247, 0xffff0000, v152
	v_lshlrev_b32_e32 v248, 16, v153
	v_and_b32_e32 v249, 0xffff0000, v153
	v_pk_mul_f32 v[242:243], v[242:243], s[86:87] op_sel_hi:[1,0]
	v_pk_mul_f32 v[244:245], v[244:245], s[86:87] op_sel_hi:[1,0]
	v_pk_mul_f32 v[246:247], v[246:247], s[86:87] op_sel_hi:[1,0]
	v_pk_mul_f32 v[248:249], v[248:249], s[86:87] op_sel_hi:[1,0]
	v_exp_f32_e32 v242, v242
	v_exp_f32_e32 v243, v243
	v_exp_f32_e32 v244, v244
	v_exp_f32_e32 v245, v245
	v_exp_f32_e32 v246, v246
	v_exp_f32_e32 v247, v247
	v_exp_f32_e32 v248, v248
	v_exp_f32_e32 v249, v249
	v_pk_add_f32 v[242:243], v[242:243], 1.0 op_sel_hi:[1,0]
	v_pk_add_f32 v[244:245], v[244:245], 1.0 op_sel_hi:[1,0]
	v_pk_add_f32 v[246:247], v[246:247], 1.0 op_sel_hi:[1,0]
	v_pk_add_f32 v[248:249], v[248:249], 1.0 op_sel_hi:[1,0]
	v_pk_mul_f32 v[216:217], v[216:217], v[242:243]
	v_pk_mul_f32 v[218:219], v[218:219], v[244:245]
	v_pk_mul_f32 v[220:221], v[220:221], v[246:247]
	v_pk_mul_f32 v[222:223], v[222:223], v[248:249]
	v_pk_mul_f32 v[54:55], v[54:55], v[216:217]
	v_pk_mul_f32 v[56:57], v[56:57], v[218:219]
	v_pk_mul_f32 v[50:51], v[50:51], v[220:221]
	v_pk_mul_f32 v[52:53], v[52:53], v[222:223]
	v_lshlrev_b32_e32 v216, 16, v154
	v_and_b32_e32 v217, 0xffff0000, v154
	v_lshlrev_b32_e32 v218, 16, v155
	v_and_b32_e32 v219, 0xffff0000, v155
	v_lshlrev_b32_e32 v220, 16, v156
	v_and_b32_e32 v221, 0xffff0000, v156
	v_lshlrev_b32_e32 v222, 16, v157
	v_and_b32_e32 v223, 0xffff0000, v157
	v_pk_mul_f32 v[216:217], v[216:217], s[86:87] op_sel_hi:[1,0]
	v_pk_mul_f32 v[218:219], v[218:219], s[86:87] op_sel_hi:[1,0]
	v_pk_mul_f32 v[220:221], v[220:221], s[86:87] op_sel_hi:[1,0]
	v_pk_mul_f32 v[222:223], v[222:223], s[86:87] op_sel_hi:[1,0]
	v_exp_f32_e32 v216, v216
	v_exp_f32_e32 v217, v217
	v_exp_f32_e32 v218, v218
	v_exp_f32_e32 v219, v219
	v_exp_f32_e32 v220, v220
	v_exp_f32_e32 v221, v221
	v_exp_f32_e32 v222, v222
	v_exp_f32_e32 v223, v223
	v_pk_add_f32 v[216:217], v[216:217], 1.0 op_sel_hi:[1,0]
	v_pk_add_f32 v[218:219], v[218:219], 1.0 op_sel_hi:[1,0]
	v_pk_add_f32 v[220:221], v[220:221], 1.0 op_sel_hi:[1,0]
	v_pk_add_f32 v[222:223], v[222:223], 1.0 op_sel_hi:[1,0]
	v_rcp_f32_e32 v216, v216
	v_rcp_f32_e32 v217, v217
	v_rcp_f32_e32 v218, v218
	v_rcp_f32_e32 v219, v219
	v_rcp_f32_e32 v220, v220
	v_rcp_f32_e32 v221, v221
	v_rcp_f32_e32 v222, v222
	v_rcp_f32_e32 v223, v223
	v_lshlrev_b32_e32 v242, 16, v158
	v_and_b32_e32 v243, 0xffff0000, v158
	v_lshlrev_b32_e32 v244, 16, v159
	v_and_b32_e32 v245, 0xffff0000, v159
	v_lshlrev_b32_e32 v246, 16, v160
	v_and_b32_e32 v247, 0xffff0000, v160
	v_lshlrev_b32_e32 v248, 16, v161
	v_and_b32_e32 v249, 0xffff0000, v161
	v_pk_mul_f32 v[242:243], v[242:243], s[86:87] op_sel_hi:[1,0]
	v_pk_mul_f32 v[244:245], v[244:245], s[86:87] op_sel_hi:[1,0]
	v_pk_mul_f32 v[246:247], v[246:247], s[86:87] op_sel_hi:[1,0]
	v_pk_mul_f32 v[248:249], v[248:249], s[86:87] op_sel_hi:[1,0]
	v_exp_f32_e32 v242, v242
	v_exp_f32_e32 v243, v243
	v_exp_f32_e32 v244, v244
	v_exp_f32_e32 v245, v245
	v_exp_f32_e32 v246, v246
	v_exp_f32_e32 v247, v247
	v_exp_f32_e32 v248, v248
	v_exp_f32_e32 v249, v249
	v_pk_add_f32 v[242:243], v[242:243], 1.0 op_sel_hi:[1,0]
	v_pk_add_f32 v[244:245], v[244:245], 1.0 op_sel_hi:[1,0]
	v_pk_add_f32 v[246:247], v[246:247], 1.0 op_sel_hi:[1,0]
	v_pk_add_f32 v[248:249], v[248:249], 1.0 op_sel_hi:[1,0]
	v_pk_mul_f32 v[216:217], v[216:217], v[242:243]
	v_pk_mul_f32 v[218:219], v[218:219], v[244:245]
	v_pk_mul_f32 v[220:221], v[220:221], v[246:247]
	v_pk_mul_f32 v[222:223], v[222:223], v[248:249]
	v_pk_mul_f32 v[22:23], v[22:23], v[216:217]
	v_pk_mul_f32 v[24:25], v[24:25], v[218:219]
	v_pk_mul_f32 v[18:19], v[18:19], v[220:221]
	v_pk_mul_f32 v[20:21], v[20:21], v[222:223]
	s_waitcnt vmcnt(4)
	v_lshlrev_b32_e32 v216, 16, v162
	v_and_b32_e32 v217, 0xffff0000, v162
	v_lshlrev_b32_e32 v218, 16, v163
	v_and_b32_e32 v219, 0xffff0000, v163
	v_lshlrev_b32_e32 v220, 16, v164
	v_and_b32_e32 v221, 0xffff0000, v164
	v_lshlrev_b32_e32 v222, 16, v165
	v_and_b32_e32 v223, 0xffff0000, v165
	v_pk_mul_f32 v[216:217], v[216:217], s[86:87] op_sel_hi:[1,0]
	v_pk_mul_f32 v[218:219], v[218:219], s[86:87] op_sel_hi:[1,0]
	v_pk_mul_f32 v[220:221], v[220:221], s[86:87] op_sel_hi:[1,0]
	v_pk_mul_f32 v[222:223], v[222:223], s[86:87] op_sel_hi:[1,0]
	v_exp_f32_e32 v216, v216
	v_exp_f32_e32 v217, v217
	v_exp_f32_e32 v218, v218
	v_exp_f32_e32 v219, v219
	v_exp_f32_e32 v220, v220
	v_exp_f32_e32 v221, v221
	v_exp_f32_e32 v222, v222
	v_exp_f32_e32 v223, v223
	v_pk_add_f32 v[216:217], v[216:217], 1.0 op_sel_hi:[1,0]
	v_pk_add_f32 v[218:219], v[218:219], 1.0 op_sel_hi:[1,0]
	v_pk_add_f32 v[220:221], v[220:221], 1.0 op_sel_hi:[1,0]
	v_pk_add_f32 v[222:223], v[222:223], 1.0 op_sel_hi:[1,0]
	v_rcp_f32_e32 v216, v216
	v_rcp_f32_e32 v217, v217
	v_rcp_f32_e32 v218, v218
	v_rcp_f32_e32 v219, v219
	v_rcp_f32_e32 v220, v220
	v_rcp_f32_e32 v221, v221
	v_rcp_f32_e32 v222, v222
	v_rcp_f32_e32 v223, v223
	v_lshlrev_b32_e32 v242, 16, v166
	v_and_b32_e32 v243, 0xffff0000, v166
	v_lshlrev_b32_e32 v244, 16, v167
	v_and_b32_e32 v245, 0xffff0000, v167
	v_lshlrev_b32_e32 v246, 16, v168
	v_and_b32_e32 v247, 0xffff0000, v168
	v_lshlrev_b32_e32 v248, 16, v169
	v_and_b32_e32 v249, 0xffff0000, v169
	v_pk_mul_f32 v[242:243], v[242:243], s[86:87] op_sel_hi:[1,0]
	v_pk_mul_f32 v[244:245], v[244:245], s[86:87] op_sel_hi:[1,0]
	v_pk_mul_f32 v[246:247], v[246:247], s[86:87] op_sel_hi:[1,0]
	v_pk_mul_f32 v[248:249], v[248:249], s[86:87] op_sel_hi:[1,0]
	v_exp_f32_e32 v242, v242
	v_exp_f32_e32 v243, v243
	v_exp_f32_e32 v244, v244
	v_exp_f32_e32 v245, v245
	v_exp_f32_e32 v246, v246
	v_exp_f32_e32 v247, v247
	v_exp_f32_e32 v248, v248
	v_exp_f32_e32 v249, v249
	v_pk_add_f32 v[242:243], v[242:243], 1.0 op_sel_hi:[1,0]
	v_pk_add_f32 v[244:245], v[244:245], 1.0 op_sel_hi:[1,0]
	v_pk_add_f32 v[246:247], v[246:247], 1.0 op_sel_hi:[1,0]
	v_pk_add_f32 v[248:249], v[248:249], 1.0 op_sel_hi:[1,0]
	v_pk_mul_f32 v[216:217], v[216:217], v[242:243]
	v_pk_mul_f32 v[218:219], v[218:219], v[244:245]
	v_pk_mul_f32 v[220:221], v[220:221], v[246:247]
	v_pk_mul_f32 v[222:223], v[222:223], v[248:249]
	v_pk_mul_f32 v[46:47], v[46:47], v[216:217]
	v_pk_mul_f32 v[48:49], v[48:49], v[218:219]
	v_pk_mul_f32 v[42:43], v[42:43], v[220:221]
	v_pk_mul_f32 v[44:45], v[44:45], v[222:223]
	v_lshlrev_b32_e32 v216, 16, v170
	v_and_b32_e32 v217, 0xffff0000, v170
	v_lshlrev_b32_e32 v218, 16, v171
	v_and_b32_e32 v219, 0xffff0000, v171
	v_lshlrev_b32_e32 v220, 16, v172
	v_and_b32_e32 v221, 0xffff0000, v172
	v_lshlrev_b32_e32 v222, 16, v173
	v_and_b32_e32 v223, 0xffff0000, v173
	v_pk_mul_f32 v[216:217], v[216:217], s[86:87] op_sel_hi:[1,0]
	v_pk_mul_f32 v[218:219], v[218:219], s[86:87] op_sel_hi:[1,0]
	v_pk_mul_f32 v[220:221], v[220:221], s[86:87] op_sel_hi:[1,0]
	v_pk_mul_f32 v[222:223], v[222:223], s[86:87] op_sel_hi:[1,0]
	v_exp_f32_e32 v216, v216
	v_exp_f32_e32 v217, v217
	v_exp_f32_e32 v218, v218
	v_exp_f32_e32 v219, v219
	v_exp_f32_e32 v220, v220
	v_exp_f32_e32 v221, v221
	v_exp_f32_e32 v222, v222
	v_exp_f32_e32 v223, v223
	v_pk_add_f32 v[216:217], v[216:217], 1.0 op_sel_hi:[1,0]
	v_pk_add_f32 v[218:219], v[218:219], 1.0 op_sel_hi:[1,0]
	v_pk_add_f32 v[220:221], v[220:221], 1.0 op_sel_hi:[1,0]
	v_pk_add_f32 v[222:223], v[222:223], 1.0 op_sel_hi:[1,0]
	v_rcp_f32_e32 v216, v216
	v_rcp_f32_e32 v217, v217
	v_rcp_f32_e32 v218, v218
	v_rcp_f32_e32 v219, v219
	v_rcp_f32_e32 v220, v220
	v_rcp_f32_e32 v221, v221
	v_rcp_f32_e32 v222, v222
	v_rcp_f32_e32 v223, v223
	v_lshlrev_b32_e32 v242, 16, v174
	v_and_b32_e32 v243, 0xffff0000, v174
	v_lshlrev_b32_e32 v244, 16, v175
	v_and_b32_e32 v245, 0xffff0000, v175
	v_lshlrev_b32_e32 v246, 16, v176
	v_and_b32_e32 v247, 0xffff0000, v176
	v_lshlrev_b32_e32 v248, 16, v177
	v_and_b32_e32 v249, 0xffff0000, v177
	v_pk_mul_f32 v[242:243], v[242:243], s[86:87] op_sel_hi:[1,0]
	v_pk_mul_f32 v[244:245], v[244:245], s[86:87] op_sel_hi:[1,0]
	v_pk_mul_f32 v[246:247], v[246:247], s[86:87] op_sel_hi:[1,0]
	v_pk_mul_f32 v[248:249], v[248:249], s[86:87] op_sel_hi:[1,0]
	v_exp_f32_e32 v242, v242
	v_exp_f32_e32 v243, v243
	v_exp_f32_e32 v244, v244
	v_exp_f32_e32 v245, v245
	v_exp_f32_e32 v246, v246
	v_exp_f32_e32 v247, v247
	v_exp_f32_e32 v248, v248
	v_exp_f32_e32 v249, v249
	v_pk_add_f32 v[242:243], v[242:243], 1.0 op_sel_hi:[1,0]
	v_pk_add_f32 v[244:245], v[244:245], 1.0 op_sel_hi:[1,0]
	v_pk_add_f32 v[246:247], v[246:247], 1.0 op_sel_hi:[1,0]
	v_pk_add_f32 v[248:249], v[248:249], 1.0 op_sel_hi:[1,0]
	v_pk_mul_f32 v[216:217], v[216:217], v[242:243]
	v_pk_mul_f32 v[218:219], v[218:219], v[244:245]
	v_pk_mul_f32 v[220:221], v[220:221], v[246:247]
	v_pk_mul_f32 v[222:223], v[222:223], v[248:249]
	v_pk_mul_f32 v[14:15], v[14:15], v[216:217]
	v_pk_mul_f32 v[16:17], v[16:17], v[218:219]
	v_pk_mul_f32 v[10:11], v[10:11], v[220:221]
	v_pk_mul_f32 v[12:13], v[12:13], v[222:223]
	s_waitcnt vmcnt(0)
	v_lshlrev_b32_e32 v216, 16, v178
	v_and_b32_e32 v217, 0xffff0000, v178
	v_lshlrev_b32_e32 v218, 16, v179
	v_and_b32_e32 v219, 0xffff0000, v179
	v_lshlrev_b32_e32 v220, 16, v180
	v_and_b32_e32 v221, 0xffff0000, v180
	v_lshlrev_b32_e32 v222, 16, v181
	v_and_b32_e32 v223, 0xffff0000, v181
	v_pk_mul_f32 v[216:217], v[216:217], s[86:87] op_sel_hi:[1,0]
	v_pk_mul_f32 v[218:219], v[218:219], s[86:87] op_sel_hi:[1,0]
	v_pk_mul_f32 v[220:221], v[220:221], s[86:87] op_sel_hi:[1,0]
	v_pk_mul_f32 v[222:223], v[222:223], s[86:87] op_sel_hi:[1,0]
	v_exp_f32_e32 v216, v216
	v_exp_f32_e32 v217, v217
	v_exp_f32_e32 v218, v218
	v_exp_f32_e32 v219, v219
	v_exp_f32_e32 v220, v220
	v_exp_f32_e32 v221, v221
	v_exp_f32_e32 v222, v222
	v_exp_f32_e32 v223, v223
	v_pk_add_f32 v[216:217], v[216:217], 1.0 op_sel_hi:[1,0]
	v_pk_add_f32 v[218:219], v[218:219], 1.0 op_sel_hi:[1,0]
	v_pk_add_f32 v[220:221], v[220:221], 1.0 op_sel_hi:[1,0]
	v_pk_add_f32 v[222:223], v[222:223], 1.0 op_sel_hi:[1,0]
	v_rcp_f32_e32 v216, v216
	v_rcp_f32_e32 v217, v217
	v_rcp_f32_e32 v218, v218
	v_rcp_f32_e32 v219, v219
	v_rcp_f32_e32 v220, v220
	v_rcp_f32_e32 v221, v221
	v_rcp_f32_e32 v222, v222
	v_rcp_f32_e32 v223, v223
	v_lshlrev_b32_e32 v242, 16, v182
	v_and_b32_e32 v243, 0xffff0000, v182
	v_lshlrev_b32_e32 v244, 16, v183
	v_and_b32_e32 v245, 0xffff0000, v183
	v_lshlrev_b32_e32 v246, 16, v184
	v_and_b32_e32 v247, 0xffff0000, v184
	v_lshlrev_b32_e32 v248, 16, v185
	v_and_b32_e32 v249, 0xffff0000, v185
	v_pk_mul_f32 v[242:243], v[242:243], s[86:87] op_sel_hi:[1,0]
	v_pk_mul_f32 v[244:245], v[244:245], s[86:87] op_sel_hi:[1,0]
	v_pk_mul_f32 v[246:247], v[246:247], s[86:87] op_sel_hi:[1,0]
	v_pk_mul_f32 v[248:249], v[248:249], s[86:87] op_sel_hi:[1,0]
	v_exp_f32_e32 v242, v242
	v_exp_f32_e32 v243, v243
	v_exp_f32_e32 v244, v244
	v_exp_f32_e32 v245, v245
	v_exp_f32_e32 v246, v246
	v_exp_f32_e32 v247, v247
	v_exp_f32_e32 v248, v248
	v_exp_f32_e32 v249, v249
	v_pk_add_f32 v[242:243], v[242:243], 1.0 op_sel_hi:[1,0]
	v_pk_add_f32 v[244:245], v[244:245], 1.0 op_sel_hi:[1,0]
	v_pk_add_f32 v[246:247], v[246:247], 1.0 op_sel_hi:[1,0]
	v_pk_add_f32 v[248:249], v[248:249], 1.0 op_sel_hi:[1,0]
	v_pk_mul_f32 v[216:217], v[216:217], v[242:243]
	v_pk_mul_f32 v[218:219], v[218:219], v[244:245]
	v_pk_mul_f32 v[220:221], v[220:221], v[246:247]
	v_pk_mul_f32 v[222:223], v[222:223], v[248:249]
	v_pk_mul_f32 v[38:39], v[38:39], v[216:217]
	v_pk_mul_f32 v[40:41], v[40:41], v[218:219]
	v_pk_mul_f32 v[34:35], v[34:35], v[220:221]
	v_pk_mul_f32 v[36:37], v[36:37], v[222:223]
	v_lshlrev_b32_e32 v216, 16, v186
	v_and_b32_e32 v217, 0xffff0000, v186
	v_lshlrev_b32_e32 v218, 16, v187
	v_and_b32_e32 v219, 0xffff0000, v187
	v_lshlrev_b32_e32 v220, 16, v188
	v_and_b32_e32 v221, 0xffff0000, v188
	v_lshlrev_b32_e32 v222, 16, v189
	v_and_b32_e32 v223, 0xffff0000, v189
	v_pk_mul_f32 v[216:217], v[216:217], s[86:87] op_sel_hi:[1,0]
	v_pk_mul_f32 v[218:219], v[218:219], s[86:87] op_sel_hi:[1,0]
	v_pk_mul_f32 v[220:221], v[220:221], s[86:87] op_sel_hi:[1,0]
	v_pk_mul_f32 v[222:223], v[222:223], s[86:87] op_sel_hi:[1,0]
	v_exp_f32_e32 v216, v216
	v_exp_f32_e32 v217, v217
	v_exp_f32_e32 v218, v218
	v_exp_f32_e32 v219, v219
	v_exp_f32_e32 v220, v220
	v_exp_f32_e32 v221, v221
	v_exp_f32_e32 v222, v222
	v_exp_f32_e32 v223, v223
	v_pk_add_f32 v[216:217], v[216:217], 1.0 op_sel_hi:[1,0]
	v_pk_add_f32 v[218:219], v[218:219], 1.0 op_sel_hi:[1,0]
	v_pk_add_f32 v[220:221], v[220:221], 1.0 op_sel_hi:[1,0]
	v_pk_add_f32 v[222:223], v[222:223], 1.0 op_sel_hi:[1,0]
	v_rcp_f32_e32 v216, v216
	v_rcp_f32_e32 v217, v217
	v_rcp_f32_e32 v218, v218
	v_rcp_f32_e32 v219, v219
	v_rcp_f32_e32 v220, v220
	v_rcp_f32_e32 v221, v221
	v_rcp_f32_e32 v222, v222
	v_rcp_f32_e32 v223, v223
	v_lshlrev_b32_e32 v242, 16, v190
	v_and_b32_e32 v243, 0xffff0000, v190
	v_lshlrev_b32_e32 v244, 16, v191
	v_and_b32_e32 v245, 0xffff0000, v191
	v_lshlrev_b32_e32 v246, 16, v192
	v_and_b32_e32 v247, 0xffff0000, v192
	v_lshlrev_b32_e32 v248, 16, v193
	v_and_b32_e32 v249, 0xffff0000, v193
	v_pk_mul_f32 v[242:243], v[242:243], s[86:87] op_sel_hi:[1,0]
	v_pk_mul_f32 v[244:245], v[244:245], s[86:87] op_sel_hi:[1,0]
	v_pk_mul_f32 v[246:247], v[246:247], s[86:87] op_sel_hi:[1,0]
	v_pk_mul_f32 v[248:249], v[248:249], s[86:87] op_sel_hi:[1,0]
	v_exp_f32_e32 v242, v242
	v_exp_f32_e32 v243, v243
	v_exp_f32_e32 v244, v244
	v_exp_f32_e32 v245, v245
	v_exp_f32_e32 v246, v246
	v_exp_f32_e32 v247, v247
	v_exp_f32_e32 v248, v248
	v_exp_f32_e32 v249, v249
	v_pk_add_f32 v[242:243], v[242:243], 1.0 op_sel_hi:[1,0]
	v_pk_add_f32 v[244:245], v[244:245], 1.0 op_sel_hi:[1,0]
	v_pk_add_f32 v[246:247], v[246:247], 1.0 op_sel_hi:[1,0]
	v_pk_add_f32 v[248:249], v[248:249], 1.0 op_sel_hi:[1,0]
	v_pk_mul_f32 v[216:217], v[216:217], v[242:243]
	v_pk_mul_f32 v[218:219], v[218:219], v[244:245]
	v_pk_mul_f32 v[220:221], v[220:221], v[246:247]
	v_pk_mul_f32 v[222:223], v[222:223], v[248:249]
	v_pk_mul_f32 v[6:7], v[6:7], v[216:217]
	v_pk_mul_f32 v[8:9], v[8:9], v[218:219]
	v_pk_mul_f32 v[2:3], v[2:3], v[220:221]
	v_pk_mul_f32 v[4:5], v[4:5], v[222:223]
	s_branch .Lem_done

.LBB0_504:
	v_or_b32_e32 v130, 0x10000, v163
	v_add_u32_e32 v134, 0x10400, v163
	v_add_u32_e32 v150, 0x10800, v163
	v_add_u32_e32 v154, 0x10c00, v163
	ds_read_b128 v[130:133], v130
	ds_read_b128 v[134:137], v134
	ds_read_b128 v[150:153], v150
	ds_read_b128 v[154:157], v154
	s_add_u32 s10, s52, 0xfff80080
	s_addc_u32 s11, s53, -1
	s_cmp_eq_u32 s29, 28
	s_cselect_b32 s11, s9, s11
	s_cselect_b32 s10, s8, s10
	s_cselect_b32 s55, s35, s7
	s_cselect_b32 s54, s34, s5
	v_lshl_add_u64 v[206:207], s[52:53], 0, v[146:147]
	s_add_i32 m0, s42, 0xc000
	ds_read_b128 v[158:161], v162
	ds_read_b128 v[166:169], v162 offset:1024
	ds_read_b128 v[170:173], v162 offset:2048
	ds_read_b128 v[174:177], v162 offset:3072
	ds_read_b128 v[178:181], v162 offset:4096
	ds_read_b128 v[182:185], v162 offset:5120
	ds_read_b128 v[186:189], v162 offset:6144
	ds_read_b128 v[190:193], v162 offset:7168
	global_load_lds_dwordx4 v[206:207], off
	v_lshl_add_u64 v[206:207], s[52:53], 0, v[148:149]
	s_add_i32 m0, s42, 0xe000
	s_nop 0
	global_load_lds_dwordx4 v[206:207], off
	s_waitcnt lgkmcnt(8)
	s_barrier
	s_waitcnt lgkmcnt(0)
	s_setprio 1
	v_mfma_f32_16x16x32_bf16 v[126:129], v[130:133], v[158:161], v[126:129]
	v_mfma_f32_16x16x32_bf16 v[122:125], v[150:153], v[158:161], v[122:125]
	v_mfma_f32_16x16x32_bf16 v[118:121], v[130:133], v[170:173], v[118:121]
	v_mfma_f32_16x16x32_bf16 v[114:117], v[150:153], v[170:173], v[114:117]
	v_mfma_f32_16x16x32_bf16 v[110:113], v[130:133], v[178:181], v[110:113]
	v_mfma_f32_16x16x32_bf16 v[106:109], v[150:153], v[178:181], v[106:109]
	v_mfma_f32_16x16x32_bf16 v[102:105], v[130:133], v[186:189], v[102:105]
	v_mfma_f32_16x16x32_bf16 v[98:101], v[150:153], v[186:189], v[98:101]
	v_mfma_f32_16x16x32_bf16 v[126:129], v[134:137], v[166:169], v[126:129]
	v_mfma_f32_16x16x32_bf16 v[122:125], v[154:157], v[166:169], v[122:125]
	v_mfma_f32_16x16x32_bf16 v[118:121], v[134:137], v[174:177], v[118:121]
	v_mfma_f32_16x16x32_bf16 v[114:117], v[154:157], v[174:177], v[114:117]
	v_mfma_f32_16x16x32_bf16 v[110:113], v[134:137], v[182:185], v[110:113]
	v_mfma_f32_16x16x32_bf16 v[106:109], v[154:157], v[182:185], v[106:109]
	v_mfma_f32_16x16x32_bf16 v[102:105], v[134:137], v[190:193], v[102:105]
	v_mfma_f32_16x16x32_bf16 v[98:101], v[154:157], v[190:193], v[98:101]
	s_setprio 0
	s_barrier
	v_or_b32_e32 v165, 0x14000, v163
	s_mov_b32 m0, s41
	v_add_u32_e32 v197, 0x14400, v163
	ds_read_b128 v[206:209], v165
	ds_read_b128 v[210:213], v197
	v_add_u32_e32 v165, 0x14800, v163
	v_lshl_add_u64 v[222:223], s[54:55], 0, v[194:195]
	v_add_u32_e32 v197, 0x14c00, v163
	ds_read_b128 v[214:217], v165
	ds_read_b128 v[218:221], v197
	global_load_lds_dwordx4 v[222:223], off
	v_lshl_add_u64 v[224:225], s[54:55], 0, v[138:139]
	s_mov_b32 m0, s57
	s_nop 0
	global_load_lds_dwordx4 v[224:225], off
	s_barrier
	s_waitcnt lgkmcnt(0)
	s_setprio 1
	v_mfma_f32_16x16x32_bf16 v[62:65], v[206:209], v[158:161], v[62:65]
	v_mfma_f32_16x16x32_bf16 v[58:61], v[214:217], v[158:161], v[58:61]
	v_mfma_f32_16x16x32_bf16 v[54:57], v[206:209], v[170:173], v[54:57]
	v_mfma_f32_16x16x32_bf16 v[46:49], v[214:217], v[170:173], v[46:49]
	v_mfma_f32_16x16x32_bf16 v[50:53], v[206:209], v[178:181], v[50:53]
	v_mfma_f32_16x16x32_bf16 v[42:45], v[214:217], v[178:181], v[42:45]
	v_mfma_f32_16x16x32_bf16 v[38:41], v[206:209], v[186:189], v[38:41]
	v_mfma_f32_16x16x32_bf16 v[34:37], v[214:217], v[186:189], v[34:37]
	v_mfma_f32_16x16x32_bf16 v[62:65], v[210:213], v[166:169], v[62:65]
	v_mfma_f32_16x16x32_bf16 v[58:61], v[218:221], v[166:169], v[58:61]
	v_mfma_f32_16x16x32_bf16 v[54:57], v[210:213], v[174:177], v[54:57]
	v_mfma_f32_16x16x32_bf16 v[46:49], v[218:221], v[174:177], v[46:49]
	v_mfma_f32_16x16x32_bf16 v[50:53], v[210:213], v[182:185], v[50:53]
	v_mfma_f32_16x16x32_bf16 v[42:45], v[218:221], v[182:185], v[42:45]
	s_mov_b32 m0, s42
	v_mfma_f32_16x16x32_bf16 v[38:41], v[210:213], v[190:193], v[38:41]
	v_lshl_add_u64 v[226:227], s[10:11], 0, v[142:143]
	v_mfma_f32_16x16x32_bf16 v[34:37], v[218:221], v[190:193], v[34:37]
	s_setprio 0
	s_barrier
	ds_read_b128 v[158:161], v162 offset:16384
	ds_read_b128 v[166:169], v162 offset:17408
	ds_read_b128 v[170:173], v162 offset:18432
	ds_read_b128 v[174:177], v162 offset:19456
	ds_read_b128 v[178:181], v162 offset:20480
	ds_read_b128 v[182:185], v162 offset:21504
	ds_read_b128 v[186:189], v162 offset:22528
	ds_read_b128 v[190:193], v162 offset:23552
	global_load_lds_dwordx4 v[226:227], off
	v_lshl_add_u64 v[228:229], s[10:11], 0, v[140:141]
	s_mov_b32 m0, s58
	s_nop 0
	global_load_lds_dwordx4 v[228:229], off
	s_barrier
	s_waitcnt lgkmcnt(0)
	s_setprio 1
	v_mfma_f32_16x16x32_bf16 v[94:97], v[130:133], v[158:161], v[94:97]
	v_mfma_f32_16x16x32_bf16 v[90:93], v[150:153], v[158:161], v[90:93]
	v_mfma_f32_16x16x32_bf16 v[86:89], v[130:133], v[170:173], v[86:89]
	v_mfma_f32_16x16x32_bf16 v[82:85], v[150:153], v[170:173], v[82:85]
	v_mfma_f32_16x16x32_bf16 v[78:81], v[130:133], v[178:181], v[78:81]
	v_mfma_f32_16x16x32_bf16 v[74:77], v[150:153], v[178:181], v[74:77]
	v_mfma_f32_16x16x32_bf16 v[70:73], v[130:133], v[186:189], v[70:73]
	v_mfma_f32_16x16x32_bf16 v[66:69], v[150:153], v[186:189], v[66:69]
	v_mfma_f32_16x16x32_bf16 v[94:97], v[134:137], v[166:169], v[94:97]
	v_mfma_f32_16x16x32_bf16 v[90:93], v[154:157], v[166:169], v[90:93]
	v_mfma_f32_16x16x32_bf16 v[86:89], v[134:137], v[174:177], v[86:89]
	v_mfma_f32_16x16x32_bf16 v[82:85], v[154:157], v[174:177], v[82:85]
	v_mfma_f32_16x16x32_bf16 v[78:81], v[134:137], v[182:185], v[78:81]
	v_mfma_f32_16x16x32_bf16 v[74:77], v[154:157], v[182:185], v[74:77]
	v_mfma_f32_16x16x32_bf16 v[70:73], v[134:137], v[190:193], v[70:73]
	v_mfma_f32_16x16x32_bf16 v[66:69], v[154:157], v[190:193], v[66:69]
	s_setprio 0
	s_barrier
	s_add_u32 s86, s54, 0x80000
	s_addc_u32 s87, s55, 0
	s_mov_b32 m0, s59
	v_lshl_add_u64 v[130:131], s[86:87], 0, v[194:195]
	global_load_lds_dwordx4 v[130:131], off
	v_lshl_add_u64 v[130:131], s[86:87], 0, v[138:139]
	s_mov_b32 m0, s60
	s_nop 0
	global_load_lds_dwordx4 v[130:131], off
	s_waitcnt vmcnt(6)
	s_barrier
	s_setprio 1
	v_mfma_f32_16x16x32_bf16 v[30:33], v[206:209], v[158:161], v[30:33]
	v_mfma_f32_16x16x32_bf16 v[18:21], v[214:217], v[158:161], v[18:21]
	v_mfma_f32_16x16x32_bf16 v[26:29], v[206:209], v[170:173], v[26:29]
	v_mfma_f32_16x16x32_bf16 v[14:17], v[214:217], v[170:173], v[14:17]
	v_mfma_f32_16x16x32_bf16 v[22:25], v[206:209], v[178:181], v[22:25]
	v_mfma_f32_16x16x32_bf16 v[6:9], v[214:217], v[178:181], v[6:9]
	v_mfma_f32_16x16x32_bf16 v[10:13], v[206:209], v[186:189], v[10:13]
	v_mfma_f32_16x16x32_bf16 v[2:5], v[214:217], v[186:189], v[2:5]
	v_mfma_f32_16x16x32_bf16 v[30:33], v[210:213], v[166:169], v[30:33]
	v_mfma_f32_16x16x32_bf16 v[18:21], v[218:221], v[166:169], v[18:21]
	v_mfma_f32_16x16x32_bf16 v[26:29], v[210:213], v[174:177], v[26:29]
	v_mfma_f32_16x16x32_bf16 v[14:17], v[218:221], v[174:177], v[14:17]
	v_or_b32_e32 v130, 0x18000, v163
	v_mfma_f32_16x16x32_bf16 v[22:25], v[210:213], v[182:185], v[22:25]
	v_add_u32_e32 v134, 0x18400, v163
	v_mfma_f32_16x16x32_bf16 v[6:9], v[218:221], v[182:185], v[6:9]
	v_add_u32_e32 v150, 0x18800, v163
	v_mfma_f32_16x16x32_bf16 v[10:13], v[210:213], v[190:193], v[10:13]
	v_add_u32_e32 v154, 0x18c00, v163
	v_mfma_f32_16x16x32_bf16 v[2:5], v[218:221], v[190:193], v[2:5]
	s_setprio 0
	s_barrier
	ds_read_b128 v[130:133], v130
	ds_read_b128 v[134:137], v134
	ds_read_b128 v[150:153], v150
	ds_read_b128 v[154:157], v154
	s_add_u32 s10, s10, 0x80000
	s_addc_u32 s11, s11, 0
	s_mov_b32 m0, s61
	v_lshl_add_u64 v[206:207], s[10:11], 0, v[142:143]
	ds_read_b128 v[158:161], v162 offset:32768
	ds_read_b128 v[166:169], v162 offset:33792
	ds_read_b128 v[170:173], v162 offset:34816
	ds_read_b128 v[174:177], v162 offset:35840
	ds_read_b128 v[178:181], v162 offset:36864
	ds_read_b128 v[182:185], v162 offset:37888
	ds_read_b128 v[186:189], v162 offset:38912
	ds_read_b128 v[190:193], v162 offset:39936
	global_load_lds_dwordx4 v[206:207], off
	v_lshl_add_u64 v[206:207], s[10:11], 0, v[140:141]
	s_mov_b32 m0, s62
	s_nop 0
	global_load_lds_dwordx4 v[206:207], off
	s_waitcnt lgkmcnt(8)
	s_barrier
	s_waitcnt lgkmcnt(0)
	s_setprio 1
	v_mfma_f32_16x16x32_bf16 v[126:129], v[130:133], v[158:161], v[126:129]
	v_mfma_f32_16x16x32_bf16 v[122:125], v[150:153], v[158:161], v[122:125]
	v_mfma_f32_16x16x32_bf16 v[118:121], v[130:133], v[170:173], v[118:121]
	v_mfma_f32_16x16x32_bf16 v[114:117], v[150:153], v[170:173], v[114:117]
	v_mfma_f32_16x16x32_bf16 v[110:113], v[130:133], v[178:181], v[110:113]
	v_mfma_f32_16x16x32_bf16 v[106:109], v[150:153], v[178:181], v[106:109]
	v_mfma_f32_16x16x32_bf16 v[102:105], v[130:133], v[186:189], v[102:105]
	v_mfma_f32_16x16x32_bf16 v[98:101], v[150:153], v[186:189], v[98:101]
	v_mfma_f32_16x16x32_bf16 v[126:129], v[134:137], v[166:169], v[126:129]
	v_mfma_f32_16x16x32_bf16 v[122:125], v[154:157], v[166:169], v[122:125]
	v_mfma_f32_16x16x32_bf16 v[118:121], v[134:137], v[174:177], v[118:121]
	v_mfma_f32_16x16x32_bf16 v[114:117], v[154:157], v[174:177], v[114:117]
	v_mfma_f32_16x16x32_bf16 v[110:113], v[134:137], v[182:185], v[110:113]
	v_mfma_f32_16x16x32_bf16 v[106:109], v[154:157], v[182:185], v[106:109]
	v_mfma_f32_16x16x32_bf16 v[102:105], v[134:137], v[190:193], v[102:105]
	v_mfma_f32_16x16x32_bf16 v[98:101], v[154:157], v[190:193], v[98:101]
	s_setprio 0
	s_barrier
	v_or_b32_e32 v165, 0x1c000, v163
	s_mov_b32 m0, s70
	v_add_u32_e32 v197, 0x1c400, v163
	ds_read_b128 v[206:209], v165
	ds_read_b128 v[210:213], v197
	v_add_u32_e32 v165, 0x1c800, v163
	v_lshl_add_u64 v[222:223], v[222:223], 0, s[76:77]
	v_add_u32_e32 v197, 0x1cc00, v163
	ds_read_b128 v[214:217], v165
	ds_read_b128 v[218:221], v197
	global_load_lds_dwordx4 v[222:223], off
	v_lshl_add_u64 v[222:223], v[224:225], 0, s[76:77]
	s_mov_b32 m0, s71
	s_nop 0
	global_load_lds_dwordx4 v[222:223], off
	s_barrier
	s_waitcnt lgkmcnt(0)
	s_setprio 1
	v_mfma_f32_16x16x32_bf16 v[62:65], v[206:209], v[158:161], v[62:65]
	v_mfma_f32_16x16x32_bf16 v[58:61], v[214:217], v[158:161], v[58:61]
	v_mfma_f32_16x16x32_bf16 v[54:57], v[206:209], v[170:173], v[54:57]
	v_mfma_f32_16x16x32_bf16 v[46:49], v[214:217], v[170:173], v[46:49]
	v_mfma_f32_16x16x32_bf16 v[50:53], v[206:209], v[178:181], v[50:53]
	v_mfma_f32_16x16x32_bf16 v[42:45], v[214:217], v[178:181], v[42:45]
	v_mfma_f32_16x16x32_bf16 v[38:41], v[206:209], v[186:189], v[38:41]
	v_mfma_f32_16x16x32_bf16 v[34:37], v[214:217], v[186:189], v[34:37]
	v_mfma_f32_16x16x32_bf16 v[62:65], v[210:213], v[166:169], v[62:65]
	v_mfma_f32_16x16x32_bf16 v[58:61], v[218:221], v[166:169], v[58:61]
	v_mfma_f32_16x16x32_bf16 v[54:57], v[210:213], v[174:177], v[54:57]
	v_mfma_f32_16x16x32_bf16 v[46:49], v[218:221], v[174:177], v[46:49]
	v_mfma_f32_16x16x32_bf16 v[50:53], v[210:213], v[182:185], v[50:53]
	v_mfma_f32_16x16x32_bf16 v[42:45], v[218:221], v[182:185], v[42:45]
	s_mov_b32 m0, s78
	v_mfma_f32_16x16x32_bf16 v[38:41], v[210:213], v[190:193], v[38:41]
	v_lshl_add_u64 v[222:223], v[226:227], 0, s[76:77]
	v_mfma_f32_16x16x32_bf16 v[34:37], v[218:221], v[190:193], v[34:37]
	s_setprio 0
	s_barrier
	ds_read_b128 v[158:161], v162 offset:49152
	ds_read_b128 v[166:169], v162 offset:50176
	ds_read_b128 v[170:173], v162 offset:51200
	ds_read_b128 v[174:177], v162 offset:52224
	ds_read_b128 v[178:181], v162 offset:53248
	ds_read_b128 v[182:185], v162 offset:54272
	ds_read_b128 v[186:189], v162 offset:55296
	ds_read_b128 v[190:193], v162 offset:56320
	global_load_lds_dwordx4 v[222:223], off
	v_lshl_add_u64 v[222:223], v[228:229], 0, s[76:77]
	s_mov_b32 m0, s79
	s_nop 0
	global_load_lds_dwordx4 v[222:223], off
	s_barrier
	s_waitcnt lgkmcnt(0)
	s_setprio 1
	v_mfma_f32_16x16x32_bf16 v[94:97], v[130:133], v[158:161], v[94:97]
	v_mfma_f32_16x16x32_bf16 v[90:93], v[150:153], v[158:161], v[90:93]
	v_mfma_f32_16x16x32_bf16 v[86:89], v[130:133], v[170:173], v[86:89]
	v_mfma_f32_16x16x32_bf16 v[82:85], v[150:153], v[170:173], v[82:85]
	v_mfma_f32_16x16x32_bf16 v[78:81], v[130:133], v[178:181], v[78:81]
	v_mfma_f32_16x16x32_bf16 v[74:77], v[150:153], v[178:181], v[74:77]
	v_mfma_f32_16x16x32_bf16 v[70:73], v[130:133], v[186:189], v[70:73]
	v_mfma_f32_16x16x32_bf16 v[66:69], v[150:153], v[186:189], v[66:69]
	v_mfma_f32_16x16x32_bf16 v[94:97], v[134:137], v[166:169], v[94:97]
	v_mfma_f32_16x16x32_bf16 v[90:93], v[154:157], v[166:169], v[90:93]
	v_mfma_f32_16x16x32_bf16 v[86:89], v[134:137], v[174:177], v[86:89]
	v_mfma_f32_16x16x32_bf16 v[82:85], v[154:157], v[174:177], v[82:85]
	v_mfma_f32_16x16x32_bf16 v[78:81], v[134:137], v[182:185], v[78:81]
	v_mfma_f32_16x16x32_bf16 v[74:77], v[154:157], v[182:185], v[74:77]
	v_mfma_f32_16x16x32_bf16 v[70:73], v[134:137], v[190:193], v[70:73]
	v_mfma_f32_16x16x32_bf16 v[66:69], v[154:157], v[190:193], v[66:69]
	s_setprio 0
	s_barrier
	s_add_u32 s10, s54, 0x80080
	s_addc_u32 s11, s55, 0
	s_mov_b32 m0, s80
	v_lshl_add_u64 v[130:131], s[10:11], 0, v[194:195]
	global_load_lds_dwordx4 v[130:131], off
	v_lshl_add_u64 v[130:131], s[10:11], 0, v[138:139]
	s_mov_b32 m0, s81
	s_nop 0
	global_load_lds_dwordx4 v[130:131], off
	s_waitcnt vmcnt(6)
	s_barrier
	s_setprio 1
	v_mfma_f32_16x16x32_bf16 v[30:33], v[206:209], v[158:161], v[30:33]
	v_mfma_f32_16x16x32_bf16 v[18:21], v[214:217], v[158:161], v[18:21]
	v_mfma_f32_16x16x32_bf16 v[26:29], v[206:209], v[170:173], v[26:29]
	v_mfma_f32_16x16x32_bf16 v[14:17], v[214:217], v[170:173], v[14:17]
	v_mfma_f32_16x16x32_bf16 v[22:25], v[206:209], v[178:181], v[22:25]
	v_mfma_f32_16x16x32_bf16 v[6:9], v[214:217], v[178:181], v[6:9]
	v_mfma_f32_16x16x32_bf16 v[10:13], v[206:209], v[186:189], v[10:13]
	v_mfma_f32_16x16x32_bf16 v[2:5], v[214:217], v[186:189], v[2:5]
	v_mfma_f32_16x16x32_bf16 v[30:33], v[210:213], v[166:169], v[30:33]
	v_mfma_f32_16x16x32_bf16 v[18:21], v[218:221], v[166:169], v[18:21]
	v_mfma_f32_16x16x32_bf16 v[26:29], v[210:213], v[174:177], v[26:29]
	v_mfma_f32_16x16x32_bf16 v[14:17], v[218:221], v[174:177], v[14:17]
	v_mfma_f32_16x16x32_bf16 v[22:25], v[210:213], v[182:185], v[22:25]
	v_mfma_f32_16x16x32_bf16 v[6:9], v[218:221], v[182:185], v[6:9]
	v_mfma_f32_16x16x32_bf16 v[10:13], v[210:213], v[190:193], v[10:13]
	v_mfma_f32_16x16x32_bf16 v[2:5], v[218:221], v[190:193], v[2:5]
	s_setprio 0
	s_add_i32 s29, s29, 2
	s_add_u32 s52, s52, 0x100
	s_addc_u32 s53, s53, 0
	s_add_u32 s5, s5, 0x100
	s_addc_u32 s7, s7, 0
	s_cmp_gt_u32 s29, 29
	s_barrier
	s_cbranch_scc0 .LBB0_504
	v_readlane_b32 s10, v250, 21
	s_cmp_gt_i32 s40, 63
	v_readlane_b32 s11, v250, 22
	s_mov_b64 s[20:21], s[48:49]
	s_cselect_b32 s11, s21, s11
	s_cselect_b32 s10, s20, s10
	v_readlane_b32 s20, v252, 0
	v_readlane_b32 s26, v252, 6
	v_readlane_b32 s27, v252, 7
	s_cselect_b32 s53, s3, s27
	s_cselect_b32 s52, s2, s26
	s_sub_i32 s5, s40, 64
	s_cmp_gt_i32 s40, 63
	s_cselect_b32 s54, s5, s40
	s_lshr_b32 s5, s40, 3
	s_cmp_gt_i32 s40, 63
	s_mulk_i32 s5, 0x1800
	v_lshl_or_b32 v130, s28, 8, v164
	s_cselect_b32 s28, 0xc000, s5
	s_ashr_i32 s29, s28, 31
	s_lshl_b64 s[28:29], s[28:29], 2
	s_add_u32 s28, s63, s28
	v_ashrrev_i32_e32 v131, 31, v130
	s_addc_u32 s29, s67, s29
	v_lshlrev_b64 v[130:131], 2, v[130:131]
	v_lshl_add_u64 v[132:133], s[28:29], 0, v[130:131]
	s_mov_b64 s[28:29], 0x6484000
	s_ashr_i32 s55, s54, 31
	v_lshl_add_u64 v[154:155], v[132:133], 0, s[28:29]
	s_lshl_b64 s[28:29], s[54:55], 19
	v_lshl_add_u64 v[134:135], s[28:29], 0, v[144:145]
	v_lshlrev_b64 v[134:135], 2, v[134:135]
	v_lshl_add_u64 v[136:137], s[10:11], 0, v[134:135]
	v_lshl_add_u64 v[134:135], s[52:53], 0, v[134:135]
	s_mov_b32 s5, 0x6484000
	v_lshl_add_u64 v[150:151], v[136:137], 0, v[130:131]
	v_lshl_add_u64 v[152:153], v[134:135], 0, v[130:131]
	v_add_co_u32_e32 v130, vcc, s5, v132
	s_mov_b64 s[10:11], 0x20000
	s_nop 0
	v_addc_co_u32_e32 v131, vcc, 0, v133, vcc
	v_add_co_u32_e32 v156, vcc, s13, v150
	global_load_dwordx4 v[134:137], v[130:131], off
	s_nop 0
	global_load_dwordx4 v[130:133], v[154:155], off offset:16
	global_load_dwordx4 v[166:169], v[150:151], off offset:16
	global_load_dwordx4 v[170:173], v[150:151], off
	v_lshl_add_u64 v[158:159], v[150:151], 0, s[10:11]
	v_addc_co_u32_e32 v157, vcc, 0, v151, vcc
	s_mov_b32 s5, 0x40000
	global_load_dwordx4 v[174:177], v[156:157], off
	global_load_dwordx4 v[178:181], v[158:159], off offset:16
	s_mov_b64 s[10:11], 0x40000
	v_add_co_u32_e32 v158, vcc, s5, v150
	v_lshl_add_u64 v[160:161], v[150:151], 0, s[10:11]
	s_nop 0
	v_addc_co_u32_e32 v159, vcc, 0, v151, vcc
	s_mov_b32 s7, 0x60000
	global_load_dwordx4 v[182:185], v[158:159], off
	global_load_dwordx4 v[186:189], v[160:161], off offset:16
	s_mov_b64 s[10:11], 0x60000
	v_add_co_u32_e32 v160, vcc, s7, v150
	v_lshl_add_u64 v[206:207], v[150:151], 0, s[10:11]
	s_nop 0
	v_addc_co_u32_e32 v161, vcc, 0, v151, vcc
	global_load_dwordx4 v[190:193], v[160:161], off
	s_nop 0
	global_load_dwordx4 v[206:209], v[206:207], off offset:16
	v_readlane_b32 s21, v252, 1
	v_readlane_b32 s22, v252, 2
	v_readlane_b32 s23, v252, 3
	v_readlane_b32 s24, v252, 4
	v_readlane_b32 s25, v252, 5
	s_waitcnt vmcnt(0)
	v_pk_fma_f32 v[124:125], v[124:125], v[132:133], v[168:169]
	v_pk_fma_f32 v[122:123], v[122:123], v[130:131], v[166:167]
	global_store_dwordx4 v[152:153], v[122:125], off offset:16
	v_pk_fma_f32 v[128:129], v[128:129], v[136:137], v[172:173]
	v_pk_fma_f32 v[126:127], v[126:127], v[134:135], v[170:171]
	v_pk_fma_f32 v[122:123], v[120:121], v[136:137], v[176:177]
	v_pk_fma_f32 v[120:121], v[118:119], v[134:135], v[174:175]
	v_add_co_u32_e32 v118, vcc, s13, v152
	v_pk_fma_f32 v[116:117], v[116:117], v[132:133], v[180:181]
	s_nop 0
	v_addc_co_u32_e32 v119, vcc, 0, v153, vcc
	v_pk_fma_f32 v[114:115], v[114:115], v[130:131], v[178:179]
	global_store_dwordx4 v[118:119], v[114:117], off offset:16
	v_pk_fma_f32 v[108:109], v[108:109], v[132:133], v[188:189]
	v_pk_fma_f32 v[106:107], v[106:107], v[130:131], v[186:187]
	v_pk_fma_f32 v[114:115], v[112:113], v[136:137], v[184:185]
	v_pk_fma_f32 v[112:113], v[110:111], v[134:135], v[182:183]
	v_add_co_u32_e32 v110, vcc, s5, v152
	global_store_dwordx4 v[152:153], v[126:129], off
	s_nop 0
	v_addc_co_u32_e32 v111, vcc, 0, v153, vcc
	global_store_dwordx4 v[110:111], v[106:109], off offset:16
	v_pk_fma_f32 v[100:101], v[100:101], v[132:133], v[208:209]
	v_pk_fma_f32 v[98:99], v[98:99], v[130:131], v[206:207]
	v_pk_fma_f32 v[106:107], v[104:105], v[136:137], v[192:193]
	v_pk_fma_f32 v[104:105], v[102:103], v[134:135], v[190:191]
	v_add_co_u32_e32 v102, vcc, s7, v152
	global_store_dwordx4 v[118:119], v[120:123], off
	s_nop 0
	v_addc_co_u32_e32 v103, vcc, 0, v153, vcc
	global_store_dwordx4 v[110:111], v[112:115], off
	global_store_dwordx4 v[102:103], v[104:107], off
	global_store_dwordx4 v[102:103], v[98:101], off offset:16
	s_mov_b32 s5, 0x100000
	s_mov_b64 s[10:11], 0x100000
	v_add_co_u32_e32 v98, vcc, s5, v150
	v_lshl_add_u64 v[100:101], v[150:151], 0, s[10:11]
	s_nop 0
	v_addc_co_u32_e32 v99, vcc, 0, v151, vcc
	global_load_dwordx4 v[112:115], v[98:99], off
	global_load_dwordx4 v[120:123], v[100:101], off offset:16
	s_mov_b64 s[10:11], 0x120000
	v_add_co_u32_e32 v100, vcc, s45, v150
	v_lshl_add_u64 v[104:105], v[150:151], 0, s[10:11]
	s_nop 0
	v_addc_co_u32_e32 v101, vcc, 0, v151, vcc
	s_mov_b64 s[10:11], 0x140000
	s_mov_b32 s7, 0x140000
	global_load_dwordx4 v[124:127], v[100:101], off
	global_load_dwordx4 v[166:169], v[104:105], off offset:16
	v_lshl_add_u64 v[106:107], v[150:151], 0, s[10:11]
	v_add_co_u32_e32 v104, vcc, s7, v150
	s_mov_b64 s[10:11], 0x160000
	s_nop 0
	v_addc_co_u32_e32 v105, vcc, 0, v151, vcc
	v_lshl_add_u64 v[108:109], v[150:151], 0, s[10:11]
	s_mov_b32 s10, 0x160000
	global_load_dwordx4 v[170:173], v[104:105], off
	global_load_dwordx4 v[174:177], v[106:107], off offset:16
	v_add_co_u32_e32 v106, vcc, s10, v150
	s_waitcnt vmcnt(0)
	v_pk_fma_f32 v[112:113], v[94:95], v[134:135], v[112:113]
	v_addc_co_u32_e32 v107, vcc, 0, v151, vcc
	global_load_dwordx4 v[178:181], v[106:107], off
	global_load_dwordx4 v[182:185], v[108:109], off offset:16
	v_add_co_u32_e32 v94, vcc, s5, v152
	v_pk_fma_f32 v[92:93], v[92:93], v[132:133], v[122:123]
	s_nop 0
	v_addc_co_u32_e32 v95, vcc, 0, v153, vcc
	v_pk_fma_f32 v[90:91], v[90:91], v[130:131], v[120:121]
	global_store_dwordx4 v[94:95], v[90:93], off offset:16
	v_pk_fma_f32 v[84:85], v[84:85], v[132:133], v[168:169]
	v_pk_fma_f32 v[82:83], v[82:83], v[130:131], v[166:167]
	v_pk_fma_f32 v[90:91], v[88:89], v[136:137], v[126:127]
	v_pk_fma_f32 v[88:89], v[86:87], v[134:135], v[124:125]
	v_add_co_u32_e32 v86, vcc, s45, v152
	v_pk_fma_f32 v[114:115], v[96:97], v[136:137], v[114:115]
	s_nop 0
	v_addc_co_u32_e32 v87, vcc, 0, v153, vcc
	global_store_dwordx4 v[86:87], v[82:85], off offset:16
	v_pk_fma_f32 v[76:77], v[76:77], v[132:133], v[176:177]
	v_pk_fma_f32 v[74:75], v[74:75], v[130:131], v[174:175]
	v_pk_fma_f32 v[82:83], v[80:81], v[136:137], v[172:173]
	v_pk_fma_f32 v[80:81], v[78:79], v[134:135], v[170:171]
	v_add_co_u32_e32 v78, vcc, s7, v152
	global_store_dwordx4 v[94:95], v[112:115], off
	s_nop 0
	v_addc_co_u32_e32 v79, vcc, 0, v153, vcc
	global_store_dwordx4 v[78:79], v[74:77], off offset:16
	global_store_dwordx4 v[86:87], v[88:91], off
	global_store_dwordx4 v[78:79], v[80:83], off
	v_add_co_u32_e32 v74, vcc, s10, v152
	s_waitcnt vmcnt(0)
	v_pk_fma_f32 v[72:73], v[72:73], v[136:137], v[180:181]
	v_pk_fma_f32 v[70:71], v[70:71], v[134:135], v[178:179]
	v_addc_co_u32_e32 v75, vcc, 0, v153, vcc
	v_pk_fma_f32 v[68:69], v[68:69], v[132:133], v[184:185]
	v_pk_fma_f32 v[66:67], v[66:67], v[130:131], v[182:183]
	global_store_dwordx4 v[74:75], v[70:73], off
	global_store_dwordx4 v[74:75], v[66:69], off offset:16
	s_mov_b64 s[10:11], 0x20200
	v_lshl_add_u64 v[76:77], v[150:151], 0, s[10:11]
	s_mov_b64 s[10:11], 0x40200
	global_load_dwordx4 v[80:83], v[150:151], off offset:512
	global_load_dwordx4 v[70:73], v[154:155], off offset:512
	global_load_dwordx4 v[66:69], v[154:155], off offset:528
	global_load_dwordx4 v[88:91], v[150:151], off offset:528
	global_load_dwordx4 v[112:115], v[156:157], off offset:512
	global_load_dwordx4 v[120:123], v[158:159], off offset:512
	global_load_dwordx4 v[124:127], v[76:77], off offset:16
	v_lshl_add_u64 v[76:77], v[150:151], 0, s[10:11]
	s_mov_b64 s[10:11], 0x60200
	global_load_dwordx4 v[128:131], v[76:77], off offset:16
	global_load_dwordx4 v[132:135], v[160:161], off offset:512
	v_lshl_add_u64 v[76:77], v[150:151], 0, s[10:11]
	global_load_dwordx4 v[154:157], v[76:77], off offset:16
	s_waitcnt vmcnt(0)
	v_pk_fma_f32 v[64:65], v[64:65], v[72:73], v[82:83]
	v_pk_fma_f32 v[62:63], v[62:63], v[70:71], v[80:81]
	v_pk_fma_f32 v[60:61], v[60:61], v[68:69], v[90:91]
	v_pk_fma_f32 v[58:59], v[58:59], v[66:67], v[88:89]
	v_pk_fma_f32 v[52:53], v[52:53], v[72:73], v[122:123]
	v_pk_fma_f32 v[50:51], v[50:51], v[70:71], v[120:121]
	v_pk_fma_f32 v[48:49], v[48:49], v[68:69], v[126:127]
	v_pk_fma_f32 v[46:47], v[46:47], v[66:67], v[124:125]
	v_pk_fma_f32 v[56:57], v[56:57], v[72:73], v[114:115]
	v_pk_fma_f32 v[54:55], v[54:55], v[70:71], v[112:113]
	global_store_dwordx4 v[152:153], v[62:65], off offset:512
	global_store_dwordx4 v[152:153], v[58:61], off offset:528
	global_store_dwordx4 v[118:119], v[54:57], off offset:512
	global_store_dwordx4 v[110:111], v[50:53], off offset:512
	v_pk_fma_f32 v[44:45], v[44:45], v[68:69], v[130:131]
	v_pk_fma_f32 v[42:43], v[42:43], v[66:67], v[128:129]
	v_pk_fma_f32 v[40:41], v[40:41], v[72:73], v[134:135]
	v_pk_fma_f32 v[38:39], v[38:39], v[70:71], v[132:133]
	v_pk_fma_f32 v[36:37], v[36:37], v[68:69], v[156:157]
	v_pk_fma_f32 v[34:35], v[34:35], v[66:67], v[154:155]
	global_store_dwordx4 v[118:119], v[46:49], off offset:528
	global_store_dwordx4 v[110:111], v[42:45], off offset:528
	global_store_dwordx4 v[102:103], v[38:41], off offset:512
	global_store_dwordx4 v[102:103], v[34:37], off offset:528
	s_mov_b64 s[10:11], 0x100200
	v_lshl_add_u64 v[50:51], v[150:151], 0, s[10:11]
	s_mov_b64 s[10:11], 0x120200
	v_lshl_add_u64 v[54:55], v[150:151], 0, s[10:11]
	s_mov_b64 s[10:11], 0x140200
	v_lshl_add_u64 v[58:59], v[150:151], 0, s[10:11]
	s_mov_b64 s[10:11], 0x160200
	global_load_dwordx4 v[34:37], v[98:99], off offset:512
	global_load_dwordx4 v[38:41], v[100:101], off offset:512
	global_load_dwordx4 v[42:45], v[104:105], off offset:512
	global_load_dwordx4 v[46:49], v[106:107], off offset:512
	v_lshl_add_u64 v[62:63], v[150:151], 0, s[10:11]
	global_load_dwordx4 v[50:53], v[50:51], off offset:16
	s_waitcnt vmcnt(0)
	v_pk_fma_f32 v[32:33], v[32:33], v[72:73], v[36:37]
	global_load_dwordx4 v[54:57], v[54:55], off offset:16
	v_pk_fma_f32 v[30:31], v[30:31], v[70:71], v[34:35]
	global_load_dwordx4 v[58:61], v[58:59], off offset:16
	v_pk_fma_f32 v[28:29], v[28:29], v[72:73], v[40:41]
	global_load_dwordx4 v[62:65], v[62:63], off offset:16
	v_pk_fma_f32 v[26:27], v[26:27], v[70:71], v[38:39]
	v_pk_fma_f32 v[24:25], v[24:25], v[72:73], v[44:45]
	v_pk_fma_f32 v[22:23], v[22:23], v[70:71], v[42:43]
	v_pk_fma_f32 v[12:13], v[12:13], v[72:73], v[48:49]
	v_pk_fma_f32 v[10:11], v[10:11], v[70:71], v[46:47]
	v_pk_fma_f32 v[20:21], v[20:21], v[68:69], v[52:53]
	v_pk_fma_f32 v[18:19], v[18:19], v[66:67], v[50:51]
	global_store_dwordx4 v[94:95], v[30:33], off offset:512
	global_store_dwordx4 v[86:87], v[26:29], off offset:512
	global_store_dwordx4 v[78:79], v[22:25], off offset:512
	global_store_dwordx4 v[74:75], v[10:13], off offset:512
	s_waitcnt vmcnt(0)
	v_pk_fma_f32 v[16:17], v[16:17], v[68:69], v[56:57]
	v_pk_fma_f32 v[14:15], v[14:15], v[66:67], v[54:55]
	v_pk_fma_f32 v[8:9], v[8:9], v[68:69], v[60:61]
	v_pk_fma_f32 v[6:7], v[6:7], v[66:67], v[58:59]
	v_pk_fma_f32 v[4:5], v[4:5], v[68:69], v[64:65]
	v_pk_fma_f32 v[2:3], v[2:3], v[66:67], v[62:63]
	global_store_dwordx4 v[94:95], v[18:21], off offset:528
	global_store_dwordx4 v[86:87], v[14:17], off offset:528
	global_store_dwordx4 v[78:79], v[6:9], off offset:528
	global_store_dwordx4 v[74:75], v[2:5], off offset:528
	s_and_b64 vcc, exec, s[0:1]
	s_mov_b32 s40, s6
	s_mov_b32 s28, s4
	s_mov_b64 s[54:55], s[34:35]
	s_mov_b64 s[52:53], s[8:9]
	s_cbranch_vccz .LBB0_501
	s_waitcnt vmcnt(0)
	v_readlane_b32 s28, v250, 12
	v_readlane_b32 s26, v250, 15
	s_cmpk_gt_u32 s12, 0xff
	v_readlane_b32 s29, v250, 13
	v_readlane_b32 s27, v250, 16
	s_mov_b32 s70, 0x800000
	v_readlane_b32 s79, v250, 18
	s_cbranch_scc1 .LBB0_508
	s_barrier
